# v7 plus: quant_rows lanes own 16 adjacent columns; the two 8-byte int8 stores per row merged into one 16-byte store (4 sites)
# speedup vs baseline: 1.0308x; 1.0018x over previous
.LBB0_294:
	s_or_b64 exec, exec, s[0:1]
	s_mov_b64 s[0:1], s[82:83]
	v_mov_b32_e32 v2, v0
	s_mov_b32 s5, s72
	s_mov_b32 s2, s73
	s_barrier
	s_load_dwordx2 s[2:3], s[0:1], 0x90
	v_readfirstlane_b32 s4, v2
	s_lshl_b32 s0, s5, 3
	s_and_b32 s0, s0, 56
	s_bfe_u32 s1, s5, 0x30003
	s_ashr_i32 s4, s4, 3
	s_or_b32 s8, s0, s1
	s_and_b32 s1, s5, 0xffffffc0
	s_and_b32 s4, s4, -8
	s_lshl_b32 s0, s8, 8
	s_add_i32 s4, s1, s4
	s_add_i32 s6, s4, s0
	s_ashr_i32 s7, s6, 31
	s_lshl_b64 s[0:1], s[6:7], 11
	v_and_b32_e32 v126, 63, v2
	s_waitcnt lgkmcnt(0)
	s_add_u32 s0, s2, s0
	s_addc_u32 s1, s3, s1
	v_lshlrev_b32_e32 v30, 5, v126
	v_mov_b32_e32 v31, 0
	v_lshl_add_u64 v[2:3], s[0:1], 0, v[30:31]
	s_mov_b32 s0, 0x3001000
	v_add_co_u32_e32 v60, vcc, s0, v2
	s_mov_b64 s[0:1], 0x3000000
	s_nop 0
	v_addc_co_u32_e32 v61, vcc, 0, v3, vcc
	global_load_dwordx4 v[18:21], v[60:61], off offset:-4096
	v_lshl_add_u64 v[4:5], v[2:3], 0, s[0:1]
	global_load_dwordx4 v[22:25], v[4:5], off offset:16
	global_load_dwordx4 v[32:35], v[4:5], off offset:2048
	global_load_dwordx4 v[36:39], v[4:5], off offset:2064
	s_mov_b32 s0, 0x3002000
	v_add_co_u32_e32 v62, vcc, s0, v2
	s_mov_b32 s1, 0x3003000
	s_nop 0
	v_addc_co_u32_e32 v63, vcc, 0, v3, vcc
	v_add_co_u32_e32 v64, vcc, s1, v2
	s_lshl_b32 s5, s8, 19
	s_nop 0
	v_addc_co_u32_e32 v65, vcc, 0, v3, vcc
	global_load_dwordx4 v[40:43], v[60:61], off
	global_load_dwordx4 v[44:47], v[60:61], off offset:16
	global_load_dwordx4 v[48:51], v[60:61], off offset:2048
	global_load_dwordx4 v[52:55], v[60:61], off offset:2064
	global_load_dwordx4 v[56:59], v[64:65], off offset:-4096
	global_load_dwordx4 v[26:29], v[62:63], off offset:16
	global_load_dwordx4 v[14:17], v[62:63], off offset:2048
	global_load_dwordx4 v[10:13], v[62:63], off offset:2064
	global_load_dwordx4 v[6:9], v[64:65], off
	global_load_dwordx4 v[2:5], v[64:65], off offset:16
	s_add_u32 s5, s2, s5
	s_addc_u32 s8, s3, 0
	s_lshl_b32 s4, s4, 10
	s_and_b32 s0, s4, 0x3e000
	s_add_u32 s4, s5, s0
	s_addc_u32 s5, s8, 0
	s_mov_b32 s9, 0x42fe0000
	s_lshl_b64 s[0:1], s[6:7], 2
	s_add_u32 s0, s2, s0
	s_addc_u32 s1, s3, s1
	s_add_u32 s0, s0, 0xfc00000
	s_addc_u32 s1, s1, 0
	s_lshl_b64 s[6:7], s[6:7], 4
	s_mov_b32 s8, 0x40c0c00
	s_add_u32 s2, s2, s6
	s_mov_b32 s6, 0xa800000
	s_addc_u32 s3, s3, s7
	s_add_u32 s2, s2, 0xda00000
	s_addc_u32 s3, s3, 0
	s_waitcnt vmcnt(12)
	v_lshlrev_b32_e32 v148, 16, v22
	v_lshlrev_b32_e32 v140, 16, v18
	v_and_b32_e32 v141, 0xffff0000, v18
	v_lshlrev_b32_e32 v142, 16, v19
	v_and_b32_e32 v143, 0xffff0000, v19
	v_max3_f32 v18, |v140|, 0, |v141|
	v_lshlrev_b32_e32 v144, 16, v20
	v_and_b32_e32 v145, 0xffff0000, v20
	v_max3_f32 v18, v18, |v142|, |v143|
	v_lshlrev_b32_e32 v146, 16, v21
	v_and_b32_e32 v147, 0xffff0000, v21
	v_max3_f32 v18, v18, |v144|, |v145|
	v_and_b32_e32 v149, 0xffff0000, v22
	v_max3_f32 v18, v18, |v146|, |v147|
	v_lshlrev_b32_e32 v134, 16, v23
	v_and_b32_e32 v132, 0xffff0000, v23
	v_max3_f32 v18, v18, |v148|, |v149|
	v_lshlrev_b32_e32 v150, 16, v24
	v_and_b32_e32 v151, 0xffff0000, v24
	v_max3_f32 v18, v18, |v134|, |v132|
	v_lshlrev_b32_e32 v133, 16, v25
	v_and_b32_e32 v131, 0xffff0000, v25
	v_max3_f32 v18, v18, |v150|, |v151|
	v_max3_f32 v18, v18, |v133|, |v131|
	ds_swizzle_b32 v19, v18 offset:swizzle(SWAP,1)
	s_waitcnt vmcnt(11)
	v_lshlrev_b32_e32 v130, 16, v32
	v_and_b32_e32 v128, 0xffff0000, v32
	v_lshlrev_b32_e32 v122, 16, v33
	v_and_b32_e32 v119, 0xffff0000, v33
	s_waitcnt lgkmcnt(0)
	v_max_f32_e32 v19, v19, v19
	v_max_f32_e32 v18, v18, v19
	ds_swizzle_b32 v19, v18 offset:swizzle(SWAP,2)
	v_max3_f32 v20, |v130|, 0, |v128|
	v_lshlrev_b32_e32 v129, 16, v34
	v_and_b32_e32 v127, 0xffff0000, v34
	v_max3_f32 v20, v20, |v122|, |v119|
	s_waitcnt lgkmcnt(0)
	v_max_f32_e32 v19, v19, v19
	v_max_f32_e32 v18, v18, v19
	ds_swizzle_b32 v19, v18 offset:swizzle(SWAP,4)
	v_lshlrev_b32_e32 v123, 16, v35
	v_and_b32_e32 v121, 0xffff0000, v35
	v_max3_f32 v20, v20, |v129|, |v127|
	s_waitcnt vmcnt(10)
	v_lshlrev_b32_e32 v117, 16, v36
	s_waitcnt lgkmcnt(0)
	v_max_f32_e32 v19, v19, v19
	v_max_f32_e32 v18, v18, v19
	ds_swizzle_b32 v19, v18 offset:swizzle(SWAP,8)
	v_and_b32_e32 v116, 0xffff0000, v36
	v_max3_f32 v20, v20, |v123|, |v121|
	v_lshlrev_b32_e32 v113, 16, v37
	v_and_b32_e32 v114, 0xffff0000, v37
	s_waitcnt lgkmcnt(0)
	v_max_f32_e32 v19, v19, v19
	v_max_f32_e32 v30, v18, v19
	v_max3_f32 v18, v20, |v117|, |v116|
	v_lshlrev_b32_e32 v120, 16, v38
	v_and_b32_e32 v118, 0xffff0000, v38
	v_max3_f32 v18, v18, |v113|, |v114|
	v_lshlrev_b32_e32 v115, 16, v39
	v_and_b32_e32 v112, 0xffff0000, v39
	v_max3_f32 v18, v18, |v120|, |v118|
	ds_swizzle_b32 v32, v30 offset:swizzle(SWAP,16)
	v_max3_f32 v33, v18, |v115|, |v112|
	ds_swizzle_b32 v34, v33 offset:swizzle(SWAP,1)
	s_waitcnt vmcnt(9)
	v_lshlrev_b32_e32 v111, 16, v40
	v_and_b32_e32 v109, 0xffff0000, v40
	s_waitcnt lgkmcnt(1)
	v_max_f32_e32 v32, v32, v32
	v_max_f32_e32 v30, v30, v32
	s_waitcnt lgkmcnt(0)
	v_max_f32_e32 v32, v34, v34
	v_max_f32_e32 v32, v33, v32
	v_lshlrev_b32_e32 v106, 16, v41
	v_and_b32_e32 v105, 0xffff0000, v41
	v_max3_f32 v35, |v111|, 0, |v109|
	global_load_dwordx4 v[22:25], v[64:65], off offset:2048
	global_load_dwordx4 v[18:21], v[64:65], off offset:2064
	ds_swizzle_b32 v33, v32 offset:swizzle(SWAP,2)
	v_lshlrev_b32_e32 v110, 16, v42
	v_and_b32_e32 v108, 0xffff0000, v42
	v_max3_f32 v35, v35, |v106|, |v105|
	v_lshlrev_b32_e32 v107, 16, v43
	v_and_b32_e32 v104, 0xffff0000, v43
	v_max3_f32 v35, v35, |v110|, |v108|
	v_max3_f32 v35, v35, |v107|, |v104|
	s_waitcnt vmcnt(10)
	v_lshlrev_b32_e32 v103, 16, v44
	v_and_b32_e32 v101, 0xffff0000, v44
	v_lshlrev_b32_e32 v99, 16, v45
	v_and_b32_e32 v95, 0xffff0000, v45
	v_max3_f32 v35, v35, |v103|, |v101|
	v_lshlrev_b32_e32 v102, 16, v46
	v_and_b32_e32 v100, 0xffff0000, v46
	v_max3_f32 v35, v35, |v99|, |v95|
	s_waitcnt lgkmcnt(0)
	v_max_f32_e32 v33, v33, v33
	v_lshlrev_b32_e32 v98, 16, v47
	v_and_b32_e32 v94, 0xffff0000, v47
	v_max3_f32 v35, v35, |v102|, |v100|
	v_max_f32_e32 v32, v32, v33
	v_max3_f32 v35, v35, |v98|, |v94|
	ds_swizzle_b32 v33, v32 offset:swizzle(SWAP,4)
	ds_swizzle_b32 v36, v35 offset:swizzle(SWAP,1)
	v_mov_b32_e32 v34, v30
	s_nop 1
	v_permlane32_swap_b32_e32 v30, v34
	s_waitcnt lgkmcnt(1)
	v_max_f32_e32 v33, v33, v33
	s_waitcnt lgkmcnt(0)
	v_max_f32_e32 v36, v36, v36
	v_max_f32_e32 v32, v32, v33
	v_max_f32_e32 v35, v35, v36
	ds_swizzle_b32 v33, v32 offset:swizzle(SWAP,8)
	ds_swizzle_b32 v36, v35 offset:swizzle(SWAP,2)
	v_max_f32_e32 v34, v34, v34
	v_max_f32_e32 v30, v30, v30
	v_max_f32_e32 v137, v30, v34
	s_waitcnt lgkmcnt(1)
	v_max_f32_e32 v30, v33, v33
	s_waitcnt lgkmcnt(0)
	v_max_f32_e32 v33, v36, v36
	s_waitcnt vmcnt(9)
	v_lshlrev_b32_e32 v93, 16, v48
	v_and_b32_e32 v91, 0xffff0000, v48
	v_max_f32_e32 v33, v35, v33
	v_lshlrev_b32_e32 v89, 16, v49
	v_and_b32_e32 v87, 0xffff0000, v49
	v_max3_f32 v35, |v93|, 0, |v91|
	v_lshlrev_b32_e32 v92, 16, v50
	v_and_b32_e32 v90, 0xffff0000, v50
	v_max3_f32 v35, v35, |v89|, |v87|
	v_lshlrev_b32_e32 v88, 16, v51
	v_and_b32_e32 v86, 0xffff0000, v51
	v_max3_f32 v35, v35, |v92|, |v90|
	v_max3_f32 v35, v35, |v88|, |v86|
	s_waitcnt vmcnt(8)
	v_lshlrev_b32_e32 v85, 16, v52
	v_and_b32_e32 v83, 0xffff0000, v52
	v_lshlrev_b32_e32 v81, 16, v53
	v_and_b32_e32 v79, 0xffff0000, v53
	v_max3_f32 v35, v35, |v85|, |v83|
	v_lshlrev_b32_e32 v84, 16, v54
	v_and_b32_e32 v82, 0xffff0000, v54
	v_max3_f32 v35, v35, |v81|, |v79|
	v_lshlrev_b32_e32 v80, 16, v55
	v_and_b32_e32 v78, 0xffff0000, v55
	v_max3_f32 v35, v35, |v84|, |v82|
	ds_swizzle_b32 v34, v33 offset:swizzle(SWAP,4)
	v_max3_f32 v35, v35, |v80|, |v78|
	ds_swizzle_b32 v36, v35 offset:swizzle(SWAP,1)
	v_max_f32_e32 v30, v32, v30
	ds_swizzle_b32 v32, v30 offset:swizzle(SWAP,16)
	s_waitcnt lgkmcnt(2)
	v_max_f32_e32 v34, v34, v34
	v_max_f32_e32 v33, v33, v34
	s_waitcnt lgkmcnt(1)
	v_max_f32_e32 v36, v36, v36
	ds_swizzle_b32 v34, v33 offset:swizzle(SWAP,8)
	v_max_f32_e32 v35, v35, v36
	ds_swizzle_b32 v36, v35 offset:swizzle(SWAP,2)
	s_waitcnt lgkmcnt(2)
	v_max_f32_e32 v32, v32, v32
	v_max_f32_e32 v138, v30, v32
	s_waitcnt lgkmcnt(1)
	v_max_f32_e32 v30, v34, v34
	v_max_f32_e32 v30, v33, v30
	s_waitcnt lgkmcnt(0)
	v_max_f32_e32 v33, v36, v36
	s_waitcnt vmcnt(7)
	v_lshlrev_b32_e32 v77, 16, v56
	v_and_b32_e32 v75, 0xffff0000, v56
	v_max_f32_e32 v33, v35, v33
	v_lshlrev_b32_e32 v72, 16, v57
	v_and_b32_e32 v71, 0xffff0000, v57
	v_max3_f32 v35, |v77|, 0, |v75|
	v_lshlrev_b32_e32 v76, 16, v58
	v_and_b32_e32 v74, 0xffff0000, v58
	v_max3_f32 v35, v35, |v72|, |v71|
	v_lshlrev_b32_e32 v73, 16, v59
	v_and_b32_e32 v70, 0xffff0000, v59
	v_max3_f32 v35, v35, |v76|, |v74|
	v_max3_f32 v35, v35, |v73|, |v70|
	s_waitcnt vmcnt(6)
	v_lshlrev_b32_e32 v69, 16, v26
	v_and_b32_e32 v67, 0xffff0000, v26
	v_lshlrev_b32_e32 v65, 16, v27
	v_and_b32_e32 v63, 0xffff0000, v27
	v_max3_f32 v26, v35, |v69|, |v67|
	v_lshlrev_b32_e32 v68, 16, v28
	v_and_b32_e32 v66, 0xffff0000, v28
	v_max3_f32 v26, v26, |v65|, |v63|
	v_lshlrev_b32_e32 v64, 16, v29
	v_and_b32_e32 v62, 0xffff0000, v29
	v_max3_f32 v26, v26, |v68|, |v66|
	v_max3_f32 v26, v26, |v64|, |v62|
	s_waitcnt vmcnt(5)
	v_lshlrev_b32_e32 v61, 16, v14
	v_and_b32_e32 v59, 0xffff0000, v14
	ds_swizzle_b32 v27, v26 offset:swizzle(SWAP,1)
	v_lshlrev_b32_e32 v57, 16, v15
	v_and_b32_e32 v55, 0xffff0000, v15
	v_max3_f32 v14, |v61|, 0, |v59|
	v_lshlrev_b32_e32 v60, 16, v16
	v_and_b32_e32 v58, 0xffff0000, v16
	v_max3_f32 v14, v14, |v57|, |v55|
	v_lshlrev_b32_e32 v56, 16, v17
	v_and_b32_e32 v54, 0xffff0000, v17
	v_max3_f32 v14, v14, |v60|, |v58|
	v_max3_f32 v14, v14, |v56|, |v54|
	s_waitcnt vmcnt(4)
	v_lshlrev_b32_e32 v53, 16, v10
	v_and_b32_e32 v51, 0xffff0000, v10
	v_lshlrev_b32_e32 v49, 16, v11
	v_and_b32_e32 v47, 0xffff0000, v11
	v_max3_f32 v10, v14, |v53|, |v51|
	s_waitcnt lgkmcnt(0)
	v_max_f32_e32 v27, v27, v27
	v_lshlrev_b32_e32 v52, 16, v12
	v_and_b32_e32 v50, 0xffff0000, v12
	v_max3_f32 v10, v10, |v49|, |v47|
	v_max_f32_e32 v26, v26, v27
	v_lshlrev_b32_e32 v48, 16, v13
	v_and_b32_e32 v46, 0xffff0000, v13
	v_max3_f32 v10, v10, |v52|, |v50|
	ds_swizzle_b32 v27, v26 offset:swizzle(SWAP,2)
	v_max3_f32 v10, v10, |v48|, |v46|
	ds_swizzle_b32 v11, v10 offset:swizzle(SWAP,1)
	ds_swizzle_b32 v34, v33 offset:swizzle(SWAP,4)
	ds_swizzle_b32 v32, v30 offset:swizzle(SWAP,16)
	s_waitcnt lgkmcnt(3)
	v_max_f32_e32 v27, v27, v27
	v_max_f32_e32 v26, v26, v27
	s_waitcnt lgkmcnt(2)
	v_max_f32_e32 v11, v11, v11
	ds_swizzle_b32 v27, v26 offset:swizzle(SWAP,4)
	v_max_f32_e32 v10, v10, v11
	ds_swizzle_b32 v11, v10 offset:swizzle(SWAP,2)
	s_waitcnt lgkmcnt(3)
	v_max_f32_e32 v34, v34, v34
	v_max_f32_e32 v33, v33, v34
	ds_swizzle_b32 v34, v33 offset:swizzle(SWAP,8)
	s_waitcnt lgkmcnt(2)
	v_max_f32_e32 v12, v27, v27
	v_max_f32_e32 v12, v26, v12
	s_waitcnt lgkmcnt(1)
	v_max_f32_e32 v11, v11, v11
	ds_swizzle_b32 v13, v12 offset:swizzle(SWAP,8)
	v_max_f32_e32 v10, v10, v11
	ds_swizzle_b32 v11, v10 offset:swizzle(SWAP,4)
	s_waitcnt lgkmcnt(2)
	v_max_f32_e32 v28, v34, v34
	v_max_f32_e32 v28, v33, v28
	ds_swizzle_b32 v29, v28 offset:swizzle(SWAP,16)
	s_waitcnt lgkmcnt(2)
	v_max_f32_e32 v13, v13, v13
	v_max_f32_e32 v12, v12, v13
	s_waitcnt lgkmcnt(1)
	v_max_f32_e32 v11, v11, v11
	ds_swizzle_b32 v13, v12 offset:swizzle(SWAP,16)
	v_max_f32_e32 v10, v10, v11
	ds_swizzle_b32 v11, v10 offset:swizzle(SWAP,8)
	s_waitcnt vmcnt(3)
	v_lshlrev_b32_e32 v45, 16, v6
	v_and_b32_e32 v43, 0xffff0000, v6
	v_max_f32_e32 v32, v32, v32
	s_waitcnt lgkmcnt(2)
	v_max_f32_e32 v29, v29, v29
	v_lshlrev_b32_e32 v40, 16, v7
	v_and_b32_e32 v39, 0xffff0000, v7
	v_max3_f32 v6, |v45|, 0, |v43|
	s_waitcnt vmcnt(1)
	v_lshlrev_b32_e32 v27, 16, v22
	v_and_b32_e32 v26, 0xffff0000, v22
	v_max_f32_e32 v135, v30, v32
	v_max_f32_e32 v124, v28, v29
	v_lshlrev_b32_e32 v44, 16, v8
	v_and_b32_e32 v42, 0xffff0000, v8
	v_max3_f32 v6, v6, |v40|, |v39|
	v_lshlrev_b32_e32 v32, 16, v5
	v_and_b32_e32 v28, 0xffff0000, v5
	v_lshlrev_b32_e32 v17, 16, v23
	v_and_b32_e32 v15, 0xffff0000, v23
	v_max3_f32 v5, |v27|, 0, |v26|
	v_lshlrev_b32_e32 v41, 16, v9
	v_and_b32_e32 v38, 0xffff0000, v9
	v_max3_f32 v6, v6, |v44|, |v42|
	v_lshlrev_b32_e32 v23, 16, v24
	v_and_b32_e32 v22, 0xffff0000, v24
	v_max3_f32 v5, v5, |v17|, |v15|
	s_waitcnt lgkmcnt(1)
	v_max_f32_e32 v13, v13, v13
	v_max3_f32 v6, v6, |v41|, |v38|
	v_lshlrev_b32_e32 v37, 16, v2
	v_and_b32_e32 v35, 0xffff0000, v2
	v_lshlrev_b32_e32 v16, 16, v25
	v_and_b32_e32 v14, 0xffff0000, v25
	v_max3_f32 v5, v5, |v23|, |v22|
	v_max_f32_e32 v96, v12, v13
	v_lshlrev_b32_e32 v33, 16, v3
	v_and_b32_e32 v29, 0xffff0000, v3
	v_lshlrev_b32_e32 v36, 16, v4
	v_and_b32_e32 v34, 0xffff0000, v4
	v_max3_f32 v2, v6, |v37|, |v35|
	s_waitcnt lgkmcnt(0)
	v_max_f32_e32 v4, v11, v11
	v_max3_f32 v5, v5, |v16|, |v14|
	s_waitcnt vmcnt(0)
	v_lshlrev_b32_e32 v13, 16, v18
	v_and_b32_e32 v11, 0xffff0000, v18
	v_max3_f32 v2, v2, |v33|, |v29|
	v_lshlrev_b32_e32 v9, 16, v19
	v_and_b32_e32 v7, 0xffff0000, v19
	v_max3_f32 v5, v5, |v13|, |v11|
	v_max3_f32 v2, v2, |v36|, |v34|
	v_max_f32_e32 v4, v10, v4
	v_lshlrev_b32_e32 v12, 16, v20
	v_and_b32_e32 v10, 0xffff0000, v20
	v_max3_f32 v5, v5, |v9|, |v7|
	v_max3_f32 v2, v2, |v32|, |v28|
	v_lshlrev_b32_e32 v8, 16, v21
	v_and_b32_e32 v6, 0xffff0000, v21
	v_max3_f32 v5, v5, |v12|, |v10|
	ds_swizzle_b32 v3, v2 offset:swizzle(SWAP,1)
	v_max3_f32 v5, v5, |v8|, |v6|
	ds_swizzle_b32 v18, v5 offset:swizzle(SWAP,1)
	ds_swizzle_b32 v19, v4 offset:swizzle(SWAP,16)
	v_lshlrev_b32_e32 v30, 4, v126
	s_waitcnt lgkmcnt(2)
	v_max_f32_e32 v3, v3, v3
	v_max_f32_e32 v2, v2, v3
	s_waitcnt lgkmcnt(1)
	v_max_f32_e32 v18, v18, v18
	ds_swizzle_b32 v3, v2 offset:swizzle(SWAP,2)
	v_max_f32_e32 v5, v5, v18
	ds_swizzle_b32 v18, v5 offset:swizzle(SWAP,2)
	s_waitcnt lgkmcnt(2)
	v_max_f32_e32 v19, v19, v19
	v_max_f32_e32 v24, v4, v19
	s_waitcnt lgkmcnt(1)
	v_max_f32_e32 v3, v3, v3
	v_max_f32_e32 v2, v2, v3
	s_waitcnt lgkmcnt(0)
	v_max_f32_e32 v18, v18, v18
	ds_swizzle_b32 v3, v2 offset:swizzle(SWAP,4)
	v_max_f32_e32 v5, v5, v18
	ds_swizzle_b32 v18, v5 offset:swizzle(SWAP,4)
	v_mov_b32_e32 v139, v138
	v_mov_b32_e32 v136, v135
	s_waitcnt lgkmcnt(1)
	v_max_f32_e32 v3, v3, v3
	v_max_f32_e32 v2, v2, v3
	s_waitcnt lgkmcnt(0)
	v_max_f32_e32 v4, v18, v18
	ds_swizzle_b32 v3, v2 offset:swizzle(SWAP,8)
	v_max_f32_e32 v4, v5, v4
	ds_swizzle_b32 v5, v4 offset:swizzle(SWAP,8)
	v_mov_b32_e32 v125, v124
	v_mov_b32_e32 v97, v96
	s_waitcnt lgkmcnt(1)
	v_max_f32_e32 v3, v3, v3
	v_max_f32_e32 v2, v2, v3
	s_waitcnt lgkmcnt(0)
	v_max_f32_e32 v5, v5, v5
	ds_swizzle_b32 v3, v2 offset:swizzle(SWAP,16)
	v_max_f32_e32 v4, v4, v5
	ds_swizzle_b32 v5, v4 offset:swizzle(SWAP,16)
	v_mov_b32_e32 v25, v24
	v_permlane32_swap_b32_e32 v138, v139
	s_waitcnt lgkmcnt(1)
	v_max_f32_e32 v3, v3, v3
	v_max_f32_e32 v20, v2, v3
	s_waitcnt lgkmcnt(0)
	v_max_f32_e32 v2, v5, v5
	v_max_f32_e32 v18, v4, v2
	v_lshl_add_u64 v[4:5], s[4:5], 0, v[30:31]
	v_div_scale_f32 v30, s[4:5], v137, v137, s9
	v_rcp_f32_e32 v152, v30
	s_mov_b64 s[4:5], 0xa800000
	v_lshl_add_u64 v[2:3], v[4:5], 0, s[4:5]
	v_cmp_eq_u32_e64 s[4:5], 0, v126
	v_fma_f32 v126, -v30, v152, 1.0
	v_fmac_f32_e32 v152, v126, v152
	v_div_scale_f32 v126, vcc, s9, v137, s9
	v_mul_f32_e32 v153, v126, v152
	v_fma_f32 v154, -v30, v153, v126
	v_fmac_f32_e32 v153, v154, v152
	v_fma_f32 v30, -v30, v153, v126
	v_div_fmas_f32 v30, v30, v152, v153
	v_div_fixup_f32 v30, v30, v137, s9
	v_cmp_lt_f32_e32 vcc, 0, v137
	v_mov_b32_e32 v21, v20
	v_mov_b32_e32 v19, v18
	v_cndmask_b32_e32 v30, 0, v30, vcc
	v_mul_f32_e32 v126, v30, v140
	v_mul_f32_e32 v140, v30, v141
	v_rndne_f32_e32 v140, v140
	v_mul_f32_e32 v141, v30, v144
	v_mul_f32_e32 v144, v30, v145
	v_mul_f32_e32 v142, v30, v142
	v_mul_f32_e32 v143, v30, v143
	v_rndne_f32_e32 v126, v126
	v_cvt_i32_f32_e32 v140, v140
	v_rndne_f32_e32 v144, v144
	v_rndne_f32_e32 v142, v142
	v_mul_f32_e32 v145, v30, v146
	v_rndne_f32_e32 v143, v143
	v_mul_f32_e32 v146, v30, v147
	v_cvt_i32_f32_e32 v126, v126
	v_rndne_f32_e32 v141, v141
	v_cvt_i32_f32_e32 v144, v144
	v_cvt_i32_f32_sdwa v142, v142 dst_sel:WORD_1 dst_unused:UNUSED_PAD src0_sel:DWORD
	v_rndne_f32_e32 v145, v145
	v_cvt_i32_f32_e32 v143, v143
	v_rndne_f32_e32 v146, v146
	v_cvt_i32_f32_e32 v141, v141
	v_cvt_i32_f32_sdwa v145, v145 dst_sel:WORD_1 dst_unused:UNUSED_PAD src0_sel:DWORD
	v_cvt_i32_f32_e32 v146, v146
	v_lshlrev_b32_e32 v140, 8, v140
	v_and_b32_e32 v140, 0xff00, v140
	v_lshlrev_b32_e32 v144, 8, v144
	v_and_b32_e32 v142, 0xff0000, v142
	v_perm_b32 v126, v143, v126, s8
	v_and_b32_e32 v144, 0xff00, v144
	v_and_b32_e32 v145, 0xff0000, v145
	v_or3_b32 v140, v126, v140, v142
	v_perm_b32 v126, v146, v141, s8
	v_add_co_u32_e32 v4, vcc, s6, v4
	v_or3_b32 v141, v126, v144, v145
	s_nop 0
	v_addc_co_u32_e32 v5, vcc, 0, v5, vcc
	v_mov_b32_e32 v200, v140
	v_mov_b32_e32 v201, v141
	v_mul_f32_e32 v5, v30, v149
	v_mul_f32_e32 v4, v30, v148
	v_rndne_f32_e32 v5, v5
	v_mul_f32_e32 v140, v30, v151
	v_mul_f32_e32 v134, v30, v134
	v_mul_f32_e32 v132, v30, v132
	v_rndne_f32_e32 v4, v4
	v_cvt_i32_f32_e32 v5, v5
	v_mul_f32_e32 v126, v30, v150
	v_rndne_f32_e32 v140, v140
	v_rndne_f32_e32 v134, v134
	v_mul_f32_e32 v133, v30, v133
	v_rndne_f32_e32 v132, v132
	v_mul_f32_e32 v30, v30, v131
	v_cvt_i32_f32_e32 v4, v4
	v_rndne_f32_e32 v126, v126
	v_cvt_i32_f32_e32 v140, v140
	v_cvt_i32_f32_sdwa v134, v134 dst_sel:WORD_1 dst_unused:UNUSED_PAD src0_sel:DWORD
	v_rndne_f32_e32 v133, v133
	v_cvt_i32_f32_e32 v132, v132
	v_rndne_f32_e32 v30, v30
	v_cvt_i32_f32_e32 v126, v126
	v_cvt_i32_f32_sdwa v133, v133 dst_sel:WORD_1 dst_unused:UNUSED_PAD src0_sel:DWORD
	v_cvt_i32_f32_e32 v30, v30
	v_lshlrev_b32_e32 v5, 8, v5
	v_and_b32_e32 v5, 0xff00, v5
	v_lshlrev_b32_e32 v140, 8, v140
	v_and_b32_e32 v134, 0xff0000, v134
	v_perm_b32 v4, v132, v4, s8
	v_and_b32_e32 v140, 0xff00, v140
	v_and_b32_e32 v131, 0xff0000, v133
	v_or3_b32 v4, v4, v5, v134
	v_perm_b32 v5, v30, v126, s8
	v_permlane32_swap_b32_e32 v135, v136
	v_permlane32_swap_b32_e32 v124, v125
	v_permlane32_swap_b32_e32 v96, v97
	v_permlane32_swap_b32_e32 v24, v25
	v_permlane32_swap_b32_e32 v20, v21
	v_permlane32_swap_b32_e32 v18, v19
	v_or3_b32 v5, v5, v140, v131
	v_mov_b32_e32 v202, v4
	v_mov_b32_e32 v203, v5
	global_store_dwordx4 v[2:3], v[200:203], off
	s_and_saveexec_b64 s[6:7], s[4:5]
	s_cbranch_execz .LBB0_296
	global_load_dwordx4 v[140:143], v31, s[2:3]
	s_waitcnt vmcnt(0)
	v_mov_b32_e32 v4, v141
	v_mov_b32_e32 v5, v142
	v_mov_b32_e32 v141, v143
	v_pk_add_f32 v[4:5], v[4:5], v[140:141]
	s_nop 0
	v_add_f32_e32 v4, v4, v5
	v_mov_b32_e32 v5, 0x358637bd
	v_fmac_f32_e32 v5, 0x3a800000, v4
	v_rsq_f32_e32 v4, v5
	v_mul_f32_e32 v5, 0x3c010204, v137
	v_mul_f32_e32 v4, v5, v4
	global_store_dword v31, v4, s[0:1]
.LBB0_296:
	s_or_b64 exec, exec, s[6:7]
	v_max_f32_e32 v4, v138, v138
	v_max_f32_e32 v5, v139, v139
	v_max_f32_e32 v4, v4, v5
	v_div_scale_f32 v5, s[6:7], v4, v4, s9
	v_rcp_f32_e32 v30, v5
	s_nop 0
	v_fma_f32 v31, -v5, v30, 1.0
	v_fmac_f32_e32 v30, v31, v30
	v_div_scale_f32 v31, vcc, s9, v4, s9
	v_mul_f32_e32 v126, v31, v30
	v_fma_f32 v131, -v5, v126, v31
	v_fmac_f32_e32 v126, v131, v30
	v_fma_f32 v5, -v5, v126, v31
	v_div_fmas_f32 v5, v5, v30, v126
	v_div_fixup_f32 v5, v5, v4, s9
	v_cmp_lt_f32_e32 vcc, 0, v4
	s_nop 1
	v_cndmask_b32_e32 v5, 0, v5, vcc
	v_mul_f32_e32 v31, v5, v128
	v_mul_f32_e32 v30, v5, v130
	v_rndne_f32_e32 v31, v31
	v_mul_f32_e32 v127, v5, v127
	v_mul_f32_e32 v122, v5, v122
	v_mul_f32_e32 v119, v5, v119
	v_rndne_f32_e32 v30, v30
	v_cvt_i32_f32_e32 v31, v31
	v_mul_f32_e32 v126, v5, v129
	v_rndne_f32_e32 v127, v127
	v_rndne_f32_e32 v122, v122
	v_mul_f32_e32 v123, v5, v123
	v_rndne_f32_e32 v119, v119
	v_mul_f32_e32 v121, v5, v121
	v_cvt_i32_f32_e32 v30, v30
	v_rndne_f32_e32 v126, v126
	v_cvt_i32_f32_e32 v127, v127
	v_cvt_i32_f32_sdwa v122, v122 dst_sel:WORD_1 dst_unused:UNUSED_PAD src0_sel:DWORD
	v_rndne_f32_e32 v123, v123
	v_cvt_i32_f32_e32 v119, v119
	v_rndne_f32_e32 v121, v121
	v_cvt_i32_f32_e32 v126, v126
	v_cvt_i32_f32_sdwa v123, v123 dst_sel:WORD_1 dst_unused:UNUSED_PAD src0_sel:DWORD
	v_cvt_i32_f32_e32 v121, v121
	v_lshlrev_b32_e32 v31, 8, v31
	v_and_b32_e32 v31, 0xff00, v31
	v_lshlrev_b32_e32 v127, 8, v127
	v_and_b32_e32 v122, 0xff0000, v122
	v_perm_b32 v30, v119, v30, s8
	v_and_b32_e32 v127, 0xff00, v127
	v_and_b32_e32 v123, 0xff0000, v123
	v_or3_b32 v30, v30, v31, v122
	v_perm_b32 v31, v121, v126, s8
	v_or3_b32 v31, v31, v127, v123
	v_mov_b32_e32 v204, v30
	v_mov_b32_e32 v205, v31
	v_mul_f32_e32 v30, v5, v117
	v_mul_f32_e32 v31, v5, v116
	v_mul_f32_e32 v117, v5, v118
	v_rndne_f32_e32 v31, v31
	v_mul_f32_e32 v116, v5, v120
	v_rndne_f32_e32 v117, v117
	v_mul_f32_e32 v113, v5, v113
	v_mul_f32_e32 v115, v5, v115
	v_mul_f32_e32 v114, v5, v114
	v_mul_f32_e32 v5, v5, v112
	v_rndne_f32_e32 v30, v30
	v_cvt_i32_f32_e32 v31, v31
	v_rndne_f32_e32 v116, v116
	v_cvt_i32_f32_e32 v117, v117
	v_rndne_f32_e32 v113, v113
	v_rndne_f32_e32 v115, v115
	v_rndne_f32_e32 v114, v114
	v_rndne_f32_e32 v5, v5
	v_cvt_i32_f32_e32 v30, v30
	v_cvt_i32_f32_e32 v116, v116
	v_cvt_i32_f32_sdwa v113, v113 dst_sel:WORD_1 dst_unused:UNUSED_PAD src0_sel:DWORD
	v_cvt_i32_f32_sdwa v115, v115 dst_sel:WORD_1 dst_unused:UNUSED_PAD src0_sel:DWORD
	v_cvt_i32_f32_e32 v114, v114
	v_cvt_i32_f32_e32 v5, v5
	v_lshlrev_b32_e32 v31, 8, v31
	v_lshlrev_b32_e32 v117, 8, v117
	v_and_b32_e32 v31, 0xff00, v31
	v_and_b32_e32 v117, 0xff00, v117
	v_and_b32_e32 v113, 0xff0000, v113
	v_and_b32_e32 v112, 0xff0000, v115
	v_perm_b32 v30, v114, v30, s8
	v_perm_b32 v5, v5, v116, s8
	v_or3_b32 v30, v30, v31, v113
	v_or3_b32 v31, v5, v117, v112
	v_mov_b32_e32 v206, v30
	v_mov_b32_e32 v207, v31
	global_store_dwordx4 v[2:3], v[204:207], off offset:1024
	s_and_saveexec_b64 s[6:7], s[4:5]
	s_cbranch_execz .LBB0_298
	v_mov_b32_e32 v5, 0
	global_load_dwordx4 v[112:115], v5, s[2:3] offset:16
	v_mul_f32_e32 v4, 0x3c010204, v4
	s_waitcnt vmcnt(0)
	v_mov_b32_e32 v30, v113
	v_mov_b32_e32 v31, v114
	v_mov_b32_e32 v113, v115
	v_pk_add_f32 v[30:31], v[30:31], v[112:113]
	s_nop 0
	v_add_f32_e32 v30, v30, v31
	v_mov_b32_e32 v31, 0x358637bd
	v_fmac_f32_e32 v31, 0x3a800000, v30
	v_rsq_f32_e32 v30, v31
	s_nop 0
	v_mul_f32_e32 v4, v4, v30
	global_store_dword v5, v4, s[0:1] offset:4
.LBB0_298:
	s_or_b64 exec, exec, s[6:7]
	v_max_f32_e32 v4, v135, v135
	v_max_f32_e32 v5, v136, v136
	v_max_f32_e32 v4, v4, v5
	v_div_scale_f32 v5, s[6:7], v4, v4, s9
	v_rcp_f32_e32 v30, v5
	s_nop 0
	v_fma_f32 v31, -v5, v30, 1.0
	v_fmac_f32_e32 v30, v31, v30
	v_div_scale_f32 v31, vcc, s9, v4, s9
	v_mul_f32_e32 v112, v31, v30
	v_fma_f32 v113, -v5, v112, v31
	v_fmac_f32_e32 v112, v113, v30
	v_fma_f32 v5, -v5, v112, v31
	v_div_fmas_f32 v5, v5, v30, v112
	v_div_fixup_f32 v5, v5, v4, s9
	v_cmp_lt_f32_e32 vcc, 0, v4
	s_nop 1
	v_cndmask_b32_e32 v5, 0, v5, vcc
	v_mul_f32_e32 v31, v5, v109
	v_mul_f32_e32 v30, v5, v111
	v_rndne_f32_e32 v31, v31
	v_mul_f32_e32 v108, v5, v108
	v_mul_f32_e32 v106, v5, v106
	v_mul_f32_e32 v105, v5, v105
	v_rndne_f32_e32 v30, v30
	v_cvt_i32_f32_e32 v31, v31
	v_mul_f32_e32 v109, v5, v110
	v_rndne_f32_e32 v108, v108
	v_rndne_f32_e32 v106, v106
	v_mul_f32_e32 v107, v5, v107
	v_rndne_f32_e32 v105, v105
	v_mul_f32_e32 v104, v5, v104
	v_cvt_i32_f32_e32 v30, v30
	v_rndne_f32_e32 v109, v109
	v_cvt_i32_f32_e32 v108, v108
	v_cvt_i32_f32_sdwa v106, v106 dst_sel:WORD_1 dst_unused:UNUSED_PAD src0_sel:DWORD
	v_rndne_f32_e32 v107, v107
	v_cvt_i32_f32_e32 v105, v105
	v_rndne_f32_e32 v104, v104
	v_cvt_i32_f32_e32 v109, v109
	v_cvt_i32_f32_sdwa v107, v107 dst_sel:WORD_1 dst_unused:UNUSED_PAD src0_sel:DWORD
	v_cvt_i32_f32_e32 v104, v104
	v_lshlrev_b32_e32 v31, 8, v31
	v_and_b32_e32 v31, 0xff00, v31
	v_lshlrev_b32_e32 v108, 8, v108
	v_and_b32_e32 v106, 0xff0000, v106
	v_perm_b32 v30, v105, v30, s8
	v_and_b32_e32 v108, 0xff00, v108
	v_and_b32_e32 v107, 0xff0000, v107
	v_or3_b32 v30, v30, v31, v106
	v_perm_b32 v31, v104, v109, s8
	v_or3_b32 v31, v31, v108, v107
	v_mov_b32_e32 v200, v30
	v_mov_b32_e32 v201, v31
	v_mul_f32_e32 v31, v5, v101
	v_mul_f32_e32 v100, v5, v100
	v_mul_f32_e32 v30, v5, v103
	v_rndne_f32_e32 v31, v31
	v_mul_f32_e32 v101, v5, v102
	v_rndne_f32_e32 v100, v100
	v_mul_f32_e32 v99, v5, v99
	v_mul_f32_e32 v98, v5, v98
	v_mul_f32_e32 v95, v5, v95
	v_mul_f32_e32 v5, v5, v94
	v_rndne_f32_e32 v30, v30
	v_cvt_i32_f32_e32 v31, v31
	v_rndne_f32_e32 v101, v101
	v_cvt_i32_f32_e32 v100, v100
	v_rndne_f32_e32 v99, v99
	v_rndne_f32_e32 v98, v98
	v_rndne_f32_e32 v95, v95
	v_rndne_f32_e32 v5, v5
	v_cvt_i32_f32_e32 v30, v30
	v_cvt_i32_f32_e32 v101, v101
	v_cvt_i32_f32_sdwa v99, v99 dst_sel:WORD_1 dst_unused:UNUSED_PAD src0_sel:DWORD
	v_cvt_i32_f32_sdwa v98, v98 dst_sel:WORD_1 dst_unused:UNUSED_PAD src0_sel:DWORD
	v_cvt_i32_f32_e32 v95, v95
	v_cvt_i32_f32_e32 v5, v5
	v_lshlrev_b32_e32 v31, 8, v31
	v_lshlrev_b32_e32 v100, 8, v100
	v_and_b32_e32 v31, 0xff00, v31
	v_and_b32_e32 v100, 0xff00, v100
	v_and_b32_e32 v99, 0xff0000, v99
	v_and_b32_e32 v94, 0xff0000, v98
	v_perm_b32 v30, v95, v30, s8
	v_perm_b32 v5, v5, v101, s8
	v_or3_b32 v30, v30, v31, v99
	v_or3_b32 v31, v5, v100, v94
	v_mov_b32_e32 v202, v30
	v_mov_b32_e32 v203, v31
	global_store_dwordx4 v[2:3], v[200:203], off offset:2048
	s_and_saveexec_b64 s[6:7], s[4:5]
	s_cbranch_execz .LBB0_300
	v_mov_b32_e32 v5, 0
	global_load_dwordx4 v[98:101], v5, s[2:3] offset:32
	v_mul_f32_e32 v4, 0x3c010204, v4
	s_waitcnt vmcnt(0)
	v_mov_b32_e32 v30, v99
	v_mov_b32_e32 v31, v100
	v_mov_b32_e32 v99, v101
	v_pk_add_f32 v[30:31], v[30:31], v[98:99]
	s_nop 0
	v_add_f32_e32 v30, v30, v31
	v_mov_b32_e32 v31, 0x358637bd
	v_fmac_f32_e32 v31, 0x3a800000, v30
	v_rsq_f32_e32 v30, v31
	s_nop 0
	v_mul_f32_e32 v4, v4, v30
	global_store_dword v5, v4, s[0:1] offset:8
.LBB0_300:
	s_or_b64 exec, exec, s[6:7]
	v_max_f32_e32 v4, v124, v124
	v_max_f32_e32 v5, v125, v125
	v_max_f32_e32 v4, v4, v5
	v_div_scale_f32 v5, s[6:7], v4, v4, s9
	v_rcp_f32_e32 v30, v5
	s_nop 0
	v_fma_f32 v31, -v5, v30, 1.0
	v_fmac_f32_e32 v30, v31, v30
	v_div_scale_f32 v31, vcc, s9, v4, s9
	v_mul_f32_e32 v94, v31, v30
	v_fma_f32 v95, -v5, v94, v31
	v_fmac_f32_e32 v94, v95, v30
	v_fma_f32 v5, -v5, v94, v31
	v_div_fmas_f32 v5, v5, v30, v94
	v_div_fixup_f32 v5, v5, v4, s9
	v_cmp_lt_f32_e32 vcc, 0, v4
	s_nop 1
	v_cndmask_b32_e32 v5, 0, v5, vcc
	v_mul_f32_e32 v31, v5, v91
	v_mul_f32_e32 v30, v5, v93
	v_rndne_f32_e32 v31, v31
	v_mul_f32_e32 v90, v5, v90
	v_mul_f32_e32 v89, v5, v89
	v_mul_f32_e32 v87, v5, v87
	v_rndne_f32_e32 v30, v30
	v_cvt_i32_f32_e32 v31, v31
	v_mul_f32_e32 v91, v5, v92
	v_rndne_f32_e32 v90, v90
	v_rndne_f32_e32 v89, v89
	v_mul_f32_e32 v88, v5, v88
	v_rndne_f32_e32 v87, v87
	v_mul_f32_e32 v86, v5, v86
	v_cvt_i32_f32_e32 v30, v30
	v_rndne_f32_e32 v91, v91
	v_cvt_i32_f32_e32 v90, v90
	v_cvt_i32_f32_sdwa v89, v89 dst_sel:WORD_1 dst_unused:UNUSED_PAD src0_sel:DWORD
	v_rndne_f32_e32 v88, v88
	v_cvt_i32_f32_e32 v87, v87
	v_rndne_f32_e32 v86, v86
	v_cvt_i32_f32_e32 v91, v91
	v_cvt_i32_f32_sdwa v88, v88 dst_sel:WORD_1 dst_unused:UNUSED_PAD src0_sel:DWORD
	v_cvt_i32_f32_e32 v86, v86
	v_lshlrev_b32_e32 v31, 8, v31
	v_and_b32_e32 v31, 0xff00, v31
	v_lshlrev_b32_e32 v90, 8, v90
	v_and_b32_e32 v89, 0xff0000, v89
	v_perm_b32 v30, v87, v30, s8
	v_and_b32_e32 v90, 0xff00, v90
	v_and_b32_e32 v88, 0xff0000, v88
	v_or3_b32 v30, v30, v31, v89
	v_perm_b32 v31, v86, v91, s8
	v_or3_b32 v31, v31, v90, v88
	v_mov_b32_e32 v204, v30
	v_mov_b32_e32 v205, v31
	v_mul_f32_e32 v31, v5, v83
	v_mul_f32_e32 v82, v5, v82
	v_mul_f32_e32 v30, v5, v85
	v_rndne_f32_e32 v31, v31
	v_mul_f32_e32 v83, v5, v84
	v_rndne_f32_e32 v82, v82
	v_mul_f32_e32 v81, v5, v81
	v_mul_f32_e32 v80, v5, v80
	v_mul_f32_e32 v79, v5, v79
	v_mul_f32_e32 v5, v5, v78
	v_rndne_f32_e32 v30, v30
	v_cvt_i32_f32_e32 v31, v31
	v_rndne_f32_e32 v83, v83
	v_cvt_i32_f32_e32 v82, v82
	v_rndne_f32_e32 v81, v81
	v_rndne_f32_e32 v80, v80
	v_rndne_f32_e32 v79, v79
	v_rndne_f32_e32 v5, v5
	v_cvt_i32_f32_e32 v30, v30
	v_cvt_i32_f32_e32 v83, v83
	v_cvt_i32_f32_sdwa v81, v81 dst_sel:WORD_1 dst_unused:UNUSED_PAD src0_sel:DWORD
	v_cvt_i32_f32_sdwa v80, v80 dst_sel:WORD_1 dst_unused:UNUSED_PAD src0_sel:DWORD
	v_cvt_i32_f32_e32 v79, v79
	v_cvt_i32_f32_e32 v5, v5
	v_lshlrev_b32_e32 v31, 8, v31
	v_lshlrev_b32_e32 v82, 8, v82
	v_and_b32_e32 v31, 0xff00, v31
	v_and_b32_e32 v82, 0xff00, v82
	v_and_b32_e32 v81, 0xff0000, v81
	v_and_b32_e32 v78, 0xff0000, v80
	v_perm_b32 v30, v79, v30, s8
	v_perm_b32 v5, v5, v83, s8
	v_or3_b32 v30, v30, v31, v81
	v_or3_b32 v31, v5, v82, v78
	v_mov_b32_e32 v206, v30
	v_mov_b32_e32 v207, v31
	global_store_dwordx4 v[2:3], v[204:207], off offset:3072
	s_and_saveexec_b64 s[6:7], s[4:5]
	s_cbranch_execz .LBB0_302
	v_mov_b32_e32 v5, 0
	global_load_dwordx4 v[78:81], v5, s[2:3] offset:48
	v_mul_f32_e32 v4, 0x3c010204, v4
	s_waitcnt vmcnt(0)
	v_mov_b32_e32 v30, v79
	v_mov_b32_e32 v31, v80
	v_mov_b32_e32 v79, v81
	v_pk_add_f32 v[30:31], v[30:31], v[78:79]
	s_nop 0
	v_add_f32_e32 v30, v30, v31
	v_mov_b32_e32 v31, 0x358637bd
	v_fmac_f32_e32 v31, 0x3a800000, v30
	v_rsq_f32_e32 v30, v31
	s_nop 0
	v_mul_f32_e32 v4, v4, v30
	global_store_dword v5, v4, s[0:1] offset:12
.LBB0_302:
	s_or_b64 exec, exec, s[6:7]
	v_max_f32_e32 v4, v96, v96
	v_max_f32_e32 v5, v97, v97
	v_max_f32_e32 v30, v4, v5
	v_div_scale_f32 v4, s[6:7], v30, v30, s9
	v_rcp_f32_e32 v5, v4
	s_movk_i32 s6, 0x1000
	v_fma_f32 v31, -v4, v5, 1.0
	v_fmac_f32_e32 v5, v31, v5
	v_div_scale_f32 v31, vcc, s9, v30, s9
	v_mul_f32_e32 v78, v31, v5
	v_fma_f32 v79, -v4, v78, v31
	v_fmac_f32_e32 v78, v79, v5
	v_fma_f32 v4, -v4, v78, v31
	v_div_fmas_f32 v4, v4, v5, v78
	v_div_fixup_f32 v4, v4, v30, s9
	v_cmp_lt_f32_e32 vcc, 0, v30
	s_nop 1
	v_cndmask_b32_e32 v31, 0, v4, vcc
	v_mul_f32_e32 v5, v31, v75
	v_mul_f32_e32 v4, v31, v77
	v_rndne_f32_e32 v5, v5
	v_mul_f32_e32 v74, v31, v74
	v_mul_f32_e32 v72, v31, v72
	v_mul_f32_e32 v71, v31, v71
	v_rndne_f32_e32 v4, v4
	v_cvt_i32_f32_e32 v5, v5
	v_mul_f32_e32 v75, v31, v76
	v_rndne_f32_e32 v74, v74
	v_rndne_f32_e32 v72, v72
	v_mul_f32_e32 v73, v31, v73
	v_rndne_f32_e32 v71, v71
	v_mul_f32_e32 v70, v31, v70
	v_mul_f32_e32 v67, v31, v67
	v_mul_f32_e32 v66, v31, v66
	v_cvt_i32_f32_e32 v4, v4
	v_rndne_f32_e32 v75, v75
	v_cvt_i32_f32_e32 v74, v74
	v_cvt_i32_f32_sdwa v72, v72 dst_sel:WORD_1 dst_unused:UNUSED_PAD src0_sel:DWORD
	v_rndne_f32_e32 v73, v73
	v_cvt_i32_f32_e32 v71, v71
	v_rndne_f32_e32 v70, v70
	v_mul_f32_e32 v69, v31, v69
	v_rndne_f32_e32 v67, v67
	v_mul_f32_e32 v68, v31, v68
	v_rndne_f32_e32 v66, v66
	v_mul_f32_e32 v65, v31, v65
	v_mul_f32_e32 v64, v31, v64
	v_mul_f32_e32 v63, v31, v63
	v_mul_f32_e32 v31, v31, v62
	v_cvt_i32_f32_e32 v75, v75
	v_cvt_i32_f32_sdwa v73, v73 dst_sel:WORD_1 dst_unused:UNUSED_PAD src0_sel:DWORD
	v_cvt_i32_f32_e32 v76, v70
	v_rndne_f32_e32 v69, v69
	v_cvt_i32_f32_e32 v67, v67
	v_rndne_f32_e32 v68, v68
	v_cvt_i32_f32_e32 v66, v66
	v_rndne_f32_e32 v65, v65
	v_rndne_f32_e32 v64, v64
	v_rndne_f32_e32 v63, v63
	v_rndne_f32_e32 v31, v31
	v_cvt_i32_f32_e32 v69, v69
	v_cvt_i32_f32_e32 v68, v68
	v_cvt_i32_f32_sdwa v65, v65 dst_sel:WORD_1 dst_unused:UNUSED_PAD src0_sel:DWORD
	v_cvt_i32_f32_sdwa v64, v64 dst_sel:WORD_1 dst_unused:UNUSED_PAD src0_sel:DWORD
	v_cvt_i32_f32_e32 v63, v63
	v_cvt_i32_f32_e32 v31, v31
	v_lshlrev_b32_e32 v5, 8, v5
	v_and_b32_e32 v5, 0xff00, v5
	v_lshlrev_b32_e32 v74, 8, v74
	v_and_b32_e32 v72, 0xff0000, v72
	v_perm_b32 v4, v71, v4, s8
	v_and_b32_e32 v74, 0xff00, v74
	v_and_b32_e32 v73, 0xff0000, v73
	v_or3_b32 v70, v4, v5, v72
	v_perm_b32 v4, v76, v75, s8
	v_lshlrev_b32_e32 v67, 8, v67
	v_lshlrev_b32_e32 v66, 8, v66
	v_or3_b32 v71, v4, v74, v73
	v_add_co_u32_e32 v4, vcc, s6, v2
	v_and_b32_e32 v67, 0xff00, v67
	v_and_b32_e32 v66, 0xff00, v66
	v_and_b32_e32 v65, 0xff0000, v65
	v_and_b32_e32 v64, 0xff0000, v64
	v_perm_b32 v62, v63, v69, s8
	v_perm_b32 v31, v31, v68, s8
	v_addc_co_u32_e32 v5, vcc, 0, v3, vcc
	v_or3_b32 v62, v62, v67, v65
	v_or3_b32 v63, v31, v66, v64
	v_mov_b32_e32 v200, v70
	v_mov_b32_e32 v201, v71
	v_mov_b32_e32 v202, v62
	v_mov_b32_e32 v203, v63
	global_store_dwordx4 v[4:5], v[200:203], off
	s_and_saveexec_b64 s[6:7], s[4:5]
	s_cbranch_execz .LBB0_304
	v_mov_b32_e32 v31, 0
	global_load_dwordx4 v[62:65], v31, s[2:3] offset:64
	v_mul_f32_e32 v30, 0x3c010204, v30
	s_waitcnt vmcnt(0)
	v_mov_b32_e32 v66, v63
	v_mov_b32_e32 v67, v64
	v_mov_b32_e32 v63, v65
	v_pk_add_f32 v[62:63], v[66:67], v[62:63]
	s_nop 0
	v_add_f32_e32 v62, v62, v63
	v_mov_b32_e32 v63, 0x358637bd
	v_fmac_f32_e32 v63, 0x3a800000, v62
	v_rsq_f32_e32 v62, v63
	s_nop 0
	v_mul_f32_e32 v30, v30, v62
	global_store_dword v31, v30, s[0:1] offset:16
.LBB0_304:
	s_or_b64 exec, exec, s[6:7]
	v_max_f32_e32 v24, v24, v24
	v_max_f32_e32 v25, v25, v25
	v_max_f32_e32 v24, v24, v25
	v_div_scale_f32 v25, s[6:7], v24, v24, s9
	v_rcp_f32_e32 v30, v25
	s_nop 0
	v_fma_f32 v31, -v25, v30, 1.0
	v_fmac_f32_e32 v30, v31, v30
	v_div_scale_f32 v31, vcc, s9, v24, s9
	v_mul_f32_e32 v62, v31, v30
	v_fma_f32 v63, -v25, v62, v31
	v_fmac_f32_e32 v62, v63, v30
	v_fma_f32 v25, -v25, v62, v31
	v_div_fmas_f32 v25, v25, v30, v62
	v_div_fixup_f32 v25, v25, v24, s9
	v_cmp_lt_f32_e32 vcc, 0, v24
	s_nop 1
	v_cndmask_b32_e32 v25, 0, v25, vcc
	v_mul_f32_e32 v31, v25, v59
	v_mul_f32_e32 v30, v25, v61
	v_rndne_f32_e32 v31, v31
	v_mul_f32_e32 v58, v25, v58
	v_mul_f32_e32 v57, v25, v57
	v_mul_f32_e32 v55, v25, v55
	v_rndne_f32_e32 v30, v30
	v_cvt_i32_f32_e32 v31, v31
	v_mul_f32_e32 v59, v25, v60
	v_rndne_f32_e32 v58, v58
	v_rndne_f32_e32 v57, v57
	v_mul_f32_e32 v56, v25, v56
	v_rndne_f32_e32 v55, v55
	v_mul_f32_e32 v54, v25, v54
	v_cvt_i32_f32_e32 v30, v30
	v_rndne_f32_e32 v59, v59
	v_cvt_i32_f32_e32 v58, v58
	v_cvt_i32_f32_sdwa v57, v57 dst_sel:WORD_1 dst_unused:UNUSED_PAD src0_sel:DWORD
	v_rndne_f32_e32 v56, v56
	v_cvt_i32_f32_e32 v55, v55
	v_rndne_f32_e32 v54, v54
	v_cvt_i32_f32_e32 v59, v59
	v_cvt_i32_f32_sdwa v56, v56 dst_sel:WORD_1 dst_unused:UNUSED_PAD src0_sel:DWORD
	v_cvt_i32_f32_e32 v54, v54
	v_lshlrev_b32_e32 v31, 8, v31
	v_and_b32_e32 v31, 0xff00, v31
	v_lshlrev_b32_e32 v58, 8, v58
	v_and_b32_e32 v57, 0xff0000, v57
	v_perm_b32 v30, v55, v30, s8
	v_and_b32_e32 v58, 0xff00, v58
	v_and_b32_e32 v56, 0xff0000, v56
	v_or3_b32 v30, v30, v31, v57
	v_perm_b32 v31, v54, v59, s8
	v_or3_b32 v31, v31, v58, v56
	v_mov_b32_e32 v204, v30
	v_mov_b32_e32 v205, v31
	v_mul_f32_e32 v31, v25, v51
	v_mul_f32_e32 v50, v25, v50
	v_mul_f32_e32 v30, v25, v53
	v_rndne_f32_e32 v31, v31
	v_mul_f32_e32 v51, v25, v52
	v_rndne_f32_e32 v50, v50
	v_mul_f32_e32 v49, v25, v49
	v_mul_f32_e32 v48, v25, v48
	v_mul_f32_e32 v47, v25, v47
	v_mul_f32_e32 v25, v25, v46
	v_rndne_f32_e32 v30, v30
	v_cvt_i32_f32_e32 v31, v31
	v_rndne_f32_e32 v51, v51
	v_cvt_i32_f32_e32 v50, v50
	v_rndne_f32_e32 v49, v49
	v_rndne_f32_e32 v48, v48
	v_rndne_f32_e32 v47, v47
	v_rndne_f32_e32 v25, v25
	v_cvt_i32_f32_e32 v30, v30
	v_cvt_i32_f32_e32 v51, v51
	v_cvt_i32_f32_sdwa v49, v49 dst_sel:WORD_1 dst_unused:UNUSED_PAD src0_sel:DWORD
	v_cvt_i32_f32_sdwa v48, v48 dst_sel:WORD_1 dst_unused:UNUSED_PAD src0_sel:DWORD
	v_cvt_i32_f32_e32 v47, v47
	v_cvt_i32_f32_e32 v25, v25
	v_lshlrev_b32_e32 v31, 8, v31
	v_lshlrev_b32_e32 v50, 8, v50
	v_and_b32_e32 v31, 0xff00, v31
	v_and_b32_e32 v50, 0xff00, v50
	v_and_b32_e32 v49, 0xff0000, v49
	v_and_b32_e32 v46, 0xff0000, v48
	v_perm_b32 v30, v47, v30, s8
	v_perm_b32 v25, v25, v51, s8
	v_or3_b32 v30, v30, v31, v49
	v_or3_b32 v31, v25, v50, v46
	v_mov_b32_e32 v206, v30
	v_mov_b32_e32 v207, v31
	global_store_dwordx4 v[4:5], v[204:207], off offset:1024
	s_and_saveexec_b64 s[6:7], s[4:5]
	s_cbranch_execz .LBB0_306
	v_mov_b32_e32 v25, 0
	global_load_dwordx4 v[46:49], v25, s[2:3] offset:80
	s_waitcnt vmcnt(0)
	v_mov_b32_e32 v4, v47
	v_mov_b32_e32 v5, v48
	v_mov_b32_e32 v47, v49
	v_pk_add_f32 v[4:5], v[4:5], v[46:47]
	s_nop 0
	v_add_f32_e32 v4, v4, v5
	v_mov_b32_e32 v5, 0x358637bd
	v_fmac_f32_e32 v5, 0x3a800000, v4
	v_rsq_f32_e32 v4, v5
	v_mul_f32_e32 v5, 0x3c010204, v24
	v_mul_f32_e32 v4, v5, v4
	global_store_dword v25, v4, s[0:1] offset:20
.LBB0_306:
	s_or_b64 exec, exec, s[6:7]
	v_max_f32_e32 v4, v20, v20
	v_max_f32_e32 v5, v21, v21
	v_max_f32_e32 v4, v4, v5
	v_div_scale_f32 v5, s[6:7], v4, v4, s9
	v_rcp_f32_e32 v20, v5
	s_movk_i32 s6, 0x1000
	v_fma_f32 v21, -v5, v20, 1.0
	v_fmac_f32_e32 v20, v21, v20
	v_div_scale_f32 v21, vcc, s9, v4, s9
	v_mul_f32_e32 v24, v21, v20
	v_fma_f32 v25, -v5, v24, v21
	v_fmac_f32_e32 v24, v25, v20
	v_fma_f32 v5, -v5, v24, v21
	v_div_fmas_f32 v5, v5, v20, v24
	v_div_fixup_f32 v5, v5, v4, s9
	v_cmp_lt_f32_e32 vcc, 0, v4
	s_nop 1
	v_cndmask_b32_e32 v5, 0, v5, vcc
	v_mul_f32_e32 v21, v5, v43
	v_mul_f32_e32 v20, v5, v45
	v_rndne_f32_e32 v21, v21
	v_mul_f32_e32 v25, v5, v42
	v_mul_f32_e32 v30, v5, v40
	v_mul_f32_e32 v39, v5, v39
	v_rndne_f32_e32 v20, v20
	v_cvt_i32_f32_e32 v21, v21
	v_mul_f32_e32 v24, v5, v44
	v_rndne_f32_e32 v25, v25
	v_rndne_f32_e32 v30, v30
	v_mul_f32_e32 v31, v5, v41
	v_rndne_f32_e32 v39, v39
	v_mul_f32_e32 v38, v5, v38
	v_cvt_i32_f32_e32 v20, v20
	v_rndne_f32_e32 v24, v24
	v_cvt_i32_f32_e32 v25, v25
	v_cvt_i32_f32_sdwa v30, v30 dst_sel:WORD_1 dst_unused:UNUSED_PAD src0_sel:DWORD
	v_rndne_f32_e32 v31, v31
	v_cvt_i32_f32_e32 v39, v39
	v_rndne_f32_e32 v38, v38
	v_cvt_i32_f32_e32 v24, v24
	v_cvt_i32_f32_sdwa v31, v31 dst_sel:WORD_1 dst_unused:UNUSED_PAD src0_sel:DWORD
	v_cvt_i32_f32_e32 v38, v38
	v_lshlrev_b32_e32 v21, 8, v21
	v_and_b32_e32 v21, 0xff00, v21
	v_lshlrev_b32_e32 v25, 8, v25
	v_and_b32_e32 v30, 0xff0000, v30
	v_perm_b32 v20, v39, v20, s8
	v_and_b32_e32 v25, 0xff00, v25
	v_and_b32_e32 v31, 0xff0000, v31
	v_or3_b32 v20, v20, v21, v30
	v_perm_b32 v21, v38, v24, s8
	v_add_co_u32_e32 v2, vcc, s6, v2
	v_or3_b32 v21, v21, v25, v31
	s_nop 0
	v_addc_co_u32_e32 v3, vcc, 0, v3, vcc
	v_mov_b32_e32 v200, v20
	v_mov_b32_e32 v201, v21
	v_mul_f32_e32 v21, v5, v35
	v_mul_f32_e32 v25, v5, v34
	v_mul_f32_e32 v20, v5, v37
	v_rndne_f32_e32 v21, v21
	v_mul_f32_e32 v24, v5, v36
	v_rndne_f32_e32 v25, v25
	v_mul_f32_e32 v30, v5, v33
	v_mul_f32_e32 v31, v5, v32
	v_mul_f32_e32 v29, v5, v29
	v_mul_f32_e32 v5, v5, v28
	v_rndne_f32_e32 v20, v20
	v_cvt_i32_f32_e32 v21, v21
	v_rndne_f32_e32 v24, v24
	v_cvt_i32_f32_e32 v25, v25
	v_rndne_f32_e32 v30, v30
	v_rndne_f32_e32 v31, v31
	v_rndne_f32_e32 v29, v29
	v_rndne_f32_e32 v5, v5
	v_cvt_i32_f32_e32 v20, v20
	v_cvt_i32_f32_e32 v24, v24
	v_cvt_i32_f32_sdwa v30, v30 dst_sel:WORD_1 dst_unused:UNUSED_PAD src0_sel:DWORD
	v_cvt_i32_f32_sdwa v31, v31 dst_sel:WORD_1 dst_unused:UNUSED_PAD src0_sel:DWORD
	v_cvt_i32_f32_e32 v29, v29
	v_cvt_i32_f32_e32 v5, v5
	v_lshlrev_b32_e32 v21, 8, v21
	v_lshlrev_b32_e32 v25, 8, v25
	v_and_b32_e32 v21, 0xff00, v21
	v_and_b32_e32 v25, 0xff00, v25
	v_and_b32_e32 v30, 0xff0000, v30
	v_and_b32_e32 v28, 0xff0000, v31
	v_perm_b32 v20, v29, v20, s8
	v_perm_b32 v5, v5, v24, s8
	v_or3_b32 v20, v20, v21, v30
	v_or3_b32 v21, v5, v25, v28
	v_mov_b32_e32 v202, v20
	v_mov_b32_e32 v203, v21
	global_store_dwordx4 v[2:3], v[200:203], off offset:2048
	s_and_saveexec_b64 s[6:7], s[4:5]
	s_cbranch_execz .LBB0_308
	v_mov_b32_e32 v5, 0
	global_load_dwordx4 v[28:31], v5, s[2:3] offset:96
	v_mul_f32_e32 v4, 0x3c010204, v4
	s_waitcnt vmcnt(0)
	v_mov_b32_e32 v20, v29
	v_mov_b32_e32 v21, v30
	v_mov_b32_e32 v29, v31
	v_pk_add_f32 v[20:21], v[20:21], v[28:29]
	s_nop 0
	v_add_f32_e32 v20, v20, v21
	v_mov_b32_e32 v21, 0x358637bd
	v_fmac_f32_e32 v21, 0x3a800000, v20
	v_rsq_f32_e32 v20, v21
	s_nop 0
	v_mul_f32_e32 v4, v4, v20
	global_store_dword v5, v4, s[0:1] offset:24
.LBB0_308:
	s_or_b64 exec, exec, s[6:7]
	v_max_f32_e32 v4, v18, v18
	v_max_f32_e32 v5, v19, v19
	v_max_f32_e32 v4, v4, v5
	v_div_scale_f32 v5, s[6:7], v4, v4, s9
	v_rcp_f32_e32 v18, v5
	s_nop 0
	v_fma_f32 v19, -v5, v18, 1.0
	v_fmac_f32_e32 v18, v19, v18
	v_div_scale_f32 v19, vcc, s9, v4, s9
	v_mul_f32_e32 v20, v19, v18
	v_fma_f32 v21, -v5, v20, v19
	v_fmac_f32_e32 v20, v21, v18
	v_fma_f32 v5, -v5, v20, v19
	v_div_fmas_f32 v5, v5, v18, v20
	v_div_fixup_f32 v5, v5, v4, s9
	v_cmp_lt_f32_e32 vcc, 0, v4
	s_nop 1
	v_cndmask_b32_e32 v5, 0, v5, vcc
	v_mul_f32_e32 v19, v5, v26
	v_mul_f32_e32 v21, v5, v22
	v_mul_f32_e32 v11, v5, v11
	v_mul_f32_e32 v10, v5, v10
	v_mul_f32_e32 v18, v5, v27
	v_rndne_f32_e32 v19, v19
	v_mul_f32_e32 v20, v5, v23
	v_rndne_f32_e32 v21, v21
	v_mul_f32_e32 v17, v5, v17
	v_mul_f32_e32 v16, v5, v16
	v_mul_f32_e32 v15, v5, v15
	v_mul_f32_e32 v14, v5, v14
	v_mul_f32_e32 v13, v5, v13
	v_rndne_f32_e32 v11, v11
	v_mul_f32_e32 v12, v5, v12
	v_rndne_f32_e32 v10, v10
	v_mul_f32_e32 v9, v5, v9
	v_mul_f32_e32 v8, v5, v8
	v_mul_f32_e32 v7, v5, v7
	v_mul_f32_e32 v5, v5, v6
	v_rndne_f32_e32 v18, v18
	v_cvt_i32_f32_e32 v19, v19
	v_rndne_f32_e32 v20, v20
	v_cvt_i32_f32_e32 v21, v21
	v_rndne_f32_e32 v17, v17
	v_rndne_f32_e32 v16, v16
	v_rndne_f32_e32 v15, v15
	v_rndne_f32_e32 v14, v14
	v_rndne_f32_e32 v13, v13
	v_cvt_i32_f32_e32 v11, v11
	v_rndne_f32_e32 v12, v12
	v_cvt_i32_f32_e32 v10, v10
	v_rndne_f32_e32 v9, v9
	v_rndne_f32_e32 v8, v8
	v_rndne_f32_e32 v7, v7
	v_rndne_f32_e32 v5, v5
	v_cvt_i32_f32_e32 v18, v18
	v_cvt_i32_f32_e32 v20, v20
	v_cvt_i32_f32_sdwa v17, v17 dst_sel:WORD_1 dst_unused:UNUSED_PAD src0_sel:DWORD
	v_cvt_i32_f32_sdwa v16, v16 dst_sel:WORD_1 dst_unused:UNUSED_PAD src0_sel:DWORD
	v_cvt_i32_f32_e32 v15, v15
	v_cvt_i32_f32_e32 v22, v14
	v_cvt_i32_f32_e32 v13, v13
	v_cvt_i32_f32_e32 v12, v12
	v_cvt_i32_f32_sdwa v9, v9 dst_sel:WORD_1 dst_unused:UNUSED_PAD src0_sel:DWORD
	v_cvt_i32_f32_sdwa v8, v8 dst_sel:WORD_1 dst_unused:UNUSED_PAD src0_sel:DWORD
	v_cvt_i32_f32_e32 v7, v7
	v_cvt_i32_f32_e32 v5, v5
	v_lshlrev_b32_e32 v19, 8, v19
	v_lshlrev_b32_e32 v21, 8, v21
	v_lshlrev_b32_e32 v11, 8, v11
	v_lshlrev_b32_e32 v10, 8, v10
	v_and_b32_e32 v19, 0xff00, v19
	v_and_b32_e32 v21, 0xff00, v21
	v_and_b32_e32 v17, 0xff0000, v17
	v_and_b32_e32 v16, 0xff0000, v16
	v_perm_b32 v14, v15, v18, s8
	v_perm_b32 v15, v22, v20, s8
	v_and_b32_e32 v11, 0xff00, v11
	v_and_b32_e32 v10, 0xff00, v10
	v_and_b32_e32 v9, 0xff0000, v9
	v_and_b32_e32 v8, 0xff0000, v8
	v_perm_b32 v6, v7, v13, s8
	v_perm_b32 v5, v5, v12, s8
	v_or3_b32 v14, v14, v19, v17
	v_or3_b32 v15, v15, v21, v16
	v_or3_b32 v6, v6, v11, v9
	v_or3_b32 v7, v5, v10, v8
	v_mov_b32_e32 v204, v14
	v_mov_b32_e32 v205, v15
	v_mov_b32_e32 v206, v6
	v_mov_b32_e32 v207, v7
	global_store_dwordx4 v[2:3], v[204:207], off offset:3072
	s_and_saveexec_b64 s[6:7], s[4:5]
	s_cbranch_execz .LBB0_310
	v_mov_b32_e32 v5, 0
	global_load_dwordx4 v[6:9], v5, s[2:3] offset:112
	s_waitcnt vmcnt(0)
	v_mov_b32_e32 v2, v7
	v_mov_b32_e32 v3, v8
	v_mov_b32_e32 v7, v9
	v_pk_add_f32 v[2:3], v[2:3], v[6:7]
	s_nop 0
	v_add_f32_e32 v2, v2, v3
	v_mov_b32_e32 v3, 0x358637bd
	v_fmac_f32_e32 v3, 0x3a800000, v2
	v_rsq_f32_e32 v2, v3
	v_mul_f32_e32 v3, 0x3c010204, v4
	v_mul_f32_e32 v2, v3, v2
	global_store_dword v5, v2, s[0:1] offset:28

.LBB0_542:
	s_or_b64 exec, exec, s[0:1]
	s_mov_b64 s[0:1], s[82:83]
	v_mov_b32_e32 v2, v0
	s_mov_b32 s5, s72
	s_mov_b32 s2, s73
	s_barrier
	s_load_dwordx2 s[2:3], s[0:1], 0x90
	v_readfirstlane_b32 s4, v2
	s_lshl_b32 s0, s5, 3
	s_and_b32 s0, s0, 56
	s_bfe_u32 s1, s5, 0x30003
	s_ashr_i32 s4, s4, 3
	s_or_b32 s8, s0, s1
	s_and_b32 s1, s5, 0xffffffc0
	s_and_b32 s4, s4, -8
	s_lshl_b32 s0, s8, 8
	s_add_i32 s4, s1, s4
	s_add_i32 s6, s4, s0
	s_ashr_i32 s7, s6, 31
	s_lshl_b64 s[0:1], s[6:7], 11
	v_and_b32_e32 v126, 63, v2
	s_waitcnt lgkmcnt(0)
	s_add_u32 s0, s2, s0
	s_addc_u32 s1, s3, s1
	v_lshlrev_b32_e32 v30, 5, v126
	v_mov_b32_e32 v31, 0
	v_lshl_add_u64 v[2:3], s[0:1], 0, v[30:31]
	s_mov_b32 s0, 0x3001000
	v_add_co_u32_e32 v60, vcc, s0, v2
	s_mov_b64 s[0:1], 0x3000000
	s_nop 0
	v_addc_co_u32_e32 v61, vcc, 0, v3, vcc
	global_load_dwordx4 v[18:21], v[60:61], off offset:-4096
	v_lshl_add_u64 v[4:5], v[2:3], 0, s[0:1]
	global_load_dwordx4 v[22:25], v[4:5], off offset:16
	global_load_dwordx4 v[32:35], v[4:5], off offset:2048
	global_load_dwordx4 v[36:39], v[4:5], off offset:2064
	s_mov_b32 s0, 0x3002000
	v_add_co_u32_e32 v62, vcc, s0, v2
	s_mov_b32 s1, 0x3003000
	s_nop 0
	v_addc_co_u32_e32 v63, vcc, 0, v3, vcc
	v_add_co_u32_e32 v64, vcc, s1, v2
	s_mul_i32 s8, s8, 0x160000
	s_nop 0
	v_addc_co_u32_e32 v65, vcc, 0, v3, vcc
	global_load_dwordx4 v[40:43], v[60:61], off
	global_load_dwordx4 v[44:47], v[60:61], off offset:16
	global_load_dwordx4 v[48:51], v[60:61], off offset:2048
	global_load_dwordx4 v[52:55], v[60:61], off offset:2064
	global_load_dwordx4 v[56:59], v[64:65], off offset:-4096
	global_load_dwordx4 v[26:29], v[62:63], off offset:16
	global_load_dwordx4 v[14:17], v[62:63], off offset:2048
	global_load_dwordx4 v[10:13], v[62:63], off offset:2064
	global_load_dwordx4 v[6:9], v[64:65], off
	global_load_dwordx4 v[2:5], v[64:65], off offset:16
	s_add_u32 s5, s2, s8
	s_addc_u32 s8, s3, 0
	s_lshl_b32 s4, s4, 10
	s_and_b32 s0, s4, 0x3e000
	s_add_u32 s4, s5, s0
	s_addc_u32 s5, s8, 0
	s_mov_b32 s9, 0x42fe0000
	s_lshl_b64 s[0:1], s[6:7], 2
	s_add_u32 s0, s2, s0
	s_addc_u32 s1, s3, s1
	s_add_u32 s0, s0, 0xfc00000
	s_addc_u32 s1, s1, 0
	s_lshl_b64 s[6:7], s[6:7], 4
	s_mov_b32 s8, 0x40c0c00
	s_add_u32 s2, s2, s6
	s_mov_b32 s6, 0x5000000
	s_addc_u32 s3, s3, s7
	s_add_u32 s2, s2, 0xda00000
	s_addc_u32 s3, s3, 0
	s_waitcnt vmcnt(12)
	v_lshlrev_b32_e32 v148, 16, v22
	v_lshlrev_b32_e32 v140, 16, v18
	v_and_b32_e32 v141, 0xffff0000, v18
	v_lshlrev_b32_e32 v142, 16, v19
	v_and_b32_e32 v143, 0xffff0000, v19
	v_max3_f32 v18, |v140|, 0, |v141|
	v_lshlrev_b32_e32 v144, 16, v20
	v_and_b32_e32 v145, 0xffff0000, v20
	v_max3_f32 v18, v18, |v142|, |v143|
	v_lshlrev_b32_e32 v146, 16, v21
	v_and_b32_e32 v147, 0xffff0000, v21
	v_max3_f32 v18, v18, |v144|, |v145|
	v_and_b32_e32 v149, 0xffff0000, v22
	v_max3_f32 v18, v18, |v146|, |v147|
	v_lshlrev_b32_e32 v134, 16, v23
	v_and_b32_e32 v132, 0xffff0000, v23
	v_max3_f32 v18, v18, |v148|, |v149|
	v_lshlrev_b32_e32 v150, 16, v24
	v_and_b32_e32 v151, 0xffff0000, v24
	v_max3_f32 v18, v18, |v134|, |v132|
	v_lshlrev_b32_e32 v133, 16, v25
	v_and_b32_e32 v131, 0xffff0000, v25
	v_max3_f32 v18, v18, |v150|, |v151|
	v_max3_f32 v18, v18, |v133|, |v131|
	ds_swizzle_b32 v19, v18 offset:swizzle(SWAP,1)
	s_waitcnt vmcnt(11)
	v_lshlrev_b32_e32 v130, 16, v32
	v_and_b32_e32 v128, 0xffff0000, v32
	v_lshlrev_b32_e32 v122, 16, v33
	v_and_b32_e32 v119, 0xffff0000, v33
	s_waitcnt lgkmcnt(0)
	v_max_f32_e32 v19, v19, v19
	v_max_f32_e32 v18, v18, v19
	ds_swizzle_b32 v19, v18 offset:swizzle(SWAP,2)
	v_max3_f32 v20, |v130|, 0, |v128|
	v_lshlrev_b32_e32 v129, 16, v34
	v_and_b32_e32 v127, 0xffff0000, v34
	v_max3_f32 v20, v20, |v122|, |v119|
	s_waitcnt lgkmcnt(0)
	v_max_f32_e32 v19, v19, v19
	v_max_f32_e32 v18, v18, v19
	ds_swizzle_b32 v19, v18 offset:swizzle(SWAP,4)
	v_lshlrev_b32_e32 v123, 16, v35
	v_and_b32_e32 v121, 0xffff0000, v35
	v_max3_f32 v20, v20, |v129|, |v127|
	s_waitcnt vmcnt(10)
	v_lshlrev_b32_e32 v117, 16, v36
	s_waitcnt lgkmcnt(0)
	v_max_f32_e32 v19, v19, v19
	v_max_f32_e32 v18, v18, v19
	ds_swizzle_b32 v19, v18 offset:swizzle(SWAP,8)
	v_and_b32_e32 v116, 0xffff0000, v36
	v_max3_f32 v20, v20, |v123|, |v121|
	v_lshlrev_b32_e32 v113, 16, v37
	v_and_b32_e32 v114, 0xffff0000, v37
	s_waitcnt lgkmcnt(0)
	v_max_f32_e32 v19, v19, v19
	v_max_f32_e32 v30, v18, v19
	v_max3_f32 v18, v20, |v117|, |v116|
	v_lshlrev_b32_e32 v120, 16, v38
	v_and_b32_e32 v118, 0xffff0000, v38
	v_max3_f32 v18, v18, |v113|, |v114|
	v_lshlrev_b32_e32 v115, 16, v39
	v_and_b32_e32 v112, 0xffff0000, v39
	v_max3_f32 v18, v18, |v120|, |v118|
	ds_swizzle_b32 v32, v30 offset:swizzle(SWAP,16)
	v_max3_f32 v33, v18, |v115|, |v112|
	ds_swizzle_b32 v34, v33 offset:swizzle(SWAP,1)
	s_waitcnt vmcnt(9)
	v_lshlrev_b32_e32 v111, 16, v40
	v_and_b32_e32 v109, 0xffff0000, v40
	s_waitcnt lgkmcnt(1)
	v_max_f32_e32 v32, v32, v32
	v_max_f32_e32 v30, v30, v32
	s_waitcnt lgkmcnt(0)
	v_max_f32_e32 v32, v34, v34
	v_max_f32_e32 v32, v33, v32
	v_lshlrev_b32_e32 v106, 16, v41
	v_and_b32_e32 v105, 0xffff0000, v41
	v_max3_f32 v35, |v111|, 0, |v109|
	global_load_dwordx4 v[22:25], v[64:65], off offset:2048
	global_load_dwordx4 v[18:21], v[64:65], off offset:2064
	ds_swizzle_b32 v33, v32 offset:swizzle(SWAP,2)
	v_lshlrev_b32_e32 v110, 16, v42
	v_and_b32_e32 v108, 0xffff0000, v42
	v_max3_f32 v35, v35, |v106|, |v105|
	v_lshlrev_b32_e32 v107, 16, v43
	v_and_b32_e32 v104, 0xffff0000, v43
	v_max3_f32 v35, v35, |v110|, |v108|
	v_max3_f32 v35, v35, |v107|, |v104|
	s_waitcnt vmcnt(10)
	v_lshlrev_b32_e32 v103, 16, v44
	v_and_b32_e32 v101, 0xffff0000, v44
	v_lshlrev_b32_e32 v99, 16, v45
	v_and_b32_e32 v95, 0xffff0000, v45
	v_max3_f32 v35, v35, |v103|, |v101|
	v_lshlrev_b32_e32 v102, 16, v46
	v_and_b32_e32 v100, 0xffff0000, v46
	v_max3_f32 v35, v35, |v99|, |v95|
	s_waitcnt lgkmcnt(0)
	v_max_f32_e32 v33, v33, v33
	v_lshlrev_b32_e32 v98, 16, v47
	v_and_b32_e32 v94, 0xffff0000, v47
	v_max3_f32 v35, v35, |v102|, |v100|
	v_max_f32_e32 v32, v32, v33
	v_max3_f32 v35, v35, |v98|, |v94|
	ds_swizzle_b32 v33, v32 offset:swizzle(SWAP,4)
	ds_swizzle_b32 v36, v35 offset:swizzle(SWAP,1)
	v_mov_b32_e32 v34, v30
	s_nop 1
	v_permlane32_swap_b32_e32 v30, v34
	s_waitcnt lgkmcnt(1)
	v_max_f32_e32 v33, v33, v33
	s_waitcnt lgkmcnt(0)
	v_max_f32_e32 v36, v36, v36
	v_max_f32_e32 v32, v32, v33
	v_max_f32_e32 v35, v35, v36
	ds_swizzle_b32 v33, v32 offset:swizzle(SWAP,8)
	ds_swizzle_b32 v36, v35 offset:swizzle(SWAP,2)
	v_max_f32_e32 v34, v34, v34
	v_max_f32_e32 v30, v30, v30
	v_max_f32_e32 v137, v30, v34
	s_waitcnt lgkmcnt(1)
	v_max_f32_e32 v30, v33, v33
	s_waitcnt lgkmcnt(0)
	v_max_f32_e32 v33, v36, v36
	s_waitcnt vmcnt(9)
	v_lshlrev_b32_e32 v93, 16, v48
	v_and_b32_e32 v91, 0xffff0000, v48
	v_max_f32_e32 v33, v35, v33
	v_lshlrev_b32_e32 v89, 16, v49
	v_and_b32_e32 v87, 0xffff0000, v49
	v_max3_f32 v35, |v93|, 0, |v91|
	v_lshlrev_b32_e32 v92, 16, v50
	v_and_b32_e32 v90, 0xffff0000, v50
	v_max3_f32 v35, v35, |v89|, |v87|
	v_lshlrev_b32_e32 v88, 16, v51
	v_and_b32_e32 v86, 0xffff0000, v51
	v_max3_f32 v35, v35, |v92|, |v90|
	v_max3_f32 v35, v35, |v88|, |v86|
	s_waitcnt vmcnt(8)
	v_lshlrev_b32_e32 v85, 16, v52
	v_and_b32_e32 v83, 0xffff0000, v52
	v_lshlrev_b32_e32 v81, 16, v53
	v_and_b32_e32 v79, 0xffff0000, v53
	v_max3_f32 v35, v35, |v85|, |v83|
	v_lshlrev_b32_e32 v84, 16, v54
	v_and_b32_e32 v82, 0xffff0000, v54
	v_max3_f32 v35, v35, |v81|, |v79|
	v_lshlrev_b32_e32 v80, 16, v55
	v_and_b32_e32 v78, 0xffff0000, v55
	v_max3_f32 v35, v35, |v84|, |v82|
	ds_swizzle_b32 v34, v33 offset:swizzle(SWAP,4)
	v_max3_f32 v35, v35, |v80|, |v78|
	ds_swizzle_b32 v36, v35 offset:swizzle(SWAP,1)
	v_max_f32_e32 v30, v32, v30
	ds_swizzle_b32 v32, v30 offset:swizzle(SWAP,16)
	s_waitcnt lgkmcnt(2)
	v_max_f32_e32 v34, v34, v34
	v_max_f32_e32 v33, v33, v34
	s_waitcnt lgkmcnt(1)
	v_max_f32_e32 v36, v36, v36
	ds_swizzle_b32 v34, v33 offset:swizzle(SWAP,8)
	v_max_f32_e32 v35, v35, v36
	ds_swizzle_b32 v36, v35 offset:swizzle(SWAP,2)
	s_waitcnt lgkmcnt(2)
	v_max_f32_e32 v32, v32, v32
	v_max_f32_e32 v138, v30, v32
	s_waitcnt lgkmcnt(1)
	v_max_f32_e32 v30, v34, v34
	v_max_f32_e32 v30, v33, v30
	s_waitcnt lgkmcnt(0)
	v_max_f32_e32 v33, v36, v36
	s_waitcnt vmcnt(7)
	v_lshlrev_b32_e32 v77, 16, v56
	v_and_b32_e32 v75, 0xffff0000, v56
	v_max_f32_e32 v33, v35, v33
	v_lshlrev_b32_e32 v72, 16, v57
	v_and_b32_e32 v71, 0xffff0000, v57
	v_max3_f32 v35, |v77|, 0, |v75|
	v_lshlrev_b32_e32 v76, 16, v58
	v_and_b32_e32 v74, 0xffff0000, v58
	v_max3_f32 v35, v35, |v72|, |v71|
	v_lshlrev_b32_e32 v73, 16, v59
	v_and_b32_e32 v70, 0xffff0000, v59
	v_max3_f32 v35, v35, |v76|, |v74|
	v_max3_f32 v35, v35, |v73|, |v70|
	s_waitcnt vmcnt(6)
	v_lshlrev_b32_e32 v69, 16, v26
	v_and_b32_e32 v67, 0xffff0000, v26
	v_lshlrev_b32_e32 v65, 16, v27
	v_and_b32_e32 v63, 0xffff0000, v27
	v_max3_f32 v26, v35, |v69|, |v67|
	v_lshlrev_b32_e32 v68, 16, v28
	v_and_b32_e32 v66, 0xffff0000, v28
	v_max3_f32 v26, v26, |v65|, |v63|
	v_lshlrev_b32_e32 v64, 16, v29
	v_and_b32_e32 v62, 0xffff0000, v29
	v_max3_f32 v26, v26, |v68|, |v66|
	v_max3_f32 v26, v26, |v64|, |v62|
	s_waitcnt vmcnt(5)
	v_lshlrev_b32_e32 v61, 16, v14
	v_and_b32_e32 v59, 0xffff0000, v14
	ds_swizzle_b32 v27, v26 offset:swizzle(SWAP,1)
	v_lshlrev_b32_e32 v57, 16, v15
	v_and_b32_e32 v55, 0xffff0000, v15
	v_max3_f32 v14, |v61|, 0, |v59|
	v_lshlrev_b32_e32 v60, 16, v16
	v_and_b32_e32 v58, 0xffff0000, v16
	v_max3_f32 v14, v14, |v57|, |v55|
	v_lshlrev_b32_e32 v56, 16, v17
	v_and_b32_e32 v54, 0xffff0000, v17
	v_max3_f32 v14, v14, |v60|, |v58|
	v_max3_f32 v14, v14, |v56|, |v54|
	s_waitcnt vmcnt(4)
	v_lshlrev_b32_e32 v53, 16, v10
	v_and_b32_e32 v51, 0xffff0000, v10
	v_lshlrev_b32_e32 v49, 16, v11
	v_and_b32_e32 v47, 0xffff0000, v11
	v_max3_f32 v10, v14, |v53|, |v51|
	s_waitcnt lgkmcnt(0)
	v_max_f32_e32 v27, v27, v27
	v_lshlrev_b32_e32 v52, 16, v12
	v_and_b32_e32 v50, 0xffff0000, v12
	v_max3_f32 v10, v10, |v49|, |v47|
	v_max_f32_e32 v26, v26, v27
	v_lshlrev_b32_e32 v48, 16, v13
	v_and_b32_e32 v46, 0xffff0000, v13
	v_max3_f32 v10, v10, |v52|, |v50|
	ds_swizzle_b32 v27, v26 offset:swizzle(SWAP,2)
	v_max3_f32 v10, v10, |v48|, |v46|
	ds_swizzle_b32 v11, v10 offset:swizzle(SWAP,1)
	ds_swizzle_b32 v34, v33 offset:swizzle(SWAP,4)
	ds_swizzle_b32 v32, v30 offset:swizzle(SWAP,16)
	s_waitcnt lgkmcnt(3)
	v_max_f32_e32 v27, v27, v27
	v_max_f32_e32 v26, v26, v27
	s_waitcnt lgkmcnt(2)
	v_max_f32_e32 v11, v11, v11
	ds_swizzle_b32 v27, v26 offset:swizzle(SWAP,4)
	v_max_f32_e32 v10, v10, v11
	ds_swizzle_b32 v11, v10 offset:swizzle(SWAP,2)
	s_waitcnt lgkmcnt(3)
	v_max_f32_e32 v34, v34, v34
	v_max_f32_e32 v33, v33, v34
	ds_swizzle_b32 v34, v33 offset:swizzle(SWAP,8)
	s_waitcnt lgkmcnt(2)
	v_max_f32_e32 v12, v27, v27
	v_max_f32_e32 v12, v26, v12
	s_waitcnt lgkmcnt(1)
	v_max_f32_e32 v11, v11, v11
	ds_swizzle_b32 v13, v12 offset:swizzle(SWAP,8)
	v_max_f32_e32 v10, v10, v11
	ds_swizzle_b32 v11, v10 offset:swizzle(SWAP,4)
	s_waitcnt lgkmcnt(2)
	v_max_f32_e32 v28, v34, v34
	v_max_f32_e32 v28, v33, v28
	ds_swizzle_b32 v29, v28 offset:swizzle(SWAP,16)
	s_waitcnt lgkmcnt(2)
	v_max_f32_e32 v13, v13, v13
	v_max_f32_e32 v12, v12, v13
	s_waitcnt lgkmcnt(1)
	v_max_f32_e32 v11, v11, v11
	ds_swizzle_b32 v13, v12 offset:swizzle(SWAP,16)
	v_max_f32_e32 v10, v10, v11
	ds_swizzle_b32 v11, v10 offset:swizzle(SWAP,8)
	s_waitcnt vmcnt(3)
	v_lshlrev_b32_e32 v45, 16, v6
	v_and_b32_e32 v43, 0xffff0000, v6
	v_max_f32_e32 v32, v32, v32
	s_waitcnt lgkmcnt(2)
	v_max_f32_e32 v29, v29, v29
	v_lshlrev_b32_e32 v40, 16, v7
	v_and_b32_e32 v39, 0xffff0000, v7
	v_max3_f32 v6, |v45|, 0, |v43|
	s_waitcnt vmcnt(1)
	v_lshlrev_b32_e32 v27, 16, v22
	v_and_b32_e32 v26, 0xffff0000, v22
	v_max_f32_e32 v135, v30, v32
	v_max_f32_e32 v124, v28, v29
	v_lshlrev_b32_e32 v44, 16, v8
	v_and_b32_e32 v42, 0xffff0000, v8
	v_max3_f32 v6, v6, |v40|, |v39|
	v_lshlrev_b32_e32 v32, 16, v5
	v_and_b32_e32 v28, 0xffff0000, v5
	v_lshlrev_b32_e32 v17, 16, v23
	v_and_b32_e32 v15, 0xffff0000, v23
	v_max3_f32 v5, |v27|, 0, |v26|
	v_lshlrev_b32_e32 v41, 16, v9
	v_and_b32_e32 v38, 0xffff0000, v9
	v_max3_f32 v6, v6, |v44|, |v42|
	v_lshlrev_b32_e32 v23, 16, v24
	v_and_b32_e32 v22, 0xffff0000, v24
	v_max3_f32 v5, v5, |v17|, |v15|
	s_waitcnt lgkmcnt(1)
	v_max_f32_e32 v13, v13, v13
	v_max3_f32 v6, v6, |v41|, |v38|
	v_lshlrev_b32_e32 v37, 16, v2
	v_and_b32_e32 v35, 0xffff0000, v2
	v_lshlrev_b32_e32 v16, 16, v25
	v_and_b32_e32 v14, 0xffff0000, v25
	v_max3_f32 v5, v5, |v23|, |v22|
	v_max_f32_e32 v96, v12, v13
	v_lshlrev_b32_e32 v33, 16, v3
	v_and_b32_e32 v29, 0xffff0000, v3
	v_lshlrev_b32_e32 v36, 16, v4
	v_and_b32_e32 v34, 0xffff0000, v4
	v_max3_f32 v2, v6, |v37|, |v35|
	s_waitcnt lgkmcnt(0)
	v_max_f32_e32 v4, v11, v11
	v_max3_f32 v5, v5, |v16|, |v14|
	s_waitcnt vmcnt(0)
	v_lshlrev_b32_e32 v13, 16, v18
	v_and_b32_e32 v11, 0xffff0000, v18
	v_max3_f32 v2, v2, |v33|, |v29|
	v_lshlrev_b32_e32 v9, 16, v19
	v_and_b32_e32 v7, 0xffff0000, v19
	v_max3_f32 v5, v5, |v13|, |v11|
	v_max3_f32 v2, v2, |v36|, |v34|
	v_max_f32_e32 v4, v10, v4
	v_lshlrev_b32_e32 v12, 16, v20
	v_and_b32_e32 v10, 0xffff0000, v20
	v_max3_f32 v5, v5, |v9|, |v7|
	v_max3_f32 v2, v2, |v32|, |v28|
	v_lshlrev_b32_e32 v8, 16, v21
	v_and_b32_e32 v6, 0xffff0000, v21
	v_max3_f32 v5, v5, |v12|, |v10|
	ds_swizzle_b32 v3, v2 offset:swizzle(SWAP,1)
	v_max3_f32 v5, v5, |v8|, |v6|
	ds_swizzle_b32 v18, v5 offset:swizzle(SWAP,1)
	ds_swizzle_b32 v19, v4 offset:swizzle(SWAP,16)
	v_lshlrev_b32_e32 v30, 4, v126
	s_waitcnt lgkmcnt(2)
	v_max_f32_e32 v3, v3, v3
	v_max_f32_e32 v2, v2, v3
	s_waitcnt lgkmcnt(1)
	v_max_f32_e32 v18, v18, v18
	ds_swizzle_b32 v3, v2 offset:swizzle(SWAP,2)
	v_max_f32_e32 v5, v5, v18
	ds_swizzle_b32 v18, v5 offset:swizzle(SWAP,2)
	s_waitcnt lgkmcnt(2)
	v_max_f32_e32 v19, v19, v19
	v_max_f32_e32 v24, v4, v19
	s_waitcnt lgkmcnt(1)
	v_max_f32_e32 v3, v3, v3
	v_max_f32_e32 v2, v2, v3
	s_waitcnt lgkmcnt(0)
	v_max_f32_e32 v18, v18, v18
	ds_swizzle_b32 v3, v2 offset:swizzle(SWAP,4)
	v_max_f32_e32 v5, v5, v18
	ds_swizzle_b32 v18, v5 offset:swizzle(SWAP,4)
	v_mov_b32_e32 v139, v138
	v_mov_b32_e32 v136, v135
	s_waitcnt lgkmcnt(1)
	v_max_f32_e32 v3, v3, v3
	v_max_f32_e32 v2, v2, v3
	s_waitcnt lgkmcnt(0)
	v_max_f32_e32 v4, v18, v18
	ds_swizzle_b32 v3, v2 offset:swizzle(SWAP,8)
	v_max_f32_e32 v4, v5, v4
	ds_swizzle_b32 v5, v4 offset:swizzle(SWAP,8)
	v_mov_b32_e32 v125, v124
	v_mov_b32_e32 v97, v96
	s_waitcnt lgkmcnt(1)
	v_max_f32_e32 v3, v3, v3
	v_max_f32_e32 v2, v2, v3
	s_waitcnt lgkmcnt(0)
	v_max_f32_e32 v5, v5, v5
	ds_swizzle_b32 v3, v2 offset:swizzle(SWAP,16)
	v_max_f32_e32 v4, v4, v5
	ds_swizzle_b32 v5, v4 offset:swizzle(SWAP,16)
	v_mov_b32_e32 v25, v24
	v_permlane32_swap_b32_e32 v138, v139
	s_waitcnt lgkmcnt(1)
	v_max_f32_e32 v3, v3, v3
	v_max_f32_e32 v20, v2, v3
	s_waitcnt lgkmcnt(0)
	v_max_f32_e32 v2, v5, v5
	v_max_f32_e32 v18, v4, v2
	v_lshl_add_u64 v[4:5], s[4:5], 0, v[30:31]
	v_div_scale_f32 v30, s[4:5], v137, v137, s9
	v_rcp_f32_e32 v152, v30
	s_mov_b64 s[4:5], 0x5000000
	v_lshl_add_u64 v[2:3], v[4:5], 0, s[4:5]
	v_cmp_eq_u32_e64 s[4:5], 0, v126
	v_fma_f32 v126, -v30, v152, 1.0
	v_fmac_f32_e32 v152, v126, v152
	v_div_scale_f32 v126, vcc, s9, v137, s9
	v_mul_f32_e32 v153, v126, v152
	v_fma_f32 v154, -v30, v153, v126
	v_fmac_f32_e32 v153, v154, v152
	v_fma_f32 v30, -v30, v153, v126
	v_div_fmas_f32 v30, v30, v152, v153
	v_div_fixup_f32 v30, v30, v137, s9
	v_cmp_lt_f32_e32 vcc, 0, v137
	v_mov_b32_e32 v21, v20
	v_mov_b32_e32 v19, v18
	v_cndmask_b32_e32 v30, 0, v30, vcc
	v_mul_f32_e32 v126, v30, v140
	v_mul_f32_e32 v140, v30, v141
	v_rndne_f32_e32 v140, v140
	v_mul_f32_e32 v141, v30, v144
	v_mul_f32_e32 v144, v30, v145
	v_mul_f32_e32 v142, v30, v142
	v_mul_f32_e32 v143, v30, v143
	v_rndne_f32_e32 v126, v126
	v_cvt_i32_f32_e32 v140, v140
	v_rndne_f32_e32 v144, v144
	v_rndne_f32_e32 v142, v142
	v_mul_f32_e32 v145, v30, v146
	v_rndne_f32_e32 v143, v143
	v_mul_f32_e32 v146, v30, v147
	v_cvt_i32_f32_e32 v126, v126
	v_rndne_f32_e32 v141, v141
	v_cvt_i32_f32_e32 v144, v144
	v_cvt_i32_f32_sdwa v142, v142 dst_sel:WORD_1 dst_unused:UNUSED_PAD src0_sel:DWORD
	v_rndne_f32_e32 v145, v145
	v_cvt_i32_f32_e32 v143, v143
	v_rndne_f32_e32 v146, v146
	v_cvt_i32_f32_e32 v141, v141
	v_cvt_i32_f32_sdwa v145, v145 dst_sel:WORD_1 dst_unused:UNUSED_PAD src0_sel:DWORD
	v_cvt_i32_f32_e32 v146, v146
	v_lshlrev_b32_e32 v140, 8, v140
	v_and_b32_e32 v140, 0xff00, v140
	v_lshlrev_b32_e32 v144, 8, v144
	v_and_b32_e32 v142, 0xff0000, v142
	v_perm_b32 v126, v143, v126, s8
	v_and_b32_e32 v144, 0xff00, v144
	v_and_b32_e32 v145, 0xff0000, v145
	v_or3_b32 v140, v126, v140, v142
	v_perm_b32 v126, v146, v141, s8
	v_add_co_u32_e32 v4, vcc, s6, v4
	v_or3_b32 v141, v126, v144, v145
	s_nop 0
	v_addc_co_u32_e32 v5, vcc, 0, v5, vcc
	v_mov_b32_e32 v200, v140
	v_mov_b32_e32 v201, v141
	v_mul_f32_e32 v5, v30, v149
	v_mul_f32_e32 v4, v30, v148
	v_rndne_f32_e32 v5, v5
	v_mul_f32_e32 v140, v30, v151
	v_mul_f32_e32 v134, v30, v134
	v_mul_f32_e32 v132, v30, v132
	v_rndne_f32_e32 v4, v4
	v_cvt_i32_f32_e32 v5, v5
	v_mul_f32_e32 v126, v30, v150
	v_rndne_f32_e32 v140, v140
	v_rndne_f32_e32 v134, v134
	v_mul_f32_e32 v133, v30, v133
	v_rndne_f32_e32 v132, v132
	v_mul_f32_e32 v30, v30, v131
	v_cvt_i32_f32_e32 v4, v4
	v_rndne_f32_e32 v126, v126
	v_cvt_i32_f32_e32 v140, v140
	v_cvt_i32_f32_sdwa v134, v134 dst_sel:WORD_1 dst_unused:UNUSED_PAD src0_sel:DWORD
	v_rndne_f32_e32 v133, v133
	v_cvt_i32_f32_e32 v132, v132
	v_rndne_f32_e32 v30, v30
	v_cvt_i32_f32_e32 v126, v126
	v_cvt_i32_f32_sdwa v133, v133 dst_sel:WORD_1 dst_unused:UNUSED_PAD src0_sel:DWORD
	v_cvt_i32_f32_e32 v30, v30
	v_lshlrev_b32_e32 v5, 8, v5
	v_and_b32_e32 v5, 0xff00, v5
	v_lshlrev_b32_e32 v140, 8, v140
	v_and_b32_e32 v134, 0xff0000, v134
	v_perm_b32 v4, v132, v4, s8
	v_and_b32_e32 v140, 0xff00, v140
	v_and_b32_e32 v131, 0xff0000, v133
	v_or3_b32 v4, v4, v5, v134
	v_perm_b32 v5, v30, v126, s8
	v_permlane32_swap_b32_e32 v135, v136
	v_permlane32_swap_b32_e32 v124, v125
	v_permlane32_swap_b32_e32 v96, v97
	v_permlane32_swap_b32_e32 v24, v25
	v_permlane32_swap_b32_e32 v20, v21
	v_permlane32_swap_b32_e32 v18, v19
	v_or3_b32 v5, v5, v140, v131
	v_mov_b32_e32 v202, v4
	v_mov_b32_e32 v203, v5
	global_store_dwordx4 v[2:3], v[200:203], off
	s_and_saveexec_b64 s[6:7], s[4:5]
	s_cbranch_execz .LBB0_544
	global_load_dwordx4 v[140:143], v31, s[2:3]
	s_waitcnt vmcnt(0)
	v_mov_b32_e32 v4, v141
	v_mov_b32_e32 v5, v142
	v_mov_b32_e32 v141, v143
	v_pk_add_f32 v[4:5], v[4:5], v[140:141]
	s_nop 0
	v_add_f32_e32 v4, v4, v5
	v_mov_b32_e32 v5, 0x358637bd
	v_fmac_f32_e32 v5, 0x3a800000, v4
	v_rsq_f32_e32 v4, v5
	v_mul_f32_e32 v5, 0x3c010204, v137
	v_mul_f32_e32 v4, v5, v4
	global_store_dword v31, v4, s[0:1]

.LBB0_864:
	s_or_b64 exec, exec, s[0:1]
	v_cvt_pk_bf16_f32 v20, v2, v3
	v_cvt_pk_bf16_f32 v21, v4, v5
	v_cvt_pk_bf16_f32 v22, v6, v7
	v_cvt_pk_bf16_f32 v23, v8, v9
	ds_read_b64_tr_b16 v[2:3], v164 offset:24576
	ds_read_b64_tr_b16 v[4:5], v164 offset:25088
	ds_read_b64_tr_b16 v[104:105], v164 offset:25600
	ds_read_b64_tr_b16 v[106:107], v164 offset:26112
	s_waitcnt lgkmcnt(2)
	v_mfma_f32_32x32x16_bf16 v[2:17], v[20:23], v[2:5], 0
	ds_read_b64_tr_b16 v[24:25], v164 offset:36864
	ds_read_b64_tr_b16 v[26:27], v164 offset:37376
	v_cvt_pk_bf16_f32 v108, v18, v19
	v_cvt_pk_bf16_f32 v109, v40, v41
	v_cvt_pk_bf16_f32 v110, v50, v51
	v_cvt_pk_bf16_f32 v111, v66, v67
	ds_read_b64_tr_b16 v[112:113], v164 offset:37888
	ds_read_b64_tr_b16 v[114:115], v164 offset:38400
	v_cvt_pk_bf16_f32 v66, v74, v75
	s_waitcnt lgkmcnt(2)
	v_mfma_f32_32x32x16_bf16 v[18:33], v[20:23], v[24:27], 0
	v_cvt_pk_bf16_f32 v67, v82, v83
	v_cvt_pk_bf16_f32 v46, v46, v47
	v_cvt_pk_bf16_f32 v47, v60, v61
	v_cvt_pk_bf16_f32 v40, v52, v53
	v_cvt_pk_bf16_f32 v41, v34, v35
	v_cvt_pk_bf16_f32 v42, v42, v43
	v_cvt_pk_bf16_f32 v43, v54, v55
	v_mfma_f32_32x32x16_bf16 v[2:17], v[108:111], v[104:107], v[2:17]
	v_cvt_pk_bf16_f32 v104, v80, v81
	v_cvt_pk_bf16_f32 v105, v88, v89
	v_cvt_pk_bf16_f32 v106, v98, v99
	v_cvt_pk_bf16_f32 v107, v102, v103
	v_cvt_pk_bf16_f32 v102, v70, v71
	v_cvt_pk_bf16_f32 v103, v44, v45
	v_cvt_pk_bf16_f32 v44, v58, v59
	s_waitcnt lgkmcnt(0)
	v_mfma_f32_32x32x16_bf16 v[18:33], v[108:111], v[112:115], v[18:33]
	ds_read_b64_tr_b16 v[108:109], v164 offset:26624
	ds_read_b64_tr_b16 v[110:111], v164 offset:27136
	ds_read_b64_tr_b16 v[112:113], v164 offset:27648
	ds_read_b64_tr_b16 v[114:115], v164 offset:28160
	v_cvt_pk_bf16_f32 v45, v36, v37
	v_cvt_pk_bf16_f32 v36, v64, v65
	v_cvt_pk_bf16_f32 v37, v38, v39
	v_cvt_pk_bf16_f32 v38, v48, v49
	v_cvt_pk_bf16_f32 v39, v62, v63
	s_movk_i32 s0, 0x7fff
	s_waitcnt lgkmcnt(2)
	v_mfma_f32_32x32x16_bf16 v[2:17], v[104:107], v[108:111], v[2:17]
	ds_read_b64_tr_b16 v[108:109], v164 offset:38912
	ds_read_b64_tr_b16 v[110:111], v164 offset:39424
	ds_read_b64_tr_b16 v[116:117], v164 offset:39936
	ds_read_b64_tr_b16 v[118:119], v164 offset:40448
	s_mov_b32 s1, 0
	v_mov_b32_e32 v155, v141
	v_mov_b32_e32 v151, v141
	v_mov_b32_e32 v153, v141
	s_mov_b32 s3, s73
	s_waitcnt lgkmcnt(2)
	v_mfma_f32_32x32x16_bf16 v[18:33], v[104:107], v[108:111], v[18:33]
	v_cvt_pk_bf16_f32 v104, v56, v57
	v_cvt_pk_bf16_f32 v105, v68, v69
	v_cvt_pk_bf16_f32 v68, v90, v91
	v_cvt_pk_bf16_f32 v69, v96, v97
	ds_read_b64_tr_b16 v[80:81], v164 offset:28672
	ds_read_b64_tr_b16 v[82:83], v164 offset:29184
	ds_read_b64_tr_b16 v[88:89], v164 offset:29696
	ds_read_b64_tr_b16 v[90:91], v164 offset:30208
	s_mov_b32 s4, s72
	v_mfma_f32_32x32x16_bf16 v[2:17], v[102:105], v[112:115], v[2:17]
	s_waitcnt lgkmcnt(4)
	v_mfma_f32_32x32x16_bf16 v[18:33], v[102:105], v[116:119], v[18:33]
	s_waitcnt lgkmcnt(2)
	v_mfma_f32_32x32x16_bf16 v[2:17], v[66:69], v[80:83], v[2:17]
	ds_read_b64_tr_b16 v[80:81], v164 offset:40960
	ds_read_b64_tr_b16 v[82:83], v164 offset:41472
	ds_read_b64_tr_b16 v[56:57], v164 offset:41984
	ds_read_b64_tr_b16 v[58:59], v164 offset:42496
	s_waitcnt lgkmcnt(2)
	v_mfma_f32_32x32x16_bf16 v[18:33], v[66:69], v[80:83], v[18:33]
	v_cvt_pk_bf16_f32 v66, v76, v77
	v_cvt_pk_bf16_f32 v67, v84, v85
	v_cvt_pk_bf16_f32 v68, v94, v95
	v_cvt_pk_bf16_f32 v69, v100, v101
	v_mfma_f32_32x32x16_bf16 v[2:17], v[44:47], v[88:91], v[2:17]
	s_waitcnt lgkmcnt(0)
	v_mfma_f32_32x32x16_bf16 v[18:33], v[44:47], v[56:59], v[18:33]
	ds_read_b64_tr_b16 v[44:45], v164 offset:30720
	ds_read_b64_tr_b16 v[46:47], v164 offset:31232
	ds_read_b64_tr_b16 v[56:57], v164 offset:31744
	ds_read_b64_tr_b16 v[58:59], v164 offset:32256
	s_waitcnt lgkmcnt(2)
	v_mfma_f32_32x32x16_bf16 v[2:17], v[66:69], v[44:47], v[2:17]
	ds_read_b64_tr_b16 v[44:45], v164 offset:43008
	ds_read_b64_tr_b16 v[46:47], v164 offset:43520
	ds_read_b64_tr_b16 v[74:75], v164 offset:44032
	ds_read_b64_tr_b16 v[76:77], v164 offset:44544
	s_waitcnt lgkmcnt(2)
	v_mfma_f32_32x32x16_bf16 v[18:33], v[66:69], v[44:47], v[18:33]
	v_cvt_pk_bf16_f32 v44, v72, v73
	v_cvt_pk_bf16_f32 v45, v78, v79
	v_cvt_pk_bf16_f32 v46, v86, v87
	v_cvt_pk_bf16_f32 v47, v92, v93
	v_mfma_f32_32x32x16_bf16 v[2:17], v[36:39], v[56:59], v[2:17]
	s_waitcnt lgkmcnt(0)
	v_mfma_f32_32x32x16_bf16 v[18:33], v[36:39], v[74:77], v[18:33]
	ds_read_b64_tr_b16 v[36:37], v164 offset:32768
	ds_read_b64_tr_b16 v[38:39], v164 offset:33280
	ds_read_b64_tr_b16 v[48:49], v164 offset:33792
	ds_read_b64_tr_b16 v[50:51], v164 offset:34304
	s_waitcnt lgkmcnt(2)
	v_mfma_f32_32x32x16_bf16 v[2:17], v[44:47], v[36:39], v[2:17]
	ds_read_b64_tr_b16 v[36:37], v164 offset:45056
	ds_read_b64_tr_b16 v[38:39], v164 offset:45568
	ds_read_b64_tr_b16 v[56:57], v164 offset:46080
	ds_read_b64_tr_b16 v[58:59], v164 offset:46592
	s_waitcnt lgkmcnt(2)
	v_mfma_f32_32x32x16_bf16 v[18:33], v[44:47], v[36:39], v[18:33]
	ds_read_b128 v[34:37], v162
	ds_read_b128 v[44:47], v162 offset:32
	v_mfma_f32_32x32x16_bf16 v[2:17], v[40:43], v[48:51], v[2:17]
	s_waitcnt lgkmcnt(2)
	v_mfma_f32_32x32x16_bf16 v[18:33], v[40:43], v[56:59], v[18:33]
	s_waitcnt lgkmcnt(1)
	s_nop 8
	v_mul_f32_e32 v2, v2, v34
	v_bfe_u32 v38, v2, 16, 1
	v_add3_u32 v2, v2, v38, s0
	ds_write_b16_d16_hi v165, v2
	v_mul_f32_e32 v2, v34, v18
	v_bfe_u32 v18, v2, 16, 1
	v_add3_u32 v2, v2, v18, s0
	ds_write_b16_d16_hi v165, v2 offset:64
	v_mul_f32_e32 v2, v3, v35
	v_bfe_u32 v3, v2, 16, 1
	v_add3_u32 v2, v2, v3, s0
	ds_write_b16_d16_hi v166, v2
	v_mul_f32_e32 v2, v19, v35
	v_bfe_u32 v3, v2, 16, 1
	v_add3_u32 v2, v2, v3, s0
	ds_write_b16_d16_hi v166, v2 offset:64
	v_mul_f32_e32 v2, v4, v36
	v_bfe_u32 v3, v2, 16, 1
	v_add3_u32 v2, v2, v3, s0
	ds_write_b16_d16_hi v167, v2
	v_mul_f32_e32 v2, v20, v36
	v_bfe_u32 v3, v2, 16, 1
	v_add3_u32 v2, v2, v3, s0
	ds_write_b16_d16_hi v167, v2 offset:64
	v_mul_f32_e32 v2, v5, v37
	v_bfe_u32 v3, v2, 16, 1
	v_add3_u32 v2, v2, v3, s0
	ds_write_b16_d16_hi v168, v2
	v_mul_f32_e32 v2, v21, v37
	v_bfe_u32 v3, v2, 16, 1
	v_add3_u32 v2, v2, v3, s0
	ds_write_b16_d16_hi v168, v2 offset:64
	s_waitcnt lgkmcnt(8)
	v_mul_f32_e32 v2, v6, v44
	v_bfe_u32 v3, v2, 16, 1
	v_add3_u32 v2, v2, v3, s0
	ds_write_b16_d16_hi v170, v2
	v_mul_f32_e32 v2, v22, v44
	v_bfe_u32 v3, v2, 16, 1
	v_add3_u32 v2, v2, v3, s0
	ds_write_b16_d16_hi v170, v2 offset:64
	v_mul_f32_e32 v2, v7, v45
	v_bfe_u32 v3, v2, 16, 1
	v_add3_u32 v2, v2, v3, s0
	ds_write_b16_d16_hi v171, v2
	v_mul_f32_e32 v2, v23, v45
	v_bfe_u32 v3, v2, 16, 1
	v_add3_u32 v2, v2, v3, s0
	ds_write_b16_d16_hi v171, v2 offset:64
	v_mul_f32_e32 v2, v8, v46
	v_bfe_u32 v3, v2, 16, 1
	v_add3_u32 v2, v2, v3, s0
	ds_write_b16_d16_hi v172, v2
	v_mul_f32_e32 v2, v24, v46
	v_bfe_u32 v3, v2, 16, 1
	v_add3_u32 v2, v2, v3, s0
	ds_write_b16_d16_hi v172, v2 offset:64
	v_mul_f32_e32 v2, v9, v47
	v_bfe_u32 v3, v2, 16, 1
	v_add3_u32 v2, v2, v3, s0
	ds_write_b16_d16_hi v169, v2
	ds_read_b128 v[2:5], v162 offset:64
	v_mul_f32_e32 v6, v25, v47
	v_bfe_u32 v7, v6, 16, 1
	v_add3_u32 v6, v6, v7, s0
	ds_write_b16_d16_hi v169, v6 offset:64
	ds_read_b128 v[6:9], v162 offset:96
	s_waitcnt lgkmcnt(2)
	v_mul_f32_e32 v10, v10, v2
	v_bfe_u32 v18, v10, 16, 1
	v_add3_u32 v10, v10, v18, s0
	v_mul_f32_e32 v2, v26, v2
	ds_write_b16_d16_hi v173, v10
	v_bfe_u32 v10, v2, 16, 1
	v_add3_u32 v2, v2, v10, s0
	ds_write_b16_d16_hi v173, v2 offset:64
	v_mul_f32_e32 v2, v11, v3
	v_bfe_u32 v10, v2, 16, 1
	v_add3_u32 v2, v2, v10, s0
	ds_write_b16_d16_hi v174, v2
	v_mul_f32_e32 v2, v27, v3
	v_bfe_u32 v3, v2, 16, 1
	v_add3_u32 v2, v2, v3, s0
	ds_write_b16_d16_hi v174, v2 offset:64
	v_mul_f32_e32 v2, v12, v4
	v_bfe_u32 v3, v2, 16, 1
	v_add3_u32 v2, v2, v3, s0
	ds_write_b16_d16_hi v175, v2
	v_mul_f32_e32 v2, v28, v4
	v_bfe_u32 v3, v2, 16, 1
	v_add3_u32 v2, v2, v3, s0
	ds_write_b16_d16_hi v175, v2 offset:64
	v_mul_f32_e32 v2, v13, v5
	v_bfe_u32 v3, v2, 16, 1
	v_add3_u32 v2, v2, v3, s0
	ds_write_b16_d16_hi v176, v2
	v_mul_f32_e32 v2, v29, v5
	v_bfe_u32 v3, v2, 16, 1
	v_add3_u32 v2, v2, v3, s0
	ds_write_b16_d16_hi v176, v2 offset:64
	s_waitcnt lgkmcnt(8)
	v_mul_f32_e32 v2, v14, v6
	v_bfe_u32 v3, v2, 16, 1
	v_add3_u32 v2, v2, v3, s0
	ds_write_b16_d16_hi v177, v2
	v_mul_f32_e32 v2, v30, v6
	v_bfe_u32 v3, v2, 16, 1
	v_add3_u32 v2, v2, v3, s0
	ds_write_b16_d16_hi v177, v2 offset:64
	v_mul_f32_e32 v2, v15, v7
	v_bfe_u32 v3, v2, 16, 1
	v_add3_u32 v2, v2, v3, s0
	ds_write_b16_d16_hi v178, v2
	v_mul_f32_e32 v2, v31, v7
	v_bfe_u32 v3, v2, 16, 1
	v_add3_u32 v2, v2, v3, s0
	ds_write_b16_d16_hi v178, v2 offset:64
	v_mul_f32_e32 v2, v16, v8
	v_bfe_u32 v3, v2, 16, 1
	v_add3_u32 v2, v2, v3, s0
	ds_write_b16_d16_hi v179, v2
	v_mul_f32_e32 v2, v32, v8
	v_bfe_u32 v3, v2, 16, 1
	v_add3_u32 v2, v2, v3, s0
	ds_write_b16_d16_hi v179, v2 offset:64
	v_mul_f32_e32 v2, v17, v9
	v_bfe_u32 v3, v2, 16, 1
	v_add3_u32 v2, v2, v3, s0
	ds_write_b16_d16_hi v180, v2
	v_mul_f32_e32 v2, v33, v9
	v_bfe_u32 v3, v2, 16, 1
	v_add3_u32 v2, v2, v3, s0
	ds_write_b16_d16_hi v180, v2 offset:64
	ds_read_b128 v[2:5], v181
	ds_read_b128 v[6:9], v182
	s_or_b32 s0, s58, 0x600
	v_lshl_add_u64 v[10:11], v[138:139], 0, s[0:1]
	v_lshl_add_u64 v[12:13], v[10:11], 0, v[140:141]
	s_waitcnt lgkmcnt(1)
	global_store_dwordx4 v[12:13], v[2:5], off
	v_lshl_add_u64 v[12:13], v[10:11], 0, v[154:155]
	ds_read_b128 v[2:5], v183
	s_waitcnt lgkmcnt(1)
	global_store_dwordx4 v[12:13], v[6:9], off
	ds_read_b128 v[6:9], v184
	v_lshl_add_u64 v[12:13], v[10:11], 0, v[150:151]
	s_mov_b64 s[0:1], s[82:83]
	s_waitcnt lgkmcnt(1)
	global_store_dwordx4 v[12:13], v[2:5], off
	s_nop 1
	v_lshl_add_u64 v[2:3], v[10:11], 0, v[152:153]
	s_waitcnt lgkmcnt(0)
	global_store_dwordx4 v[2:3], v[6:9], off
	v_mov_b32_e32 v2, v0
	s_barrier
	s_lshl_b32 s3, s4, 3
	v_readfirstlane_b32 s2, v2
	s_and_b32 s3, s3, 56
	s_bfe_u32 s5, s4, 0x30003
	s_ashr_i32 s2, s2, 3
	s_load_dwordx2 s[0:1], s[0:1], 0x90
	s_or_b32 s6, s3, s5
	s_andn2_b32 s4, s4, 63
	s_and_b32 s2, s2, -8
	s_lshl_b32 s3, s6, 8
	s_add_i32 s7, s4, s2
	s_add_i32 s4, s7, s3
	s_ashr_i32 s5, s4, 31
	s_lshl_b64 s[2:3], s[4:5], 11
	v_and_b32_e32 v122, 63, v2
	s_waitcnt lgkmcnt(0)
	s_add_u32 s2, s0, s2
	s_addc_u32 s3, s1, s3
	v_lshlrev_b32_e32 v140, 5, v122
	v_lshl_add_u64 v[14:15], s[2:3], 0, v[140:141]
	s_mov_b32 s2, 0xa801000
	v_add_co_u32_e32 v16, vcc, s2, v14
	s_waitcnt vmcnt(0)
	s_nop 1
	v_addc_co_u32_e32 v17, vcc, 0, v15, vcc
	s_barrier
	global_load_dwordx4 v[2:5], v[16:17], off offset:-4096
	s_mov_b64 s[2:3], 0xa800000
	v_lshl_add_u64 v[18:19], v[14:15], 0, s[2:3]
	global_load_dwordx4 v[6:9], v[18:19], off offset:16
	global_load_dwordx4 v[10:13], v[18:19], off offset:2048
	global_load_dwordx4 v[22:25], v[16:17], off
	s_lshl_b32 s2, s6, 19
	global_load_dwordx4 v[18:21], v[18:19], off offset:2064
	s_nop 0
	global_load_dwordx4 v[26:29], v[16:17], off offset:16
	global_load_dwordx4 v[30:33], v[16:17], off offset:2048
	s_add_u32 s2, s0, s2
	s_addc_u32 s3, s1, 0
	s_lshl_b32 s6, s7, 10
	s_and_b32 s6, s6, 0x3e000
	s_add_u32 s2, s2, s6
	s_addc_u32 s3, s3, 0
	s_lshl_b64 s[4:5], s[4:5], 2
	s_add_u32 s0, s0, s4
	s_mov_b32 s4, 0xa802000
	v_lshlrev_b32_e32 v140, 4, v122
	s_mov_b32 s7, 0x42fe0000
	s_addc_u32 s1, s1, s5
	s_mov_b32 s6, 0x40c0c00
	s_add_u32 s0, s0, 0xfc40000
	s_addc_u32 s1, s1, 0
	s_waitcnt vmcnt(6)
	v_lshlrev_b32_e32 v138, 16, v2
	v_and_b32_e32 v139, 0xffff0000, v2
	v_lshlrev_b32_e32 v150, 16, v3
	v_and_b32_e32 v151, 0xffff0000, v3
	v_max3_f32 v2, |v138|, 0, |v139|
	v_lshlrev_b32_e32 v152, 16, v4
	v_and_b32_e32 v153, 0xffff0000, v4
	v_max3_f32 v2, v2, |v150|, |v151|
	v_lshlrev_b32_e32 v154, 16, v5
	v_and_b32_e32 v155, 0xffff0000, v5
	v_max3_f32 v2, v2, |v152|, |v153|
	v_max3_f32 v2, v2, |v154|, |v155|
	s_waitcnt vmcnt(5)
	v_lshlrev_b32_e32 v156, 16, v6
	v_and_b32_e32 v157, 0xffff0000, v6
	v_lshlrev_b32_e32 v132, 16, v7
	v_and_b32_e32 v128, 0xffff0000, v7
	v_max3_f32 v2, v2, |v156|, |v157|
	v_lshlrev_b32_e32 v158, 16, v8
	v_and_b32_e32 v159, 0xffff0000, v8
	v_max3_f32 v2, v2, |v132|, |v128|
	v_lshlrev_b32_e32 v131, 16, v9
	v_and_b32_e32 v126, 0xffff0000, v9
	v_max3_f32 v2, v2, |v158|, |v159|
	v_max3_f32 v2, v2, |v131|, |v126|
	ds_swizzle_b32 v3, v2 offset:swizzle(SWAP,1)
	s_waitcnt vmcnt(4)
	v_lshlrev_b32_e32 v129, 16, v10
	v_and_b32_e32 v124, 0xffff0000, v10
	v_lshlrev_b32_e32 v121, 16, v11
	v_and_b32_e32 v119, 0xffff0000, v11
	s_waitcnt lgkmcnt(0)
	v_max_f32_e32 v3, v3, v3
	v_max_f32_e32 v4, v2, v3
	v_add_co_u32_e32 v2, vcc, s4, v14
	s_mov_b32 s4, 0xa803000
	s_nop 0
	v_addc_co_u32_e32 v3, vcc, 0, v15, vcc
	v_add_co_u32_e32 v46, vcc, s4, v14
	ds_swizzle_b32 v5, v4 offset:swizzle(SWAP,2)
	s_nop 0
	v_addc_co_u32_e32 v47, vcc, 0, v15, vcc
	global_load_dwordx4 v[34:37], v[16:17], off offset:2064
	global_load_dwordx4 v[38:41], v[46:47], off offset:-4096
	global_load_dwordx4 v[42:45], v[2:3], off offset:16
	global_load_dwordx4 v[142:145], v[2:3], off offset:2048
	global_load_dwordx4 v[146:149], v[2:3], off offset:2064
	s_nop 0
	global_load_dwordx4 v[14:17], v[46:47], off
	global_load_dwordx4 v[6:9], v[46:47], off offset:16
	s_waitcnt lgkmcnt(0)
	v_max_f32_e32 v5, v5, v5
	v_max_f32_e32 v4, v4, v5
	ds_swizzle_b32 v5, v4 offset:swizzle(SWAP,4)
	v_lshlrev_b32_e32 v125, 16, v12
	v_and_b32_e32 v123, 0xffff0000, v12
	s_waitcnt vmcnt(10)
	v_lshlrev_b32_e32 v109, 16, v22
	v_and_b32_e32 v107, 0xffff0000, v22
	s_waitcnt lgkmcnt(0)
	v_max_f32_e32 v5, v5, v5
	v_max_f32_e32 v4, v4, v5
	ds_swizzle_b32 v5, v4 offset:swizzle(SWAP,8)
	v_lshlrev_b32_e32 v120, 16, v13
	v_and_b32_e32 v118, 0xffff0000, v13
	v_lshlrev_b32_e32 v104, 16, v23
	v_and_b32_e32 v103, 0xffff0000, v23
	s_waitcnt lgkmcnt(0)
	v_max_f32_e32 v2, v5, v5
	v_max_f32_e32 v48, v4, v2
	v_max3_f32 v2, |v129|, 0, |v124|
	v_max3_f32 v2, v2, |v121|, |v119|
	v_max3_f32 v2, v2, |v125|, |v123|
	v_max3_f32 v22, |v109|, 0, |v107|
	v_max3_f32 v2, v2, |v120|, |v118|
	s_waitcnt vmcnt(9)
	v_lshlrev_b32_e32 v117, 16, v18
	v_and_b32_e32 v115, 0xffff0000, v18
	v_lshlrev_b32_e32 v108, 16, v24
	v_and_b32_e32 v106, 0xffff0000, v24
	v_max3_f32 v22, v22, |v104|, |v103|
	v_lshlrev_b32_e32 v113, 16, v19
	v_and_b32_e32 v111, 0xffff0000, v19
	v_max3_f32 v2, v2, |v117|, |v115|
	v_lshlrev_b32_e32 v105, 16, v25
	v_and_b32_e32 v102, 0xffff0000, v25
	v_max3_f32 v22, v22, |v108|, |v106|
	v_lshlrev_b32_e32 v116, 16, v20
	v_and_b32_e32 v114, 0xffff0000, v20
	v_max3_f32 v2, v2, |v113|, |v111|
	v_max3_f32 v22, v22, |v105|, |v102|
	s_waitcnt vmcnt(8)
	v_lshlrev_b32_e32 v99, 16, v26
	v_and_b32_e32 v97, 0xffff0000, v26
	v_lshlrev_b32_e32 v112, 16, v21
	v_and_b32_e32 v110, 0xffff0000, v21
	v_max3_f32 v2, v2, |v116|, |v114|
	v_lshlrev_b32_e32 v95, 16, v27
	v_and_b32_e32 v92, 0xffff0000, v27
	v_max3_f32 v22, v22, |v99|, |v97|
	v_max3_f32 v18, v2, |v112|, |v110|
	v_lshlrev_b32_e32 v98, 16, v28
	v_and_b32_e32 v96, 0xffff0000, v28
	v_max3_f32 v22, v22, |v95|, |v92|
	ds_swizzle_b32 v19, v18 offset:swizzle(SWAP,1)
	v_lshlrev_b32_e32 v94, 16, v29
	v_and_b32_e32 v91, 0xffff0000, v29
	v_max3_f32 v22, v22, |v98|, |v96|
	v_max3_f32 v22, v22, |v94|, |v91|
	ds_swizzle_b32 v23, v22 offset:swizzle(SWAP,1)
	ds_swizzle_b32 v49, v48 offset:swizzle(SWAP,16)
	s_waitcnt lgkmcnt(2)
	v_max_f32_e32 v19, v19, v19
	v_max_f32_e32 v18, v18, v19
	global_load_dwordx4 v[10:13], v[46:47], off offset:2048
	global_load_dwordx4 v[2:5], v[46:47], off offset:2064
	ds_swizzle_b32 v19, v18 offset:swizzle(SWAP,2)
	s_waitcnt lgkmcnt(2)
	v_max_f32_e32 v23, v23, v23
	v_max_f32_e32 v22, v22, v23
	s_waitcnt lgkmcnt(1)
	v_max_f32_e32 v20, v49, v49
	ds_swizzle_b32 v23, v22 offset:swizzle(SWAP,2)
	v_max_f32_e32 v20, v48, v20
	v_mov_b32_e32 v21, v20
	s_nop 1
	v_permlane32_swap_b32_e32 v20, v21
	s_waitcnt lgkmcnt(1)
	v_max_f32_e32 v19, v19, v19
	v_max_f32_e32 v21, v21, v21
	v_max_f32_e32 v18, v18, v19
	v_max_f32_e32 v20, v20, v20
	ds_swizzle_b32 v19, v18 offset:swizzle(SWAP,4)
	v_max_f32_e32 v135, v20, v21
	s_waitcnt lgkmcnt(1)
	v_max_f32_e32 v20, v23, v23
	s_waitcnt vmcnt(9)
	v_lshlrev_b32_e32 v89, 16, v30
	v_and_b32_e32 v87, 0xffff0000, v30
	v_max_f32_e32 v20, v22, v20
	v_lshlrev_b32_e32 v85, 16, v31
	v_and_b32_e32 v83, 0xffff0000, v31
	v_max3_f32 v22, |v89|, 0, |v87|
	v_lshlrev_b32_e32 v88, 16, v32
	v_and_b32_e32 v86, 0xffff0000, v32
	v_max3_f32 v22, v22, |v85|, |v83|
	v_lshlrev_b32_e32 v84, 16, v33
	v_and_b32_e32 v82, 0xffff0000, v33
	v_max3_f32 v22, v22, |v88|, |v86|
	v_max3_f32 v22, v22, |v84|, |v82|
	s_waitcnt vmcnt(8)
	v_lshlrev_b32_e32 v81, 16, v34
	v_and_b32_e32 v79, 0xffff0000, v34
	s_waitcnt lgkmcnt(0)
	v_max_f32_e32 v19, v19, v19
	v_lshlrev_b32_e32 v77, 16, v35
	v_and_b32_e32 v75, 0xffff0000, v35
	v_max3_f32 v22, v22, |v81|, |v79|
	v_max_f32_e32 v18, v18, v19
	v_lshlrev_b32_e32 v80, 16, v36
	v_and_b32_e32 v78, 0xffff0000, v36
	v_max3_f32 v22, v22, |v77|, |v75|
	ds_swizzle_b32 v19, v18 offset:swizzle(SWAP,8)
	v_lshlrev_b32_e32 v76, 16, v37
	v_and_b32_e32 v74, 0xffff0000, v37
	v_max3_f32 v22, v22, |v80|, |v78|
	ds_swizzle_b32 v21, v20 offset:swizzle(SWAP,4)
	v_max3_f32 v22, v22, |v76|, |v74|
	ds_swizzle_b32 v23, v22 offset:swizzle(SWAP,1)
	s_waitcnt lgkmcnt(2)
	v_max_f32_e32 v19, v19, v19
	v_max_f32_e32 v18, v18, v19
	s_waitcnt lgkmcnt(1)
	v_max_f32_e32 v21, v21, v21
	ds_swizzle_b32 v19, v18 offset:swizzle(SWAP,16)
	v_max_f32_e32 v20, v20, v21
	s_waitcnt lgkmcnt(1)
	v_max_f32_e32 v23, v23, v23
	ds_swizzle_b32 v21, v20 offset:swizzle(SWAP,8)
	v_max_f32_e32 v22, v22, v23
	ds_swizzle_b32 v23, v22 offset:swizzle(SWAP,2)
	s_waitcnt lgkmcnt(2)
	v_max_f32_e32 v19, v19, v19
	v_max_f32_e32 v136, v18, v19
	s_waitcnt lgkmcnt(1)
	v_max_f32_e32 v18, v21, v21
	v_max_f32_e32 v18, v20, v18
	s_waitcnt lgkmcnt(0)
	v_max_f32_e32 v20, v23, v23
	v_max_f32_e32 v20, v22, v20
	s_waitcnt vmcnt(7)
	v_lshlrev_b32_e32 v73, 16, v38
	v_and_b32_e32 v71, 0xffff0000, v38
	ds_swizzle_b32 v21, v20 offset:swizzle(SWAP,4)
	v_lshlrev_b32_e32 v68, 16, v39
	v_and_b32_e32 v67, 0xffff0000, v39
	v_max3_f32 v22, |v73|, 0, |v71|
	v_lshlrev_b32_e32 v72, 16, v40
	v_and_b32_e32 v70, 0xffff0000, v40
	v_max3_f32 v22, v22, |v68|, |v67|
	v_lshlrev_b32_e32 v69, 16, v41
	v_and_b32_e32 v66, 0xffff0000, v41
	v_max3_f32 v22, v22, |v72|, |v70|
	v_max3_f32 v22, v22, |v69|, |v66|
	s_waitcnt vmcnt(6)
	v_lshlrev_b32_e32 v63, 16, v42
	v_and_b32_e32 v61, 0xffff0000, v42
	v_lshlrev_b32_e32 v59, 16, v43
	v_and_b32_e32 v57, 0xffff0000, v43
	v_max3_f32 v22, v22, |v63|, |v61|
	s_waitcnt lgkmcnt(0)
	v_max_f32_e32 v21, v21, v21
	v_lshlrev_b32_e32 v62, 16, v44
	v_and_b32_e32 v60, 0xffff0000, v44
	v_max3_f32 v22, v22, |v59|, |v57|
	ds_swizzle_b32 v19, v18 offset:swizzle(SWAP,16)
	v_max_f32_e32 v20, v20, v21
	v_lshlrev_b32_e32 v58, 16, v45
	v_and_b32_e32 v56, 0xffff0000, v45
	v_max3_f32 v22, v22, |v62|, |v60|
	ds_swizzle_b32 v21, v20 offset:swizzle(SWAP,8)
	v_max3_f32 v22, v22, |v58|, |v56|
	ds_swizzle_b32 v23, v22 offset:swizzle(SWAP,1)
	s_waitcnt lgkmcnt(2)
	v_max_f32_e32 v19, v19, v19
	v_max_f32_e32 v133, v18, v19
	s_waitcnt lgkmcnt(1)
	v_max_f32_e32 v18, v21, v21
	v_max_f32_e32 v18, v20, v18
	s_waitcnt lgkmcnt(0)
	v_max_f32_e32 v20, v23, v23
	v_max_f32_e32 v20, v22, v20
	s_waitcnt vmcnt(5)
	v_lshlrev_b32_e32 v55, 16, v142
	v_and_b32_e32 v53, 0xffff0000, v142
	ds_swizzle_b32 v21, v20 offset:swizzle(SWAP,2)
	v_lshlrev_b32_e32 v51, 16, v143
	v_and_b32_e32 v49, 0xffff0000, v143
	v_max3_f32 v22, |v55|, 0, |v53|
	v_lshlrev_b32_e32 v54, 16, v144
	v_and_b32_e32 v52, 0xffff0000, v144
	v_max3_f32 v22, v22, |v51|, |v49|
	v_lshlrev_b32_e32 v50, 16, v145
	v_and_b32_e32 v48, 0xffff0000, v145
	v_max3_f32 v22, v22, |v54|, |v52|
	v_max3_f32 v22, v22, |v50|, |v48|
	s_waitcnt vmcnt(4)
	v_lshlrev_b32_e32 v47, 16, v146
	v_and_b32_e32 v45, 0xffff0000, v146
	v_lshlrev_b32_e32 v43, 16, v147
	v_and_b32_e32 v41, 0xffff0000, v147
	v_max3_f32 v22, v22, |v47|, |v45|
	s_waitcnt lgkmcnt(0)
	v_max_f32_e32 v21, v21, v21
	v_lshlrev_b32_e32 v46, 16, v148
	v_and_b32_e32 v44, 0xffff0000, v148
	v_max3_f32 v22, v22, |v43|, |v41|
	ds_swizzle_b32 v19, v18 offset:swizzle(SWAP,16)
	v_max_f32_e32 v20, v20, v21
	v_lshlrev_b32_e32 v42, 16, v149
	v_and_b32_e32 v40, 0xffff0000, v149
	v_max3_f32 v22, v22, |v46|, |v44|
	ds_swizzle_b32 v21, v20 offset:swizzle(SWAP,4)
	v_max3_f32 v22, v22, |v42|, |v40|
	ds_swizzle_b32 v23, v22 offset:swizzle(SWAP,1)
	s_waitcnt lgkmcnt(2)
	v_max_f32_e32 v19, v19, v19
	v_max_f32_e32 v127, v18, v19
	s_waitcnt lgkmcnt(1)
	v_max_f32_e32 v18, v21, v21
	v_max_f32_e32 v18, v20, v18
	s_waitcnt lgkmcnt(0)
	v_max_f32_e32 v20, v23, v23
	ds_swizzle_b32 v19, v18 offset:swizzle(SWAP,8)
	v_max_f32_e32 v20, v22, v20
	ds_swizzle_b32 v21, v20 offset:swizzle(SWAP,2)
	s_waitcnt vmcnt(3)
	v_lshlrev_b32_e32 v39, 16, v14
	v_and_b32_e32 v37, 0xffff0000, v14
	v_lshlrev_b32_e32 v32, 16, v15
	v_and_b32_e32 v31, 0xffff0000, v15
	v_max3_f32 v14, |v39|, 0, |v37|
	s_waitcnt lgkmcnt(1)
	v_max_f32_e32 v19, v19, v19
	v_lshlrev_b32_e32 v38, 16, v16
	v_and_b32_e32 v34, 0xffff0000, v16
	v_max3_f32 v14, v14, |v32|, |v31|
	v_max_f32_e32 v18, v18, v19
	s_waitcnt lgkmcnt(0)
	v_max_f32_e32 v21, v21, v21
	v_lshlrev_b32_e32 v33, 16, v17
	v_and_b32_e32 v30, 0xffff0000, v17
	v_max3_f32 v14, v14, |v38|, |v34|
	ds_swizzle_b32 v19, v18 offset:swizzle(SWAP,16)
	v_max_f32_e32 v20, v20, v21
	v_max3_f32 v14, v14, |v33|, |v30|
	s_waitcnt vmcnt(2)
	v_lshlrev_b32_e32 v29, 16, v6
	v_and_b32_e32 v27, 0xffff0000, v6
	ds_swizzle_b32 v21, v20 offset:swizzle(SWAP,4)
	v_lshlrev_b32_e32 v25, 16, v7
	v_and_b32_e32 v23, 0xffff0000, v7
	v_max3_f32 v6, v14, |v29|, |v27|
	v_lshlrev_b32_e32 v28, 16, v8
	v_and_b32_e32 v26, 0xffff0000, v8
	v_max3_f32 v6, v6, |v25|, |v23|
	v_lshlrev_b32_e32 v24, 16, v9
	v_and_b32_e32 v22, 0xffff0000, v9
	v_max3_f32 v6, v6, |v28|, |v26|
	v_max3_f32 v6, v6, |v24|, |v22|
	s_waitcnt lgkmcnt(1)
	v_max_f32_e32 v19, v19, v19
	ds_swizzle_b32 v7, v6 offset:swizzle(SWAP,1)
	v_max_f32_e32 v100, v18, v19
	s_waitcnt lgkmcnt(1)
	v_max_f32_e32 v18, v21, v21
	v_max_f32_e32 v18, v20, v18
	ds_swizzle_b32 v19, v18 offset:swizzle(SWAP,8)
	s_waitcnt lgkmcnt(1)
	v_max_f32_e32 v7, v7, v7
	v_max_f32_e32 v36, v6, v7
	ds_swizzle_b32 v64, v36 offset:swizzle(SWAP,2)
	s_waitcnt vmcnt(1)
	v_lshlrev_b32_e32 v21, 16, v10
	s_waitcnt lgkmcnt(1)
	v_max_f32_e32 v8, v19, v19
	v_and_b32_e32 v19, 0xffff0000, v10
	v_lshlrev_b32_e32 v17, 16, v11
	v_and_b32_e32 v15, 0xffff0000, v11
	v_max3_f32 v6, |v21|, 0, |v19|
	v_max_f32_e32 v35, v18, v8
	v_lshlrev_b32_e32 v20, 16, v12
	v_and_b32_e32 v18, 0xffff0000, v12
	v_max3_f32 v6, v6, |v17|, |v15|
	v_lshlrev_b32_e32 v16, 16, v13
	v_and_b32_e32 v14, 0xffff0000, v13
	v_max3_f32 v6, v6, |v20|, |v18|
	v_max3_f32 v65, v6, |v16|, |v14|
	s_waitcnt vmcnt(0)
	v_lshlrev_b32_e32 v8, 16, v5
	v_and_b32_e32 v6, 0xffff0000, v5
	s_waitcnt lgkmcnt(0)
	v_max_f32_e32 v5, v64, v64
	v_max_f32_e32 v5, v36, v5
	ds_swizzle_b32 v36, v5 offset:swizzle(SWAP,4)
	v_lshlrev_b32_e32 v13, 16, v2
	v_and_b32_e32 v11, 0xffff0000, v2
	v_lshlrev_b32_e32 v9, 16, v3
	v_and_b32_e32 v7, 0xffff0000, v3
	v_max3_f32 v2, v65, |v13|, |v11|
	v_lshlrev_b32_e32 v12, 16, v4
	v_and_b32_e32 v10, 0xffff0000, v4
	v_max3_f32 v2, v2, |v9|, |v7|
	v_max3_f32 v2, v2, |v12|, |v10|
	s_waitcnt lgkmcnt(0)
	v_max_f32_e32 v36, v36, v36
	v_max3_f32 v2, v2, |v8|, |v6|
	ds_swizzle_b32 v4, v35 offset:swizzle(SWAP,16)
	v_max_f32_e32 v5, v5, v36
	ds_swizzle_b32 v3, v2 offset:swizzle(SWAP,1)
	ds_swizzle_b32 v36, v5 offset:swizzle(SWAP,8)
	v_cmp_eq_u32_e64 s[4:5], 0, v122
	s_waitcnt lgkmcnt(2)
	v_max_f32_e32 v4, v4, v4
	v_max_f32_e32 v90, v35, v4
	s_waitcnt lgkmcnt(1)
	v_max_f32_e32 v3, v3, v3
	s_waitcnt lgkmcnt(0)
	v_max_f32_e32 v4, v36, v36
	v_max_f32_e32 v2, v2, v3
	v_max_f32_e32 v4, v5, v4
	ds_swizzle_b32 v3, v2 offset:swizzle(SWAP,2)
	ds_swizzle_b32 v5, v4 offset:swizzle(SWAP,16)
	v_mov_b32_e32 v137, v136
	v_mov_b32_e32 v134, v133
	v_mov_b32_e32 v130, v127
	s_waitcnt lgkmcnt(1)
	v_max_f32_e32 v3, v3, v3
	s_waitcnt lgkmcnt(0)
	v_max_f32_e32 v5, v5, v5
	v_max_f32_e32 v2, v2, v3
	v_max_f32_e32 v64, v4, v5
	v_lshl_add_u64 v[4:5], s[2:3], 0, v[140:141]
	v_div_scale_f32 v140, s[2:3], v135, v135, s7
	ds_swizzle_b32 v3, v2 offset:swizzle(SWAP,4)
	v_rcp_f32_e32 v141, v140
	s_mov_b64 s[2:3], 0xdc00000
	v_mov_b32_e32 v101, v100
	v_mov_b32_e32 v93, v90
	v_fma_f32 v122, -v140, v141, 1.0
	s_waitcnt lgkmcnt(0)
	v_max_f32_e32 v3, v3, v3
	v_fmac_f32_e32 v141, v122, v141
	v_div_scale_f32 v122, vcc, s7, v135, s7
	v_max_f32_e32 v2, v2, v3
	v_mul_f32_e32 v142, v122, v141
	ds_swizzle_b32 v3, v2 offset:swizzle(SWAP,8)
	v_fma_f32 v143, -v140, v142, v122
	v_fmac_f32_e32 v142, v143, v141
	v_fma_f32 v122, -v140, v142, v122
	v_div_fmas_f32 v122, v122, v141, v142
	v_div_fixup_f32 v122, v122, v135, s7
	v_cmp_lt_f32_e32 vcc, 0, v135
	s_waitcnt lgkmcnt(0)
	v_max_f32_e32 v3, v3, v3
	v_max_f32_e32 v2, v2, v3
	v_cndmask_b32_e32 v122, 0, v122, vcc
	v_mul_f32_e32 v139, v122, v139
	ds_swizzle_b32 v3, v2 offset:swizzle(SWAP,16)
	v_mul_f32_e32 v138, v122, v138
	v_rndne_f32_e32 v139, v139
	v_mul_f32_e32 v141, v122, v153
	v_mul_f32_e32 v142, v122, v150
	v_mul_f32_e32 v144, v122, v151
	v_rndne_f32_e32 v138, v138
	v_cvt_i32_f32_e32 v139, v139
	v_mul_f32_e32 v140, v122, v152
	v_rndne_f32_e32 v141, v141
	v_rndne_f32_e32 v142, v142
	v_mul_f32_e32 v143, v122, v154
	v_rndne_f32_e32 v144, v144
	v_mul_f32_e32 v145, v122, v155
	v_cvt_i32_f32_e32 v138, v138
	v_rndne_f32_e32 v140, v140
	v_cvt_i32_f32_e32 v141, v141
	v_cvt_i32_f32_sdwa v142, v142 dst_sel:WORD_1 dst_unused:UNUSED_PAD src0_sel:DWORD
	v_rndne_f32_e32 v143, v143
	v_cvt_i32_f32_e32 v144, v144
	v_rndne_f32_e32 v145, v145
	v_cvt_i32_f32_e32 v140, v140
	v_cvt_i32_f32_sdwa v143, v143 dst_sel:WORD_1 dst_unused:UNUSED_PAD src0_sel:DWORD
	v_cvt_i32_f32_e32 v145, v145
	s_waitcnt lgkmcnt(0)
	v_max_f32_e32 v3, v3, v3
	v_lshlrev_b32_e32 v139, 8, v139
	v_max_f32_e32 v35, v2, v3
	v_lshl_add_u64 v[2:3], v[4:5], 0, s[2:3]
	v_and_b32_e32 v139, 0xff00, v139
	v_lshlrev_b32_e32 v141, 8, v141
	v_and_b32_e32 v142, 0xff0000, v142
	v_perm_b32 v138, v144, v138, s6
	s_mov_b32 s2, 0xdc00000
	v_and_b32_e32 v141, 0xff00, v141
	v_and_b32_e32 v143, 0xff0000, v143
	v_or3_b32 v138, v138, v139, v142
	v_perm_b32 v139, v145, v140, s6
	v_add_co_u32_e32 v4, vcc, s2, v4
	v_or3_b32 v139, v139, v141, v143
	s_nop 0
	v_addc_co_u32_e32 v5, vcc, 0, v5, vcc
	v_mov_b32_e32 v200, v138
	v_mov_b32_e32 v201, v139
	v_mul_f32_e32 v5, v122, v157
	v_mul_f32_e32 v4, v122, v156
	v_rndne_f32_e32 v5, v5
	v_mul_f32_e32 v139, v122, v159
	v_mul_f32_e32 v132, v122, v132
	v_mul_f32_e32 v128, v122, v128
	v_rndne_f32_e32 v4, v4
	v_cvt_i32_f32_e32 v5, v5
	v_mul_f32_e32 v138, v122, v158
	v_rndne_f32_e32 v139, v139
	v_rndne_f32_e32 v132, v132
	v_mul_f32_e32 v131, v122, v131
	v_rndne_f32_e32 v128, v128
	v_mul_f32_e32 v122, v122, v126
	v_cvt_i32_f32_e32 v4, v4
	v_rndne_f32_e32 v138, v138
	v_cvt_i32_f32_e32 v139, v139
	v_cvt_i32_f32_sdwa v132, v132 dst_sel:WORD_1 dst_unused:UNUSED_PAD src0_sel:DWORD
	v_rndne_f32_e32 v131, v131
	v_cvt_i32_f32_e32 v128, v128
	v_rndne_f32_e32 v122, v122
	v_cvt_i32_f32_e32 v138, v138
	v_cvt_i32_f32_sdwa v131, v131 dst_sel:WORD_1 dst_unused:UNUSED_PAD src0_sel:DWORD
	v_cvt_i32_f32_e32 v122, v122
	v_lshlrev_b32_e32 v5, 8, v5
	v_and_b32_e32 v5, 0xff00, v5
	v_lshlrev_b32_e32 v139, 8, v139
	v_and_b32_e32 v132, 0xff0000, v132
	v_perm_b32 v4, v128, v4, s6
	v_mov_b32_e32 v65, v64
	v_mov_b32_e32 v36, v35
	v_and_b32_e32 v139, 0xff00, v139
	v_and_b32_e32 v126, 0xff0000, v131
	v_or3_b32 v4, v4, v5, v132
	v_perm_b32 v5, v122, v138, s6
	v_permlane32_swap_b32_e32 v136, v137
	v_permlane32_swap_b32_e32 v133, v134
	v_permlane32_swap_b32_e32 v127, v130
	v_permlane32_swap_b32_e32 v100, v101
	v_permlane32_swap_b32_e32 v90, v93
	v_permlane32_swap_b32_e32 v64, v65
	v_permlane32_swap_b32_e32 v35, v36
	v_or3_b32 v5, v5, v139, v126
	v_mov_b32_e32 v202, v4
	v_mov_b32_e32 v203, v5
	global_store_dwordx4 v[2:3], v[200:203], off
	s_and_saveexec_b64 s[2:3], s[4:5]
	s_cbranch_execz .LBB0_866
	v_mul_f32_e32 v4, 0x3c010204, v135
	v_mov_b32_e32 v5, 0
	global_store_dword v5, v4, s[0:1]
.LBB0_866:
	s_or_b64 exec, exec, s[2:3]
	v_max_f32_e32 v4, v136, v136
	v_max_f32_e32 v5, v137, v137
	v_max_f32_e32 v4, v4, v5
	v_div_scale_f32 v5, s[2:3], v4, v4, s7
	v_rcp_f32_e32 v122, v5
	s_nop 0
	v_fma_f32 v126, -v5, v122, 1.0
	v_fmac_f32_e32 v122, v126, v122
	v_div_scale_f32 v126, vcc, s7, v4, s7
	v_mul_f32_e32 v128, v126, v122
	v_fma_f32 v131, -v5, v128, v126
	v_fmac_f32_e32 v128, v131, v122
	v_fma_f32 v5, -v5, v128, v126
	v_div_fmas_f32 v5, v5, v122, v128
	v_div_fixup_f32 v5, v5, v4, s7
	v_cmp_lt_f32_e32 vcc, 0, v4
	s_nop 1
	v_cndmask_b32_e32 v5, 0, v5, vcc
	v_mul_f32_e32 v124, v5, v124
	v_mul_f32_e32 v123, v5, v123
	v_mul_f32_e32 v115, v5, v115
	v_mul_f32_e32 v114, v5, v114
	v_mul_f32_e32 v122, v5, v129
	v_rndne_f32_e32 v124, v124
	v_mul_f32_e32 v125, v5, v125
	v_rndne_f32_e32 v123, v123
	v_mul_f32_e32 v121, v5, v121
	v_mul_f32_e32 v120, v5, v120
	v_mul_f32_e32 v119, v5, v119
	v_mul_f32_e32 v118, v5, v118
	v_mul_f32_e32 v117, v5, v117
	v_rndne_f32_e32 v115, v115
	v_mul_f32_e32 v116, v5, v116
	v_rndne_f32_e32 v114, v114
	v_mul_f32_e32 v113, v5, v113
	v_mul_f32_e32 v112, v5, v112
	v_mul_f32_e32 v111, v5, v111
	v_mul_f32_e32 v5, v5, v110
	v_rndne_f32_e32 v122, v122
	v_cvt_i32_f32_e32 v124, v124
	v_rndne_f32_e32 v125, v125
	v_cvt_i32_f32_e32 v123, v123
	v_rndne_f32_e32 v121, v121
	v_rndne_f32_e32 v120, v120
	v_rndne_f32_e32 v119, v119
	v_rndne_f32_e32 v118, v118
	v_rndne_f32_e32 v117, v117
	v_cvt_i32_f32_e32 v115, v115
	v_rndne_f32_e32 v116, v116
	v_cvt_i32_f32_e32 v114, v114
	v_rndne_f32_e32 v113, v113
	v_rndne_f32_e32 v112, v112
	v_rndne_f32_e32 v111, v111
	v_rndne_f32_e32 v5, v5
	v_cvt_i32_f32_e32 v122, v122
	v_cvt_i32_f32_e32 v125, v125
	v_cvt_i32_f32_sdwa v121, v121 dst_sel:WORD_1 dst_unused:UNUSED_PAD src0_sel:DWORD
	v_cvt_i32_f32_sdwa v120, v120 dst_sel:WORD_1 dst_unused:UNUSED_PAD src0_sel:DWORD
	v_cvt_i32_f32_e32 v119, v119
	v_cvt_i32_f32_e32 v126, v118
	v_cvt_i32_f32_e32 v117, v117
	v_cvt_i32_f32_e32 v116, v116
	v_cvt_i32_f32_sdwa v113, v113 dst_sel:WORD_1 dst_unused:UNUSED_PAD src0_sel:DWORD
	v_cvt_i32_f32_sdwa v112, v112 dst_sel:WORD_1 dst_unused:UNUSED_PAD src0_sel:DWORD
	v_cvt_i32_f32_e32 v111, v111
	v_cvt_i32_f32_e32 v5, v5
	v_lshlrev_b32_e32 v124, 8, v124
	v_lshlrev_b32_e32 v123, 8, v123
	v_lshlrev_b32_e32 v115, 8, v115
	v_lshlrev_b32_e32 v114, 8, v114
	v_and_b32_e32 v124, 0xff00, v124
	v_and_b32_e32 v123, 0xff00, v123
	v_and_b32_e32 v121, 0xff0000, v121
	v_and_b32_e32 v120, 0xff0000, v120
	v_perm_b32 v118, v119, v122, s6
	v_perm_b32 v119, v126, v125, s6
	v_and_b32_e32 v115, 0xff00, v115
	v_and_b32_e32 v114, 0xff00, v114
	v_and_b32_e32 v113, 0xff0000, v113
	v_and_b32_e32 v112, 0xff0000, v112
	v_perm_b32 v110, v111, v117, s6
	v_perm_b32 v5, v5, v116, s6
	v_or3_b32 v118, v118, v124, v121
	v_or3_b32 v119, v119, v123, v120
	v_or3_b32 v110, v110, v115, v113
	v_or3_b32 v111, v5, v114, v112
	v_mov_b32_e32 v204, v118
	v_mov_b32_e32 v205, v119
	v_mov_b32_e32 v206, v110
	v_mov_b32_e32 v207, v111
	global_store_dwordx4 v[2:3], v[204:207], off offset:1024
	s_and_saveexec_b64 s[2:3], s[4:5]
	s_cbranch_execz .LBB0_868
	v_mov_b32_e32 v5, 0
	v_mul_f32_e32 v4, 0x3c010204, v4
	global_store_dword v5, v4, s[0:1] offset:4
.LBB0_868:
	s_or_b64 exec, exec, s[2:3]
	v_max_f32_e32 v4, v133, v133
	v_max_f32_e32 v5, v134, v134
	v_max_f32_e32 v4, v4, v5
	v_div_scale_f32 v5, s[2:3], v4, v4, s7
	v_rcp_f32_e32 v110, v5
	s_nop 0
	v_fma_f32 v111, -v5, v110, 1.0
	v_fmac_f32_e32 v110, v111, v110
	v_div_scale_f32 v111, vcc, s7, v4, s7
	v_mul_f32_e32 v112, v111, v110
	v_fma_f32 v113, -v5, v112, v111
	v_fmac_f32_e32 v112, v113, v110
	v_fma_f32 v5, -v5, v112, v111
	v_div_fmas_f32 v5, v5, v110, v112
	v_div_fixup_f32 v5, v5, v4, s7
	v_cmp_lt_f32_e32 vcc, 0, v4
	s_nop 1
	v_cndmask_b32_e32 v5, 0, v5, vcc
	v_mul_f32_e32 v107, v5, v107
	v_mul_f32_e32 v106, v5, v106
	v_mul_f32_e32 v97, v5, v97
	v_mul_f32_e32 v96, v5, v96
	v_mul_f32_e32 v109, v5, v109
	v_rndne_f32_e32 v107, v107
	v_mul_f32_e32 v108, v5, v108
	v_rndne_f32_e32 v106, v106
	v_mul_f32_e32 v104, v5, v104
	v_mul_f32_e32 v105, v5, v105
	v_mul_f32_e32 v103, v5, v103
	v_mul_f32_e32 v102, v5, v102
	v_mul_f32_e32 v99, v5, v99
	v_rndne_f32_e32 v97, v97
	v_mul_f32_e32 v98, v5, v98
	v_rndne_f32_e32 v96, v96
	v_mul_f32_e32 v95, v5, v95
	v_mul_f32_e32 v94, v5, v94
	v_mul_f32_e32 v92, v5, v92
	v_mul_f32_e32 v5, v5, v91
	v_rndne_f32_e32 v109, v109
	v_cvt_i32_f32_e32 v107, v107
	v_rndne_f32_e32 v108, v108
	v_cvt_i32_f32_e32 v106, v106
	v_rndne_f32_e32 v104, v104
	v_rndne_f32_e32 v105, v105
	v_rndne_f32_e32 v103, v103
	v_rndne_f32_e32 v102, v102
	v_rndne_f32_e32 v99, v99
	v_cvt_i32_f32_e32 v97, v97
	v_rndne_f32_e32 v98, v98
	v_cvt_i32_f32_e32 v96, v96
	v_rndne_f32_e32 v95, v95
	v_rndne_f32_e32 v94, v94
	v_rndne_f32_e32 v92, v92
	v_rndne_f32_e32 v5, v5
	v_cvt_i32_f32_e32 v109, v109
	v_cvt_i32_f32_e32 v108, v108
	v_cvt_i32_f32_sdwa v104, v104 dst_sel:WORD_1 dst_unused:UNUSED_PAD src0_sel:DWORD
	v_cvt_i32_f32_sdwa v105, v105 dst_sel:WORD_1 dst_unused:UNUSED_PAD src0_sel:DWORD
	v_cvt_i32_f32_e32 v103, v103
	v_cvt_i32_f32_e32 v110, v102
	v_cvt_i32_f32_e32 v99, v99
	v_cvt_i32_f32_e32 v98, v98
	v_cvt_i32_f32_sdwa v95, v95 dst_sel:WORD_1 dst_unused:UNUSED_PAD src0_sel:DWORD
	v_cvt_i32_f32_sdwa v94, v94 dst_sel:WORD_1 dst_unused:UNUSED_PAD src0_sel:DWORD
	v_cvt_i32_f32_e32 v92, v92
	v_cvt_i32_f32_e32 v5, v5
	v_lshlrev_b32_e32 v107, 8, v107
	v_lshlrev_b32_e32 v106, 8, v106
	v_lshlrev_b32_e32 v97, 8, v97
	v_lshlrev_b32_e32 v96, 8, v96
	v_and_b32_e32 v107, 0xff00, v107
	v_and_b32_e32 v106, 0xff00, v106
	v_and_b32_e32 v104, 0xff0000, v104
	v_and_b32_e32 v105, 0xff0000, v105
	v_perm_b32 v102, v103, v109, s6
	v_perm_b32 v103, v110, v108, s6
	v_and_b32_e32 v97, 0xff00, v97
	v_and_b32_e32 v96, 0xff00, v96
	v_and_b32_e32 v95, 0xff0000, v95
	v_and_b32_e32 v91, 0xff0000, v94
	v_perm_b32 v92, v92, v99, s6
	v_perm_b32 v5, v5, v98, s6
	v_or3_b32 v102, v102, v107, v104
	v_or3_b32 v103, v103, v106, v105
	v_or3_b32 v94, v92, v97, v95
	v_or3_b32 v95, v5, v96, v91
	v_mov_b32_e32 v200, v102
	v_mov_b32_e32 v201, v103
	v_mov_b32_e32 v202, v94
	v_mov_b32_e32 v203, v95
	global_store_dwordx4 v[2:3], v[200:203], off offset:2048
	s_and_saveexec_b64 s[2:3], s[4:5]
	s_cbranch_execz .LBB0_870
	v_mov_b32_e32 v5, 0
	v_mul_f32_e32 v4, 0x3c010204, v4
	global_store_dword v5, v4, s[0:1] offset:8
.LBB0_870:
	s_or_b64 exec, exec, s[2:3]
	v_max_f32_e32 v4, v127, v127
	v_max_f32_e32 v5, v130, v130
	v_max_f32_e32 v4, v4, v5
	v_div_scale_f32 v5, s[2:3], v4, v4, s7
	v_rcp_f32_e32 v91, v5
	s_nop 0
	v_fma_f32 v92, -v5, v91, 1.0
	v_fmac_f32_e32 v91, v92, v91
	v_div_scale_f32 v92, vcc, s7, v4, s7
	v_mul_f32_e32 v94, v92, v91
	v_fma_f32 v95, -v5, v94, v92
	v_fmac_f32_e32 v94, v95, v91
	v_fma_f32 v5, -v5, v94, v92
	v_div_fmas_f32 v5, v5, v91, v94
	v_div_fixup_f32 v5, v5, v4, s7
	v_cmp_lt_f32_e32 vcc, 0, v4
	s_nop 1
	v_cndmask_b32_e32 v5, 0, v5, vcc
	v_mul_f32_e32 v87, v5, v87
	v_mul_f32_e32 v86, v5, v86
	v_mul_f32_e32 v79, v5, v79
	v_mul_f32_e32 v78, v5, v78
	v_mul_f32_e32 v89, v5, v89
	v_rndne_f32_e32 v87, v87
	v_mul_f32_e32 v88, v5, v88
	v_rndne_f32_e32 v86, v86
	v_mul_f32_e32 v85, v5, v85
	v_mul_f32_e32 v84, v5, v84
	v_mul_f32_e32 v83, v5, v83
	v_mul_f32_e32 v82, v5, v82
	v_mul_f32_e32 v81, v5, v81
	v_rndne_f32_e32 v79, v79
	v_mul_f32_e32 v80, v5, v80
	v_rndne_f32_e32 v78, v78
	v_mul_f32_e32 v77, v5, v77
	v_mul_f32_e32 v76, v5, v76
	v_mul_f32_e32 v75, v5, v75
	v_mul_f32_e32 v5, v5, v74
	v_rndne_f32_e32 v89, v89
	v_cvt_i32_f32_e32 v87, v87
	v_rndne_f32_e32 v88, v88
	v_cvt_i32_f32_e32 v86, v86
	v_rndne_f32_e32 v85, v85
	v_rndne_f32_e32 v84, v84
	v_rndne_f32_e32 v83, v83
	v_rndne_f32_e32 v82, v82
	v_rndne_f32_e32 v81, v81
	v_cvt_i32_f32_e32 v79, v79
	v_rndne_f32_e32 v80, v80
	v_cvt_i32_f32_e32 v78, v78
	v_rndne_f32_e32 v77, v77
	v_rndne_f32_e32 v76, v76
	v_rndne_f32_e32 v75, v75
	v_rndne_f32_e32 v5, v5
	v_cvt_i32_f32_e32 v89, v89
	v_cvt_i32_f32_e32 v88, v88
	v_cvt_i32_f32_sdwa v85, v85 dst_sel:WORD_1 dst_unused:UNUSED_PAD src0_sel:DWORD
	v_cvt_i32_f32_sdwa v84, v84 dst_sel:WORD_1 dst_unused:UNUSED_PAD src0_sel:DWORD
	v_cvt_i32_f32_e32 v83, v83
	v_cvt_i32_f32_e32 v91, v82
	v_cvt_i32_f32_e32 v81, v81
	v_cvt_i32_f32_e32 v80, v80
	v_cvt_i32_f32_sdwa v77, v77 dst_sel:WORD_1 dst_unused:UNUSED_PAD src0_sel:DWORD
	v_cvt_i32_f32_sdwa v76, v76 dst_sel:WORD_1 dst_unused:UNUSED_PAD src0_sel:DWORD
	v_cvt_i32_f32_e32 v75, v75
	v_cvt_i32_f32_e32 v5, v5
	v_lshlrev_b32_e32 v87, 8, v87
	v_lshlrev_b32_e32 v86, 8, v86
	v_lshlrev_b32_e32 v79, 8, v79
	v_lshlrev_b32_e32 v78, 8, v78
	v_and_b32_e32 v87, 0xff00, v87
	v_and_b32_e32 v86, 0xff00, v86
	v_and_b32_e32 v85, 0xff0000, v85
	v_and_b32_e32 v84, 0xff0000, v84
	v_perm_b32 v82, v83, v89, s6
	v_perm_b32 v83, v91, v88, s6
	v_and_b32_e32 v79, 0xff00, v79
	v_and_b32_e32 v78, 0xff00, v78
	v_and_b32_e32 v77, 0xff0000, v77
	v_and_b32_e32 v76, 0xff0000, v76
	v_perm_b32 v74, v75, v81, s6
	v_perm_b32 v5, v5, v80, s6
	v_or3_b32 v82, v82, v87, v85
	v_or3_b32 v83, v83, v86, v84
	v_or3_b32 v74, v74, v79, v77
	v_or3_b32 v75, v5, v78, v76
	v_mov_b32_e32 v204, v82
	v_mov_b32_e32 v205, v83
	v_mov_b32_e32 v206, v74
	v_mov_b32_e32 v207, v75
	global_store_dwordx4 v[2:3], v[204:207], off offset:3072
	s_and_saveexec_b64 s[2:3], s[4:5]
	s_cbranch_execz .LBB0_872
	v_mov_b32_e32 v5, 0
	v_mul_f32_e32 v4, 0x3c010204, v4
	global_store_dword v5, v4, s[0:1] offset:12
.LBB0_872:
	s_or_b64 exec, exec, s[2:3]
	v_max_f32_e32 v4, v100, v100
	v_max_f32_e32 v5, v101, v101
	v_max_f32_e32 v74, v4, v5
	v_div_scale_f32 v4, s[2:3], v74, v74, s7
	v_rcp_f32_e32 v5, v4
	s_movk_i32 s2, 0x1000
	v_fma_f32 v75, -v4, v5, 1.0
	v_fmac_f32_e32 v5, v75, v5
	v_div_scale_f32 v75, vcc, s7, v74, s7
	v_mul_f32_e32 v76, v75, v5
	v_fma_f32 v77, -v4, v76, v75
	v_fmac_f32_e32 v76, v77, v5
	v_fma_f32 v4, -v4, v76, v75
	v_div_fmas_f32 v4, v4, v5, v76
	v_div_fixup_f32 v4, v4, v74, s7
	v_cmp_lt_f32_e32 vcc, 0, v74
	s_nop 1
	v_cndmask_b32_e32 v75, 0, v4, vcc
	v_mul_f32_e32 v5, v75, v71
	v_mul_f32_e32 v4, v75, v73
	v_rndne_f32_e32 v5, v5
	v_mul_f32_e32 v70, v75, v70
	v_mul_f32_e32 v68, v75, v68
	v_mul_f32_e32 v67, v75, v67
	v_rndne_f32_e32 v4, v4
	v_cvt_i32_f32_e32 v5, v5
	v_mul_f32_e32 v71, v75, v72
	v_rndne_f32_e32 v70, v70
	v_rndne_f32_e32 v68, v68
	v_mul_f32_e32 v69, v75, v69
	v_rndne_f32_e32 v67, v67
	v_mul_f32_e32 v66, v75, v66
	v_cvt_i32_f32_e32 v4, v4
	v_rndne_f32_e32 v71, v71
	v_cvt_i32_f32_e32 v70, v70
	v_cvt_i32_f32_sdwa v68, v68 dst_sel:WORD_1 dst_unused:UNUSED_PAD src0_sel:DWORD
	v_rndne_f32_e32 v69, v69
	v_cvt_i32_f32_e32 v67, v67
	v_rndne_f32_e32 v66, v66
	v_cvt_i32_f32_e32 v71, v71
	v_cvt_i32_f32_sdwa v69, v69 dst_sel:WORD_1 dst_unused:UNUSED_PAD src0_sel:DWORD
	v_cvt_i32_f32_e32 v72, v66
	v_lshlrev_b32_e32 v5, 8, v5
	v_and_b32_e32 v5, 0xff00, v5
	v_lshlrev_b32_e32 v70, 8, v70
	v_and_b32_e32 v68, 0xff0000, v68
	v_perm_b32 v4, v67, v4, s6
	v_and_b32_e32 v70, 0xff00, v70
	v_and_b32_e32 v69, 0xff0000, v69
	v_or3_b32 v66, v4, v5, v68
	v_perm_b32 v4, v72, v71, s6
	v_mul_f32_e32 v61, v75, v61
	v_mul_f32_e32 v60, v75, v60
	v_or3_b32 v67, v4, v70, v69
	v_add_co_u32_e32 v4, vcc, s2, v2
	v_mul_f32_e32 v63, v75, v63
	v_rndne_f32_e32 v61, v61
	v_mul_f32_e32 v62, v75, v62
	v_rndne_f32_e32 v60, v60
	v_mul_f32_e32 v59, v75, v59
	v_mul_f32_e32 v58, v75, v58
	v_mul_f32_e32 v57, v75, v57
	v_mul_f32_e32 v56, v75, v56
	v_addc_co_u32_e32 v5, vcc, 0, v3, vcc
	v_rndne_f32_e32 v63, v63
	v_cvt_i32_f32_e32 v61, v61
	v_rndne_f32_e32 v62, v62
	v_cvt_i32_f32_e32 v60, v60
	v_rndne_f32_e32 v59, v59
	v_rndne_f32_e32 v58, v58
	v_rndne_f32_e32 v57, v57
	v_rndne_f32_e32 v56, v56
	v_mov_b32_e32 v200, v66
	v_mov_b32_e32 v201, v67
	v_cvt_i32_f32_e32 v63, v63
	v_cvt_i32_f32_e32 v62, v62
	v_cvt_i32_f32_sdwa v59, v59 dst_sel:WORD_1 dst_unused:UNUSED_PAD src0_sel:DWORD
	v_cvt_i32_f32_sdwa v58, v58 dst_sel:WORD_1 dst_unused:UNUSED_PAD src0_sel:DWORD
	v_cvt_i32_f32_e32 v57, v57
	v_cvt_i32_f32_e32 v66, v56
	v_lshlrev_b32_e32 v61, 8, v61
	v_lshlrev_b32_e32 v60, 8, v60
	v_and_b32_e32 v61, 0xff00, v61
	v_and_b32_e32 v60, 0xff00, v60
	v_and_b32_e32 v59, 0xff0000, v59
	v_and_b32_e32 v58, 0xff0000, v58
	v_perm_b32 v56, v57, v63, s6
	v_perm_b32 v57, v66, v62, s6
	v_or3_b32 v56, v56, v61, v59
	v_or3_b32 v57, v57, v60, v58
	v_mov_b32_e32 v202, v56
	v_mov_b32_e32 v203, v57
	global_store_dwordx4 v[4:5], v[200:203], off
	s_and_saveexec_b64 s[2:3], s[4:5]
	s_cbranch_execz .LBB0_874
	v_mov_b32_e32 v56, 0
	v_mul_f32_e32 v57, 0x3c010204, v74
	global_store_dword v56, v57, s[0:1] offset:16
.LBB0_874:
	s_or_b64 exec, exec, s[2:3]
	v_max_f32_e32 v56, v90, v90
	v_max_f32_e32 v57, v93, v93
	v_max_f32_e32 v56, v56, v57
	v_div_scale_f32 v57, s[2:3], v56, v56, s7
	v_rcp_f32_e32 v58, v57
	s_nop 0
	v_fma_f32 v59, -v57, v58, 1.0
	v_fmac_f32_e32 v58, v59, v58
	v_div_scale_f32 v59, vcc, s7, v56, s7
	v_mul_f32_e32 v60, v59, v58
	v_fma_f32 v61, -v57, v60, v59
	v_fmac_f32_e32 v60, v61, v58
	v_fma_f32 v57, -v57, v60, v59
	v_div_fmas_f32 v57, v57, v58, v60
	v_div_fixup_f32 v57, v57, v56, s7
	v_cmp_lt_f32_e32 vcc, 0, v56
	s_nop 1
	v_cndmask_b32_e32 v57, 0, v57, vcc
	v_mul_f32_e32 v53, v57, v53
	v_mul_f32_e32 v52, v57, v52
	v_mul_f32_e32 v55, v57, v55
	v_rndne_f32_e32 v53, v53
	v_mul_f32_e32 v54, v57, v54
	v_rndne_f32_e32 v52, v52
	v_mul_f32_e32 v51, v57, v51
	v_mul_f32_e32 v50, v57, v50
	v_mul_f32_e32 v49, v57, v49
	v_mul_f32_e32 v48, v57, v48
	v_rndne_f32_e32 v55, v55
	v_cvt_i32_f32_e32 v53, v53
	v_rndne_f32_e32 v54, v54
	v_cvt_i32_f32_e32 v52, v52
	v_rndne_f32_e32 v51, v51
	v_rndne_f32_e32 v50, v50
	v_rndne_f32_e32 v49, v49
	v_rndne_f32_e32 v48, v48
	v_cvt_i32_f32_e32 v55, v55
	v_cvt_i32_f32_e32 v54, v54
	v_cvt_i32_f32_sdwa v51, v51 dst_sel:WORD_1 dst_unused:UNUSED_PAD src0_sel:DWORD
	v_cvt_i32_f32_sdwa v50, v50 dst_sel:WORD_1 dst_unused:UNUSED_PAD src0_sel:DWORD
	v_cvt_i32_f32_e32 v49, v49
	v_cvt_i32_f32_e32 v58, v48
	v_lshlrev_b32_e32 v53, 8, v53
	v_lshlrev_b32_e32 v52, 8, v52
	v_mul_f32_e32 v45, v57, v45
	v_mul_f32_e32 v44, v57, v44
	v_and_b32_e32 v53, 0xff00, v53
	v_and_b32_e32 v52, 0xff00, v52
	v_and_b32_e32 v51, 0xff0000, v51
	v_and_b32_e32 v50, 0xff0000, v50
	v_perm_b32 v48, v49, v55, s6
	v_perm_b32 v49, v58, v54, s6
	v_mul_f32_e32 v47, v57, v47
	v_rndne_f32_e32 v45, v45
	v_mul_f32_e32 v46, v57, v46
	v_rndne_f32_e32 v44, v44
	v_mul_f32_e32 v43, v57, v43
	v_mul_f32_e32 v42, v57, v42
	v_mul_f32_e32 v41, v57, v41
	v_mul_f32_e32 v40, v57, v40
	v_or3_b32 v48, v48, v53, v51
	v_or3_b32 v49, v49, v52, v50
	v_rndne_f32_e32 v47, v47
	v_cvt_i32_f32_e32 v45, v45
	v_rndne_f32_e32 v46, v46
	v_cvt_i32_f32_e32 v44, v44
	v_rndne_f32_e32 v43, v43
	v_rndne_f32_e32 v42, v42
	v_rndne_f32_e32 v41, v41
	v_rndne_f32_e32 v40, v40
	v_mov_b32_e32 v204, v48
	v_mov_b32_e32 v205, v49
	v_cvt_i32_f32_e32 v47, v47
	v_cvt_i32_f32_e32 v46, v46
	v_cvt_i32_f32_sdwa v43, v43 dst_sel:WORD_1 dst_unused:UNUSED_PAD src0_sel:DWORD
	v_cvt_i32_f32_sdwa v42, v42 dst_sel:WORD_1 dst_unused:UNUSED_PAD src0_sel:DWORD
	v_cvt_i32_f32_e32 v41, v41
	v_cvt_i32_f32_e32 v48, v40
	v_lshlrev_b32_e32 v45, 8, v45
	v_lshlrev_b32_e32 v44, 8, v44
	v_and_b32_e32 v45, 0xff00, v45
	v_and_b32_e32 v44, 0xff00, v44
	v_and_b32_e32 v43, 0xff0000, v43
	v_and_b32_e32 v42, 0xff0000, v42
	v_perm_b32 v40, v41, v47, s6
	v_perm_b32 v41, v48, v46, s6
	v_or3_b32 v40, v40, v45, v43
	v_or3_b32 v41, v41, v44, v42
	v_mov_b32_e32 v206, v40
	v_mov_b32_e32 v207, v41
	global_store_dwordx4 v[4:5], v[204:207], off offset:1024
	s_and_saveexec_b64 s[2:3], s[4:5]
	s_cbranch_execz .LBB0_876
	v_mov_b32_e32 v4, 0
	v_mul_f32_e32 v5, 0x3c010204, v56
	global_store_dword v4, v5, s[0:1] offset:20
.LBB0_876:
	s_or_b64 exec, exec, s[2:3]
	v_max_f32_e32 v4, v64, v64
	v_max_f32_e32 v5, v65, v65
	v_max_f32_e32 v4, v4, v5
	v_div_scale_f32 v5, s[2:3], v4, v4, s7
	v_rcp_f32_e32 v40, v5
	s_movk_i32 s2, 0x1000
	v_fma_f32 v41, -v5, v40, 1.0
	v_fmac_f32_e32 v40, v41, v40
	v_div_scale_f32 v41, vcc, s7, v4, s7
	v_mul_f32_e32 v42, v41, v40
	v_fma_f32 v43, -v5, v42, v41
	v_fmac_f32_e32 v42, v43, v40
	v_fma_f32 v5, -v5, v42, v41
	v_div_fmas_f32 v5, v5, v40, v42
	v_div_fixup_f32 v5, v5, v4, s7
	v_cmp_lt_f32_e32 vcc, 0, v4
	s_nop 1
	v_cndmask_b32_e32 v5, 0, v5, vcc
	v_mul_f32_e32 v37, v5, v37
	v_mul_f32_e32 v34, v5, v34
	v_mul_f32_e32 v27, v5, v27
	v_mul_f32_e32 v26, v5, v26
	v_mul_f32_e32 v39, v5, v39
	v_rndne_f32_e32 v37, v37
	v_mul_f32_e32 v38, v5, v38
	v_rndne_f32_e32 v34, v34
	v_mul_f32_e32 v32, v5, v32
	v_mul_f32_e32 v33, v5, v33
	v_mul_f32_e32 v31, v5, v31
	v_mul_f32_e32 v30, v5, v30
	v_mul_f32_e32 v29, v5, v29
	v_rndne_f32_e32 v27, v27
	v_mul_f32_e32 v28, v5, v28
	v_rndne_f32_e32 v26, v26
	v_mul_f32_e32 v25, v5, v25
	v_mul_f32_e32 v24, v5, v24
	v_mul_f32_e32 v23, v5, v23
	v_mul_f32_e32 v5, v5, v22
	v_rndne_f32_e32 v39, v39
	v_cvt_i32_f32_e32 v37, v37
	v_rndne_f32_e32 v38, v38
	v_cvt_i32_f32_e32 v34, v34
	v_rndne_f32_e32 v32, v32
	v_rndne_f32_e32 v33, v33
	v_rndne_f32_e32 v31, v31
	v_rndne_f32_e32 v30, v30
	v_rndne_f32_e32 v29, v29
	v_cvt_i32_f32_e32 v27, v27
	v_rndne_f32_e32 v28, v28
	v_cvt_i32_f32_e32 v26, v26
	v_rndne_f32_e32 v25, v25
	v_rndne_f32_e32 v24, v24
	v_rndne_f32_e32 v23, v23
	v_rndne_f32_e32 v5, v5
	v_cvt_i32_f32_e32 v39, v39
	v_cvt_i32_f32_e32 v38, v38
	v_cvt_i32_f32_sdwa v32, v32 dst_sel:WORD_1 dst_unused:UNUSED_PAD src0_sel:DWORD
	v_cvt_i32_f32_sdwa v33, v33 dst_sel:WORD_1 dst_unused:UNUSED_PAD src0_sel:DWORD
	v_cvt_i32_f32_e32 v31, v31
	v_cvt_i32_f32_e32 v40, v30
	v_cvt_i32_f32_e32 v29, v29
	v_cvt_i32_f32_e32 v28, v28
	v_cvt_i32_f32_sdwa v25, v25 dst_sel:WORD_1 dst_unused:UNUSED_PAD src0_sel:DWORD
	v_cvt_i32_f32_sdwa v24, v24 dst_sel:WORD_1 dst_unused:UNUSED_PAD src0_sel:DWORD
	v_cvt_i32_f32_e32 v23, v23
	v_cvt_i32_f32_e32 v5, v5
	v_lshlrev_b32_e32 v37, 8, v37
	v_lshlrev_b32_e32 v34, 8, v34
	v_lshlrev_b32_e32 v27, 8, v27
	v_lshlrev_b32_e32 v26, 8, v26
	v_and_b32_e32 v37, 0xff00, v37
	v_and_b32_e32 v34, 0xff00, v34
	v_and_b32_e32 v32, 0xff0000, v32
	v_and_b32_e32 v33, 0xff0000, v33
	v_perm_b32 v30, v31, v39, s6
	v_perm_b32 v31, v40, v38, s6
	v_add_co_u32_e32 v2, vcc, s2, v2
	v_and_b32_e32 v27, 0xff00, v27
	v_and_b32_e32 v26, 0xff00, v26
	v_and_b32_e32 v25, 0xff0000, v25
	v_and_b32_e32 v24, 0xff0000, v24
	v_perm_b32 v22, v23, v29, s6
	v_perm_b32 v5, v5, v28, s6
	v_or3_b32 v30, v30, v37, v32
	v_or3_b32 v31, v31, v34, v33
	v_addc_co_u32_e32 v3, vcc, 0, v3, vcc
	v_or3_b32 v22, v22, v27, v25
	v_or3_b32 v23, v5, v26, v24
	v_mov_b32_e32 v200, v30
	v_mov_b32_e32 v201, v31
	v_mov_b32_e32 v202, v22
	v_mov_b32_e32 v203, v23
	global_store_dwordx4 v[2:3], v[200:203], off offset:2048
	s_and_saveexec_b64 s[2:3], s[4:5]
	s_cbranch_execz .LBB0_878
	v_mov_b32_e32 v5, 0
	v_mul_f32_e32 v4, 0x3c010204, v4
	global_store_dword v5, v4, s[0:1] offset:24
.LBB0_878:
	s_or_b64 exec, exec, s[2:3]
	v_max_f32_e32 v4, v35, v35
	v_max_f32_e32 v5, v36, v36
	v_max_f32_e32 v4, v4, v5
	v_div_scale_f32 v5, s[2:3], v4, v4, s7
	v_rcp_f32_e32 v22, v5
	s_nop 0
	v_fma_f32 v23, -v5, v22, 1.0
	v_fmac_f32_e32 v22, v23, v22
	v_div_scale_f32 v23, vcc, s7, v4, s7
	v_mul_f32_e32 v24, v23, v22
	v_fma_f32 v25, -v5, v24, v23
	v_fmac_f32_e32 v24, v25, v22
	v_fma_f32 v5, -v5, v24, v23
	v_div_fmas_f32 v5, v5, v22, v24
	v_div_fixup_f32 v5, v5, v4, s7
	v_cmp_lt_f32_e32 vcc, 0, v4
	s_nop 1
	v_cndmask_b32_e32 v5, 0, v5, vcc
	v_mul_f32_e32 v19, v5, v19
	v_mul_f32_e32 v18, v5, v18
	v_mul_f32_e32 v11, v5, v11
	v_mul_f32_e32 v10, v5, v10
	v_mul_f32_e32 v21, v5, v21
	v_rndne_f32_e32 v19, v19
	v_mul_f32_e32 v20, v5, v20
	v_rndne_f32_e32 v18, v18
	v_mul_f32_e32 v17, v5, v17
	v_mul_f32_e32 v16, v5, v16
	v_mul_f32_e32 v15, v5, v15
	v_mul_f32_e32 v14, v5, v14
	v_mul_f32_e32 v13, v5, v13
	v_rndne_f32_e32 v11, v11
	v_mul_f32_e32 v12, v5, v12
	v_rndne_f32_e32 v10, v10
	v_mul_f32_e32 v9, v5, v9
	v_mul_f32_e32 v8, v5, v8
	v_mul_f32_e32 v7, v5, v7
	v_mul_f32_e32 v5, v5, v6
	v_rndne_f32_e32 v21, v21
	v_cvt_i32_f32_e32 v19, v19
	v_rndne_f32_e32 v20, v20
	v_cvt_i32_f32_e32 v18, v18
	v_rndne_f32_e32 v17, v17
	v_rndne_f32_e32 v16, v16
	v_rndne_f32_e32 v15, v15
	v_rndne_f32_e32 v14, v14
	v_rndne_f32_e32 v13, v13
	v_cvt_i32_f32_e32 v11, v11
	v_rndne_f32_e32 v12, v12
	v_cvt_i32_f32_e32 v10, v10
	v_rndne_f32_e32 v9, v9
	v_rndne_f32_e32 v8, v8
	v_rndne_f32_e32 v7, v7
	v_rndne_f32_e32 v5, v5
	v_cvt_i32_f32_e32 v21, v21
	v_cvt_i32_f32_e32 v20, v20
	v_cvt_i32_f32_sdwa v17, v17 dst_sel:WORD_1 dst_unused:UNUSED_PAD src0_sel:DWORD
	v_cvt_i32_f32_sdwa v16, v16 dst_sel:WORD_1 dst_unused:UNUSED_PAD src0_sel:DWORD
	v_cvt_i32_f32_e32 v15, v15
	v_cvt_i32_f32_e32 v22, v14
	v_cvt_i32_f32_e32 v13, v13
	v_cvt_i32_f32_e32 v12, v12
	v_cvt_i32_f32_sdwa v9, v9 dst_sel:WORD_1 dst_unused:UNUSED_PAD src0_sel:DWORD
	v_cvt_i32_f32_sdwa v8, v8 dst_sel:WORD_1 dst_unused:UNUSED_PAD src0_sel:DWORD
	v_cvt_i32_f32_e32 v7, v7
	v_cvt_i32_f32_e32 v5, v5
	v_lshlrev_b32_e32 v19, 8, v19
	v_lshlrev_b32_e32 v18, 8, v18
	v_lshlrev_b32_e32 v11, 8, v11
	v_lshlrev_b32_e32 v10, 8, v10
	v_and_b32_e32 v19, 0xff00, v19
	v_and_b32_e32 v18, 0xff00, v18
	v_and_b32_e32 v17, 0xff0000, v17
	v_and_b32_e32 v16, 0xff0000, v16
	v_perm_b32 v14, v15, v21, s6
	v_perm_b32 v15, v22, v20, s6
	v_and_b32_e32 v11, 0xff00, v11
	v_and_b32_e32 v10, 0xff00, v10
	v_and_b32_e32 v9, 0xff0000, v9
	v_and_b32_e32 v8, 0xff0000, v8
	v_perm_b32 v6, v7, v13, s6
	v_perm_b32 v5, v5, v12, s6
	v_or3_b32 v14, v14, v19, v17
	v_or3_b32 v15, v15, v18, v16
	v_or3_b32 v6, v6, v11, v9
	v_or3_b32 v7, v5, v10, v8
	v_mov_b32_e32 v204, v14
	v_mov_b32_e32 v205, v15
	v_mov_b32_e32 v206, v6
	v_mov_b32_e32 v207, v7
	global_store_dwordx4 v[2:3], v[204:207], off offset:3072
	s_and_saveexec_b64 s[2:3], s[4:5]
	s_cbranch_execz .LBB0_880
	v_mov_b32_e32 v2, 0
	v_mul_f32_e32 v3, 0x3c010204, v4
	global_store_dword v2, v3, s[0:1] offset:28

.LBB0_1014:
	s_or_b64 exec, exec, s[0:1]
	s_mov_b64 s[0:1], s[82:83]
	v_mov_b32_e32 v2, v0
	s_mov_b32 s2, s73
	s_mov_b32 s5, s72
	s_barrier
	s_load_dwordx2 s[2:3], s[0:1], 0x90
	v_readfirstlane_b32 s4, v2
	s_lshl_b32 s0, s5, 3
	s_and_b32 s0, s0, 56
	s_bfe_u32 s1, s5, 0x30003
	s_ashr_i32 s4, s4, 3
	s_or_b32 s8, s0, s1
	s_and_b32 s1, s5, 0xffffffc0
	s_and_b32 s4, s4, -8
	s_lshl_b32 s0, s8, 8
	s_add_i32 s4, s1, s4
	s_add_i32 s6, s4, s0
	s_ashr_i32 s7, s6, 31
	s_lshl_b64 s[0:1], s[6:7], 11
	v_and_b32_e32 v126, 63, v2
	s_waitcnt lgkmcnt(0)
	s_add_u32 s0, s2, s0
	s_addc_u32 s1, s3, s1
	v_lshlrev_b32_e32 v30, 5, v126
	v_mov_b32_e32 v31, 0
	v_lshl_add_u64 v[2:3], s[0:1], 0, v[30:31]
	s_mov_b32 s0, 0x3001000
	v_add_co_u32_e32 v60, vcc, s0, v2
	s_mov_b64 s[0:1], 0x3000000
	s_nop 0
	v_addc_co_u32_e32 v61, vcc, 0, v3, vcc
	global_load_dwordx4 v[18:21], v[60:61], off offset:-4096
	v_lshl_add_u64 v[4:5], v[2:3], 0, s[0:1]
	global_load_dwordx4 v[22:25], v[4:5], off offset:16
	global_load_dwordx4 v[32:35], v[4:5], off offset:2048
	global_load_dwordx4 v[36:39], v[4:5], off offset:2064
	s_mov_b32 s0, 0x3002000
	v_add_co_u32_e32 v62, vcc, s0, v2
	s_mov_b32 s1, 0x3003000
	s_nop 0
	v_addc_co_u32_e32 v63, vcc, 0, v3, vcc
	v_add_co_u32_e32 v64, vcc, s1, v2
	s_lshl_b32 s5, s8, 19
	s_nop 0
	v_addc_co_u32_e32 v65, vcc, 0, v3, vcc
	global_load_dwordx4 v[40:43], v[60:61], off
	global_load_dwordx4 v[44:47], v[60:61], off offset:16
	global_load_dwordx4 v[48:51], v[60:61], off offset:2048
	global_load_dwordx4 v[52:55], v[60:61], off offset:2064
	global_load_dwordx4 v[56:59], v[64:65], off offset:-4096
	global_load_dwordx4 v[26:29], v[62:63], off offset:16
	global_load_dwordx4 v[14:17], v[62:63], off offset:2048
	global_load_dwordx4 v[10:13], v[62:63], off offset:2064
	global_load_dwordx4 v[6:9], v[64:65], off
	global_load_dwordx4 v[2:5], v[64:65], off offset:16
	s_add_u32 s5, s2, s5
	s_addc_u32 s8, s3, 0
	s_lshl_b32 s4, s4, 10
	s_and_b32 s0, s4, 0x3e000
	s_add_u32 s4, s5, s0
	s_addc_u32 s5, s8, 0
	s_mov_b32 s9, 0x42fe0000
	s_lshl_b64 s[0:1], s[6:7], 2
	s_add_u32 s0, s2, s0
	s_addc_u32 s1, s3, s1
	s_add_u32 s0, s0, 0xfc00000
	s_addc_u32 s1, s1, 0
	s_lshl_b64 s[6:7], s[6:7], 4
	s_mov_b32 s8, 0x40c0c00
	s_add_u32 s2, s2, s6
	s_mov_b32 s6, 0xa800000
	s_addc_u32 s3, s3, s7
	s_add_u32 s2, s2, 0xda00000
	s_addc_u32 s3, s3, 0
	s_waitcnt vmcnt(12)
	v_lshlrev_b32_e32 v148, 16, v22
	v_lshlrev_b32_e32 v140, 16, v18
	v_and_b32_e32 v141, 0xffff0000, v18
	v_lshlrev_b32_e32 v142, 16, v19
	v_and_b32_e32 v143, 0xffff0000, v19
	v_max3_f32 v18, |v140|, 0, |v141|
	v_lshlrev_b32_e32 v144, 16, v20
	v_and_b32_e32 v145, 0xffff0000, v20
	v_max3_f32 v18, v18, |v142|, |v143|
	v_lshlrev_b32_e32 v146, 16, v21
	v_and_b32_e32 v147, 0xffff0000, v21
	v_max3_f32 v18, v18, |v144|, |v145|
	v_and_b32_e32 v149, 0xffff0000, v22
	v_max3_f32 v18, v18, |v146|, |v147|
	v_lshlrev_b32_e32 v134, 16, v23
	v_and_b32_e32 v132, 0xffff0000, v23
	v_max3_f32 v18, v18, |v148|, |v149|
	v_lshlrev_b32_e32 v150, 16, v24
	v_and_b32_e32 v151, 0xffff0000, v24
	v_max3_f32 v18, v18, |v134|, |v132|
	v_lshlrev_b32_e32 v133, 16, v25
	v_and_b32_e32 v131, 0xffff0000, v25
	v_max3_f32 v18, v18, |v150|, |v151|
	v_max3_f32 v18, v18, |v133|, |v131|
	ds_swizzle_b32 v19, v18 offset:swizzle(SWAP,1)
	s_waitcnt vmcnt(11)
	v_lshlrev_b32_e32 v130, 16, v32
	v_and_b32_e32 v128, 0xffff0000, v32
	v_lshlrev_b32_e32 v122, 16, v33
	v_and_b32_e32 v119, 0xffff0000, v33
	s_waitcnt lgkmcnt(0)
	v_max_f32_e32 v19, v19, v19
	v_max_f32_e32 v18, v18, v19
	ds_swizzle_b32 v19, v18 offset:swizzle(SWAP,2)
	v_max3_f32 v20, |v130|, 0, |v128|
	v_lshlrev_b32_e32 v129, 16, v34
	v_and_b32_e32 v127, 0xffff0000, v34
	v_max3_f32 v20, v20, |v122|, |v119|
	s_waitcnt lgkmcnt(0)
	v_max_f32_e32 v19, v19, v19
	v_max_f32_e32 v18, v18, v19
	ds_swizzle_b32 v19, v18 offset:swizzle(SWAP,4)
	v_lshlrev_b32_e32 v123, 16, v35
	v_and_b32_e32 v121, 0xffff0000, v35
	v_max3_f32 v20, v20, |v129|, |v127|
	s_waitcnt vmcnt(10)
	v_lshlrev_b32_e32 v117, 16, v36
	s_waitcnt lgkmcnt(0)
	v_max_f32_e32 v19, v19, v19
	v_max_f32_e32 v18, v18, v19
	ds_swizzle_b32 v19, v18 offset:swizzle(SWAP,8)
	v_and_b32_e32 v116, 0xffff0000, v36
	v_max3_f32 v20, v20, |v123|, |v121|
	v_lshlrev_b32_e32 v113, 16, v37
	v_and_b32_e32 v114, 0xffff0000, v37
	s_waitcnt lgkmcnt(0)
	v_max_f32_e32 v19, v19, v19
	v_max_f32_e32 v30, v18, v19
	v_max3_f32 v18, v20, |v117|, |v116|
	v_lshlrev_b32_e32 v120, 16, v38
	v_and_b32_e32 v118, 0xffff0000, v38
	v_max3_f32 v18, v18, |v113|, |v114|
	v_lshlrev_b32_e32 v115, 16, v39
	v_and_b32_e32 v112, 0xffff0000, v39
	v_max3_f32 v18, v18, |v120|, |v118|
	ds_swizzle_b32 v32, v30 offset:swizzle(SWAP,16)
	v_max3_f32 v33, v18, |v115|, |v112|
	ds_swizzle_b32 v34, v33 offset:swizzle(SWAP,1)
	s_waitcnt vmcnt(9)
	v_lshlrev_b32_e32 v111, 16, v40
	v_and_b32_e32 v109, 0xffff0000, v40
	s_waitcnt lgkmcnt(1)
	v_max_f32_e32 v32, v32, v32
	v_max_f32_e32 v30, v30, v32
	s_waitcnt lgkmcnt(0)
	v_max_f32_e32 v32, v34, v34
	v_max_f32_e32 v32, v33, v32
	v_lshlrev_b32_e32 v106, 16, v41
	v_and_b32_e32 v105, 0xffff0000, v41
	v_max3_f32 v35, |v111|, 0, |v109|
	global_load_dwordx4 v[22:25], v[64:65], off offset:2048
	global_load_dwordx4 v[18:21], v[64:65], off offset:2064
	ds_swizzle_b32 v33, v32 offset:swizzle(SWAP,2)
	v_lshlrev_b32_e32 v110, 16, v42
	v_and_b32_e32 v108, 0xffff0000, v42
	v_max3_f32 v35, v35, |v106|, |v105|
	v_lshlrev_b32_e32 v107, 16, v43
	v_and_b32_e32 v104, 0xffff0000, v43
	v_max3_f32 v35, v35, |v110|, |v108|
	v_max3_f32 v35, v35, |v107|, |v104|
	s_waitcnt vmcnt(10)
	v_lshlrev_b32_e32 v103, 16, v44
	v_and_b32_e32 v101, 0xffff0000, v44
	v_lshlrev_b32_e32 v99, 16, v45
	v_and_b32_e32 v95, 0xffff0000, v45
	v_max3_f32 v35, v35, |v103|, |v101|
	v_lshlrev_b32_e32 v102, 16, v46
	v_and_b32_e32 v100, 0xffff0000, v46
	v_max3_f32 v35, v35, |v99|, |v95|
	s_waitcnt lgkmcnt(0)
	v_max_f32_e32 v33, v33, v33
	v_lshlrev_b32_e32 v98, 16, v47
	v_and_b32_e32 v94, 0xffff0000, v47
	v_max3_f32 v35, v35, |v102|, |v100|
	v_max_f32_e32 v32, v32, v33
	v_max3_f32 v35, v35, |v98|, |v94|
	ds_swizzle_b32 v33, v32 offset:swizzle(SWAP,4)
	ds_swizzle_b32 v36, v35 offset:swizzle(SWAP,1)
	v_mov_b32_e32 v34, v30
	s_nop 1
	v_permlane32_swap_b32_e32 v30, v34
	s_waitcnt lgkmcnt(1)
	v_max_f32_e32 v33, v33, v33
	s_waitcnt lgkmcnt(0)
	v_max_f32_e32 v36, v36, v36
	v_max_f32_e32 v32, v32, v33
	v_max_f32_e32 v35, v35, v36
	ds_swizzle_b32 v33, v32 offset:swizzle(SWAP,8)
	ds_swizzle_b32 v36, v35 offset:swizzle(SWAP,2)
	v_max_f32_e32 v34, v34, v34
	v_max_f32_e32 v30, v30, v30
	v_max_f32_e32 v137, v30, v34
	s_waitcnt lgkmcnt(1)
	v_max_f32_e32 v30, v33, v33
	s_waitcnt lgkmcnt(0)
	v_max_f32_e32 v33, v36, v36
	s_waitcnt vmcnt(9)
	v_lshlrev_b32_e32 v93, 16, v48
	v_and_b32_e32 v91, 0xffff0000, v48
	v_max_f32_e32 v33, v35, v33
	v_lshlrev_b32_e32 v89, 16, v49
	v_and_b32_e32 v87, 0xffff0000, v49
	v_max3_f32 v35, |v93|, 0, |v91|
	v_lshlrev_b32_e32 v92, 16, v50
	v_and_b32_e32 v90, 0xffff0000, v50
	v_max3_f32 v35, v35, |v89|, |v87|
	v_lshlrev_b32_e32 v88, 16, v51
	v_and_b32_e32 v86, 0xffff0000, v51
	v_max3_f32 v35, v35, |v92|, |v90|
	v_max3_f32 v35, v35, |v88|, |v86|
	s_waitcnt vmcnt(8)
	v_lshlrev_b32_e32 v85, 16, v52
	v_and_b32_e32 v83, 0xffff0000, v52
	v_lshlrev_b32_e32 v81, 16, v53
	v_and_b32_e32 v79, 0xffff0000, v53
	v_max3_f32 v35, v35, |v85|, |v83|
	v_lshlrev_b32_e32 v84, 16, v54
	v_and_b32_e32 v82, 0xffff0000, v54
	v_max3_f32 v35, v35, |v81|, |v79|
	v_lshlrev_b32_e32 v80, 16, v55
	v_and_b32_e32 v78, 0xffff0000, v55
	v_max3_f32 v35, v35, |v84|, |v82|
	ds_swizzle_b32 v34, v33 offset:swizzle(SWAP,4)
	v_max3_f32 v35, v35, |v80|, |v78|
	ds_swizzle_b32 v36, v35 offset:swizzle(SWAP,1)
	v_max_f32_e32 v30, v32, v30
	ds_swizzle_b32 v32, v30 offset:swizzle(SWAP,16)
	s_waitcnt lgkmcnt(2)
	v_max_f32_e32 v34, v34, v34
	v_max_f32_e32 v33, v33, v34
	s_waitcnt lgkmcnt(1)
	v_max_f32_e32 v36, v36, v36
	ds_swizzle_b32 v34, v33 offset:swizzle(SWAP,8)
	v_max_f32_e32 v35, v35, v36
	ds_swizzle_b32 v36, v35 offset:swizzle(SWAP,2)
	s_waitcnt lgkmcnt(2)
	v_max_f32_e32 v32, v32, v32
	v_max_f32_e32 v138, v30, v32
	s_waitcnt lgkmcnt(1)
	v_max_f32_e32 v30, v34, v34
	v_max_f32_e32 v30, v33, v30
	s_waitcnt lgkmcnt(0)
	v_max_f32_e32 v33, v36, v36
	s_waitcnt vmcnt(7)
	v_lshlrev_b32_e32 v77, 16, v56
	v_and_b32_e32 v75, 0xffff0000, v56
	v_max_f32_e32 v33, v35, v33
	v_lshlrev_b32_e32 v72, 16, v57
	v_and_b32_e32 v71, 0xffff0000, v57
	v_max3_f32 v35, |v77|, 0, |v75|
	v_lshlrev_b32_e32 v76, 16, v58
	v_and_b32_e32 v74, 0xffff0000, v58
	v_max3_f32 v35, v35, |v72|, |v71|
	v_lshlrev_b32_e32 v73, 16, v59
	v_and_b32_e32 v70, 0xffff0000, v59
	v_max3_f32 v35, v35, |v76|, |v74|
	v_max3_f32 v35, v35, |v73|, |v70|
	s_waitcnt vmcnt(6)
	v_lshlrev_b32_e32 v69, 16, v26
	v_and_b32_e32 v67, 0xffff0000, v26
	v_lshlrev_b32_e32 v65, 16, v27
	v_and_b32_e32 v63, 0xffff0000, v27
	v_max3_f32 v26, v35, |v69|, |v67|
	v_lshlrev_b32_e32 v68, 16, v28
	v_and_b32_e32 v66, 0xffff0000, v28
	v_max3_f32 v26, v26, |v65|, |v63|
	v_lshlrev_b32_e32 v64, 16, v29
	v_and_b32_e32 v62, 0xffff0000, v29
	v_max3_f32 v26, v26, |v68|, |v66|
	v_max3_f32 v26, v26, |v64|, |v62|
	s_waitcnt vmcnt(5)
	v_lshlrev_b32_e32 v61, 16, v14
	v_and_b32_e32 v59, 0xffff0000, v14
	ds_swizzle_b32 v27, v26 offset:swizzle(SWAP,1)
	v_lshlrev_b32_e32 v57, 16, v15
	v_and_b32_e32 v55, 0xffff0000, v15
	v_max3_f32 v14, |v61|, 0, |v59|
	v_lshlrev_b32_e32 v60, 16, v16
	v_and_b32_e32 v58, 0xffff0000, v16
	v_max3_f32 v14, v14, |v57|, |v55|
	v_lshlrev_b32_e32 v56, 16, v17
	v_and_b32_e32 v54, 0xffff0000, v17
	v_max3_f32 v14, v14, |v60|, |v58|
	v_max3_f32 v14, v14, |v56|, |v54|
	s_waitcnt vmcnt(4)
	v_lshlrev_b32_e32 v53, 16, v10
	v_and_b32_e32 v51, 0xffff0000, v10
	v_lshlrev_b32_e32 v49, 16, v11
	v_and_b32_e32 v47, 0xffff0000, v11
	v_max3_f32 v10, v14, |v53|, |v51|
	s_waitcnt lgkmcnt(0)
	v_max_f32_e32 v27, v27, v27
	v_lshlrev_b32_e32 v52, 16, v12
	v_and_b32_e32 v50, 0xffff0000, v12
	v_max3_f32 v10, v10, |v49|, |v47|
	v_max_f32_e32 v26, v26, v27
	v_lshlrev_b32_e32 v48, 16, v13
	v_and_b32_e32 v46, 0xffff0000, v13
	v_max3_f32 v10, v10, |v52|, |v50|
	ds_swizzle_b32 v27, v26 offset:swizzle(SWAP,2)
	v_max3_f32 v10, v10, |v48|, |v46|
	ds_swizzle_b32 v11, v10 offset:swizzle(SWAP,1)
	ds_swizzle_b32 v34, v33 offset:swizzle(SWAP,4)
	ds_swizzle_b32 v32, v30 offset:swizzle(SWAP,16)
	s_waitcnt lgkmcnt(3)
	v_max_f32_e32 v27, v27, v27
	v_max_f32_e32 v26, v26, v27
	s_waitcnt lgkmcnt(2)
	v_max_f32_e32 v11, v11, v11
	ds_swizzle_b32 v27, v26 offset:swizzle(SWAP,4)
	v_max_f32_e32 v10, v10, v11
	ds_swizzle_b32 v11, v10 offset:swizzle(SWAP,2)
	s_waitcnt lgkmcnt(3)
	v_max_f32_e32 v34, v34, v34
	v_max_f32_e32 v33, v33, v34
	ds_swizzle_b32 v34, v33 offset:swizzle(SWAP,8)
	s_waitcnt lgkmcnt(2)
	v_max_f32_e32 v12, v27, v27
	v_max_f32_e32 v12, v26, v12
	s_waitcnt lgkmcnt(1)
	v_max_f32_e32 v11, v11, v11
	ds_swizzle_b32 v13, v12 offset:swizzle(SWAP,8)
	v_max_f32_e32 v10, v10, v11
	ds_swizzle_b32 v11, v10 offset:swizzle(SWAP,4)
	s_waitcnt lgkmcnt(2)
	v_max_f32_e32 v28, v34, v34
	v_max_f32_e32 v28, v33, v28
	ds_swizzle_b32 v29, v28 offset:swizzle(SWAP,16)
	s_waitcnt lgkmcnt(2)
	v_max_f32_e32 v13, v13, v13
	v_max_f32_e32 v12, v12, v13
	s_waitcnt lgkmcnt(1)
	v_max_f32_e32 v11, v11, v11
	ds_swizzle_b32 v13, v12 offset:swizzle(SWAP,16)
	v_max_f32_e32 v10, v10, v11
	ds_swizzle_b32 v11, v10 offset:swizzle(SWAP,8)
	s_waitcnt vmcnt(3)
	v_lshlrev_b32_e32 v45, 16, v6
	v_and_b32_e32 v43, 0xffff0000, v6
	v_max_f32_e32 v32, v32, v32
	s_waitcnt lgkmcnt(2)
	v_max_f32_e32 v29, v29, v29
	v_lshlrev_b32_e32 v40, 16, v7
	v_and_b32_e32 v39, 0xffff0000, v7
	v_max3_f32 v6, |v45|, 0, |v43|
	s_waitcnt vmcnt(1)
	v_lshlrev_b32_e32 v27, 16, v22
	v_and_b32_e32 v26, 0xffff0000, v22
	v_max_f32_e32 v135, v30, v32
	v_max_f32_e32 v124, v28, v29
	v_lshlrev_b32_e32 v44, 16, v8
	v_and_b32_e32 v42, 0xffff0000, v8
	v_max3_f32 v6, v6, |v40|, |v39|
	v_lshlrev_b32_e32 v32, 16, v5
	v_and_b32_e32 v28, 0xffff0000, v5
	v_lshlrev_b32_e32 v17, 16, v23
	v_and_b32_e32 v15, 0xffff0000, v23
	v_max3_f32 v5, |v27|, 0, |v26|
	v_lshlrev_b32_e32 v41, 16, v9
	v_and_b32_e32 v38, 0xffff0000, v9
	v_max3_f32 v6, v6, |v44|, |v42|
	v_lshlrev_b32_e32 v23, 16, v24
	v_and_b32_e32 v22, 0xffff0000, v24
	v_max3_f32 v5, v5, |v17|, |v15|
	s_waitcnt lgkmcnt(1)
	v_max_f32_e32 v13, v13, v13
	v_max3_f32 v6, v6, |v41|, |v38|
	v_lshlrev_b32_e32 v37, 16, v2
	v_and_b32_e32 v35, 0xffff0000, v2
	v_lshlrev_b32_e32 v16, 16, v25
	v_and_b32_e32 v14, 0xffff0000, v25
	v_max3_f32 v5, v5, |v23|, |v22|
	v_max_f32_e32 v96, v12, v13
	v_lshlrev_b32_e32 v33, 16, v3
	v_and_b32_e32 v29, 0xffff0000, v3
	v_lshlrev_b32_e32 v36, 16, v4
	v_and_b32_e32 v34, 0xffff0000, v4
	v_max3_f32 v2, v6, |v37|, |v35|
	s_waitcnt lgkmcnt(0)
	v_max_f32_e32 v4, v11, v11
	v_max3_f32 v5, v5, |v16|, |v14|
	s_waitcnt vmcnt(0)
	v_lshlrev_b32_e32 v13, 16, v18
	v_and_b32_e32 v11, 0xffff0000, v18
	v_max3_f32 v2, v2, |v33|, |v29|
	v_lshlrev_b32_e32 v9, 16, v19
	v_and_b32_e32 v7, 0xffff0000, v19
	v_max3_f32 v5, v5, |v13|, |v11|
	v_max3_f32 v2, v2, |v36|, |v34|
	v_max_f32_e32 v4, v10, v4
	v_lshlrev_b32_e32 v12, 16, v20
	v_and_b32_e32 v10, 0xffff0000, v20
	v_max3_f32 v5, v5, |v9|, |v7|
	v_max3_f32 v2, v2, |v32|, |v28|
	v_lshlrev_b32_e32 v8, 16, v21
	v_and_b32_e32 v6, 0xffff0000, v21
	v_max3_f32 v5, v5, |v12|, |v10|
	ds_swizzle_b32 v3, v2 offset:swizzle(SWAP,1)
	v_max3_f32 v5, v5, |v8|, |v6|
	ds_swizzle_b32 v18, v5 offset:swizzle(SWAP,1)
	ds_swizzle_b32 v19, v4 offset:swizzle(SWAP,16)
	v_lshlrev_b32_e32 v30, 4, v126
	s_waitcnt lgkmcnt(2)
	v_max_f32_e32 v3, v3, v3
	v_max_f32_e32 v2, v2, v3
	s_waitcnt lgkmcnt(1)
	v_max_f32_e32 v18, v18, v18
	ds_swizzle_b32 v3, v2 offset:swizzle(SWAP,2)
	v_max_f32_e32 v5, v5, v18
	ds_swizzle_b32 v18, v5 offset:swizzle(SWAP,2)
	s_waitcnt lgkmcnt(2)
	v_max_f32_e32 v19, v19, v19
	v_max_f32_e32 v24, v4, v19
	s_waitcnt lgkmcnt(1)
	v_max_f32_e32 v3, v3, v3
	v_max_f32_e32 v2, v2, v3
	s_waitcnt lgkmcnt(0)
	v_max_f32_e32 v18, v18, v18
	ds_swizzle_b32 v3, v2 offset:swizzle(SWAP,4)
	v_max_f32_e32 v5, v5, v18
	ds_swizzle_b32 v18, v5 offset:swizzle(SWAP,4)
	v_mov_b32_e32 v139, v138
	v_mov_b32_e32 v136, v135
	s_waitcnt lgkmcnt(1)
	v_max_f32_e32 v3, v3, v3
	v_max_f32_e32 v2, v2, v3
	s_waitcnt lgkmcnt(0)
	v_max_f32_e32 v4, v18, v18
	ds_swizzle_b32 v3, v2 offset:swizzle(SWAP,8)
	v_max_f32_e32 v4, v5, v4
	ds_swizzle_b32 v5, v4 offset:swizzle(SWAP,8)
	v_mov_b32_e32 v125, v124
	v_mov_b32_e32 v97, v96
	s_waitcnt lgkmcnt(1)
	v_max_f32_e32 v3, v3, v3
	v_max_f32_e32 v2, v2, v3
	s_waitcnt lgkmcnt(0)
	v_max_f32_e32 v5, v5, v5
	ds_swizzle_b32 v3, v2 offset:swizzle(SWAP,16)
	v_max_f32_e32 v4, v4, v5
	ds_swizzle_b32 v5, v4 offset:swizzle(SWAP,16)
	v_mov_b32_e32 v25, v24
	v_permlane32_swap_b32_e32 v138, v139
	s_waitcnt lgkmcnt(1)
	v_max_f32_e32 v3, v3, v3
	v_max_f32_e32 v20, v2, v3
	s_waitcnt lgkmcnt(0)
	v_max_f32_e32 v2, v5, v5
	v_max_f32_e32 v18, v4, v2
	v_lshl_add_u64 v[4:5], s[4:5], 0, v[30:31]
	v_div_scale_f32 v30, s[4:5], v137, v137, s9
	v_rcp_f32_e32 v152, v30
	s_mov_b64 s[4:5], 0xa800000
	v_lshl_add_u64 v[2:3], v[4:5], 0, s[4:5]
	v_cmp_eq_u32_e64 s[4:5], 0, v126
	v_fma_f32 v126, -v30, v152, 1.0
	v_fmac_f32_e32 v152, v126, v152
	v_div_scale_f32 v126, vcc, s9, v137, s9
	v_mul_f32_e32 v153, v126, v152
	v_fma_f32 v154, -v30, v153, v126
	v_fmac_f32_e32 v153, v154, v152
	v_fma_f32 v30, -v30, v153, v126
	v_div_fmas_f32 v30, v30, v152, v153
	v_div_fixup_f32 v30, v30, v137, s9
	v_cmp_lt_f32_e32 vcc, 0, v137
	v_mov_b32_e32 v21, v20
	v_mov_b32_e32 v19, v18
	v_cndmask_b32_e32 v30, 0, v30, vcc
	v_mul_f32_e32 v126, v30, v140
	v_mul_f32_e32 v140, v30, v141
	v_rndne_f32_e32 v140, v140
	v_mul_f32_e32 v141, v30, v144
	v_mul_f32_e32 v144, v30, v145
	v_mul_f32_e32 v142, v30, v142
	v_mul_f32_e32 v143, v30, v143
	v_rndne_f32_e32 v126, v126
	v_cvt_i32_f32_e32 v140, v140
	v_rndne_f32_e32 v144, v144
	v_rndne_f32_e32 v142, v142
	v_mul_f32_e32 v145, v30, v146
	v_rndne_f32_e32 v143, v143
	v_mul_f32_e32 v146, v30, v147
	v_cvt_i32_f32_e32 v126, v126
	v_rndne_f32_e32 v141, v141
	v_cvt_i32_f32_e32 v144, v144
	v_cvt_i32_f32_sdwa v142, v142 dst_sel:WORD_1 dst_unused:UNUSED_PAD src0_sel:DWORD
	v_rndne_f32_e32 v145, v145
	v_cvt_i32_f32_e32 v143, v143
	v_rndne_f32_e32 v146, v146
	v_cvt_i32_f32_e32 v141, v141
	v_cvt_i32_f32_sdwa v145, v145 dst_sel:WORD_1 dst_unused:UNUSED_PAD src0_sel:DWORD
	v_cvt_i32_f32_e32 v146, v146
	v_lshlrev_b32_e32 v140, 8, v140
	v_and_b32_e32 v140, 0xff00, v140
	v_lshlrev_b32_e32 v144, 8, v144
	v_and_b32_e32 v142, 0xff0000, v142
	v_perm_b32 v126, v143, v126, s8
	v_and_b32_e32 v144, 0xff00, v144
	v_and_b32_e32 v145, 0xff0000, v145
	v_or3_b32 v140, v126, v140, v142
	v_perm_b32 v126, v146, v141, s8
	v_add_co_u32_e32 v4, vcc, s6, v4
	v_or3_b32 v141, v126, v144, v145
	s_nop 0
	v_addc_co_u32_e32 v5, vcc, 0, v5, vcc
	v_mov_b32_e32 v200, v140
	v_mov_b32_e32 v201, v141
	v_mul_f32_e32 v5, v30, v149
	v_mul_f32_e32 v4, v30, v148
	v_rndne_f32_e32 v5, v5
	v_mul_f32_e32 v140, v30, v151
	v_mul_f32_e32 v134, v30, v134
	v_mul_f32_e32 v132, v30, v132
	v_rndne_f32_e32 v4, v4
	v_cvt_i32_f32_e32 v5, v5
	v_mul_f32_e32 v126, v30, v150
	v_rndne_f32_e32 v140, v140
	v_rndne_f32_e32 v134, v134
	v_mul_f32_e32 v133, v30, v133
	v_rndne_f32_e32 v132, v132
	v_mul_f32_e32 v30, v30, v131
	v_cvt_i32_f32_e32 v4, v4
	v_rndne_f32_e32 v126, v126
	v_cvt_i32_f32_e32 v140, v140
	v_cvt_i32_f32_sdwa v134, v134 dst_sel:WORD_1 dst_unused:UNUSED_PAD src0_sel:DWORD
	v_rndne_f32_e32 v133, v133
	v_cvt_i32_f32_e32 v132, v132
	v_rndne_f32_e32 v30, v30
	v_cvt_i32_f32_e32 v126, v126
	v_cvt_i32_f32_sdwa v133, v133 dst_sel:WORD_1 dst_unused:UNUSED_PAD src0_sel:DWORD
	v_cvt_i32_f32_e32 v30, v30
	v_lshlrev_b32_e32 v5, 8, v5
	v_and_b32_e32 v5, 0xff00, v5
	v_lshlrev_b32_e32 v140, 8, v140
	v_and_b32_e32 v134, 0xff0000, v134
	v_perm_b32 v4, v132, v4, s8
	v_and_b32_e32 v140, 0xff00, v140
	v_and_b32_e32 v131, 0xff0000, v133
	v_or3_b32 v4, v4, v5, v134
	v_perm_b32 v5, v30, v126, s8
	v_permlane32_swap_b32_e32 v135, v136
	v_permlane32_swap_b32_e32 v124, v125
	v_permlane32_swap_b32_e32 v96, v97
	v_permlane32_swap_b32_e32 v24, v25
	v_permlane32_swap_b32_e32 v20, v21
	v_permlane32_swap_b32_e32 v18, v19
	v_or3_b32 v5, v5, v140, v131
	v_mov_b32_e32 v202, v4
	v_mov_b32_e32 v203, v5
	global_store_dwordx4 v[2:3], v[200:203], off
	s_and_saveexec_b64 s[6:7], s[4:5]
	s_cbranch_execz .LBB0_1016
	global_load_dwordx4 v[140:143], v31, s[2:3]
	s_waitcnt vmcnt(0)
	v_mov_b32_e32 v4, v141
	v_mov_b32_e32 v5, v142
	v_mov_b32_e32 v141, v143
	v_pk_add_f32 v[4:5], v[4:5], v[140:141]
	s_nop 0
	v_add_f32_e32 v4, v4, v5
	v_mov_b32_e32 v5, 0x358637bd
	v_fmac_f32_e32 v5, 0x3a800000, v4
	v_rsq_f32_e32 v4, v5
	v_mul_f32_e32 v5, 0x3c010204, v137
	v_mul_f32_e32 v4, v5, v4
	global_store_dword v31, v4, s[0:1]
